# v7 + MFMA k-inner chains with snake accumulator order
# baseline (speedup 1.0000x reference)
; #define PG8_STAGE(bufoff, gbase, voff) do { _Pragma("unroll") for (int _i = 0; _i < 2; ++_i) \
;         __builtin_amdgcn_global_load_lds((const unsigned*)((const char*)(gbase) + (voff)[_i]), (PG8_LAS unsigned*)(lds + (bufoff) + ldsw + _i * 8192), 16, 0, 0); } while (0)
; #define PG8_LDA(dst, b, h) do { _Pragma("unroll") for (int m = 0; m < 4; ++m) _Pragma("unroll") for (int k = 0; k < 2; ++k) dst[m][k] = *(const PG8_LAS bf16x8*)(lds + PG8_SA(b, h) + aoff + m * 2048 + k * 1024); } while (0)
; #define PG8_MMA(ai, bj, At, Bt) do { __builtin_amdgcn_s_setprio(3); _Pragma("unroll") for (int m = 0; m < 4; ++m) _Pragma("unroll") for (int n = 0; n < 2; ++n) _Pragma("unroll") for (int k = 0; k < 2; ++k) \
;         acc[ai][bj][m][n] = __builtin_amdgcn_mfma_f32_16x16x32_bf16(Bt[n][k], At[m][k], acc[ai][bj][m][n], 0, 0, 0); __builtin_amdgcn_s_setprio(0); } while (0)
; #define PG8_WAIT_V(n) asm volatile("s_waitcnt vmcnt(" #n ")" ::: "memory")
; #define PG8_WAIT_L(n) asm volatile("s_waitcnt lgkmcnt(" #n ")" ::: "memory")
; #define PG8_BAR __builtin_amdgcn_s_barrier()
; #define PG8_SCHED __builtin_amdgcn_sched_barrier(0)
; template <class Epi, class Sched, bool ALIGN_EPI = false, bool SP2 = false>
; __device__ __forceinline__ void gemm_phase(PG8_LAS unsigned char* lds, const Gemm g, const Sched& S, const Epi& E) {
;     ...
;             PG8_WAIT_V(8); PG8_WAIT_L(0); PG8_BAR; PG8_MMA(0, 0, At, B0); PG8_MMA(0, 1, At, B1); PG8_BAR; PG8_SCHED;
;             PG8_LDA(At, 0, 1); PG8_STAGE(PG8_SB(0, 0), b2, voffB); PG8_STAGE(PG8_SB(0, 1), b2 + hstepB, voffB); PG8_STAGE(PG8_SA(0, 0), a2, voffA);
.Lengw1_e:
	s_waitcnt lgkmcnt(0)
	s_barrier
	s_setprio 3
	s_waitcnt lgkmcnt(0)
	v_mfma_f32_16x16x32_bf16 v[126:129], v[130:133], v[192:195], v[126:129]
	v_mfma_f32_16x16x32_bf16 v[126:129], v[134:137], v[196:199], v[126:129]
	v_mfma_f32_16x16x32_bf16 v[118:121], v[156:159], v[192:195], v[118:121]
	v_mfma_f32_16x16x32_bf16 v[118:121], v[172:175], v[196:199], v[118:121]
	v_mfma_f32_16x16x32_bf16 v[102:105], v[156:159], v[200:203], v[102:105]
	v_mfma_f32_16x16x32_bf16 v[102:105], v[172:175], v[204:207], v[102:105]
	v_mfma_f32_16x16x32_bf16 v[110:113], v[130:133], v[200:203], v[110:113]
	v_mfma_f32_16x16x32_bf16 v[110:113], v[134:137], v[204:207], v[110:113]
	v_mfma_f32_16x16x32_bf16 v[94:97], v[130:133], v[208:211], v[94:97]
	v_mfma_f32_16x16x32_bf16 v[94:97], v[134:137], v[212:215], v[94:97]
	v_mfma_f32_16x16x32_bf16 v[86:89], v[156:159], v[208:211], v[86:89]
	v_mfma_f32_16x16x32_bf16 v[86:89], v[172:175], v[212:215], v[86:89]
	v_mfma_f32_16x16x32_bf16 v[70:73], v[156:159], v[216:219], v[70:73]
	v_mfma_f32_16x16x32_bf16 v[70:73], v[172:175], v[220:223], v[70:73]
	v_mfma_f32_16x16x32_bf16 v[78:81], v[130:133], v[216:219], v[78:81]
	v_mfma_f32_16x16x32_bf16 v[78:81], v[134:137], v[220:223], v[78:81]
	s_setprio 0
	s_setprio 3
	v_mfma_f32_16x16x32_bf16 v[122:125], v[176:179], v[192:195], v[122:125]
	v_mfma_f32_16x16x32_bf16 v[122:125], v[180:183], v[196:199], v[122:125]
	v_mfma_f32_16x16x32_bf16 v[114:117], v[184:187], v[192:195], v[114:117]
	v_mfma_f32_16x16x32_bf16 v[114:117], v[188:191], v[196:199], v[114:117]
	v_mfma_f32_16x16x32_bf16 v[98:101], v[184:187], v[200:203], v[98:101]
	v_mfma_f32_16x16x32_bf16 v[98:101], v[188:191], v[204:207], v[98:101]
	v_mfma_f32_16x16x32_bf16 v[106:109], v[176:179], v[200:203], v[106:109]
	v_mfma_f32_16x16x32_bf16 v[106:109], v[180:183], v[204:207], v[106:109]
	v_mfma_f32_16x16x32_bf16 v[90:93], v[176:179], v[208:211], v[90:93]
	v_mfma_f32_16x16x32_bf16 v[90:93], v[180:183], v[212:215], v[90:93]
	v_mfma_f32_16x16x32_bf16 v[82:85], v[184:187], v[208:211], v[82:85]
	v_mfma_f32_16x16x32_bf16 v[82:85], v[188:191], v[212:215], v[82:85]
	v_mfma_f32_16x16x32_bf16 v[66:69], v[184:187], v[216:219], v[66:69]
	v_mfma_f32_16x16x32_bf16 v[66:69], v[188:191], v[220:223], v[66:69]
	v_mfma_f32_16x16x32_bf16 v[74:77], v[176:179], v[216:219], v[74:77]
	v_mfma_f32_16x16x32_bf16 v[74:77], v[180:183], v[220:223], v[74:77]
	s_setprio 0
	s_barrier
	s_add_i32 s56, s83, s66
	v_lshl_add_u64 v[160:161], s[8:9], 0, v[140:141]
	s_mov_b32 m0, s56
	ds_read_b128 v[192:195], v169 offset:16384
	ds_read_b128 v[196:199], v169 offset:17408
	ds_read_b128 v[200:203], v169 offset:18432
	ds_read_b128 v[204:207], v169 offset:19456
	ds_read_b128 v[208:211], v169 offset:20480
	ds_read_b128 v[212:215], v169 offset:21504
	ds_read_b128 v[216:219], v169 offset:22528
	ds_read_b128 v[220:223], v169 offset:23552
	global_load_lds_dwordx4 v[160:161], off
	s_add_i32 m0, s56, 0x2000
	s_add_u32 s56, s8, 0x100000
	v_lshl_add_u64 v[224:225], s[8:9], 0, v[144:145]
	s_addc_u32 s57, s9, 0
	s_add_i32 s58, s89, s66
	global_load_lds_dwordx4 v[224:225], off
	v_lshl_add_u64 v[226:227], s[56:57], 0, v[140:141]
	s_mov_b32 m0, s58
	v_lshl_add_u64 v[228:229], s[36:37], 0, v[142:143]
	global_load_lds_dwordx4 v[226:227], off
	v_lshl_add_u64 v[226:227], s[56:57], 0, v[144:145]
	s_add_i32 m0, s58, 0x2000
	s_nop 0
	global_load_lds_dwordx4 v[226:227], off
	v_lshl_add_u64 v[226:227], s[36:37], 0, v[138:139]
	s_mov_b32 m0, s55
	s_nop 0
	global_load_lds_dwordx4 v[226:227], off
	s_mov_b32 m0, s67
	s_nop 0
	global_load_lds_dwordx4 v[228:229], off
	s_cmp_eq_u32 s97, 0
	s_cbranch_scc1 .Lengw2_a
	s_cmp_eq_u32 s97, 2
	s_cbranch_scc1 .Lengw2_b
	s_cmp_eq_u32 s97, 4
	s_cbranch_scc1 .Lengw2_c
	s_waitcnt vmcnt(16)
	s_branch .Lengw2_e

; #define PG8_STAGE(bufoff, gbase, voff) do { _Pragma("unroll") for (int _i = 0; _i < 2; ++_i) \
;         __builtin_amdgcn_global_load_lds((const unsigned*)((const char*)(gbase) + (voff)[_i]), (PG8_LAS unsigned*)(lds + (bufoff) + ldsw + _i * 8192), 16, 0, 0); } while (0)
; #define PG8_LDA(dst, b, h) do { _Pragma("unroll") for (int m = 0; m < 4; ++m) _Pragma("unroll") for (int k = 0; k < 2; ++k) dst[m][k] = *(const PG8_LAS bf16x8*)(lds + PG8_SA(b, h) + aoff + m * 2048 + k * 1024); } while (0)
; #define PG8_LDB(dst, b, h) do { _Pragma("unroll") for (int n = 0; n < 2; ++n) _Pragma("unroll") for (int k = 0; k < 2; ++k) dst[n][k] = *(const PG8_LAS bf16x8*)(lds + PG8_SB(b, h) + boff + n * 2048 + k * 1024); } while (0)
; #define PG8_MMA(ai, bj, At, Bt) do { __builtin_amdgcn_s_setprio(3); _Pragma("unroll") for (int m = 0; m < 4; ++m) _Pragma("unroll") for (int n = 0; n < 2; ++n) _Pragma("unroll") for (int k = 0; k < 2; ++k) \
;         acc[ai][bj][m][n] = __builtin_amdgcn_mfma_f32_16x16x32_bf16(Bt[n][k], At[m][k], acc[ai][bj][m][n], 0, 0, 0); __builtin_amdgcn_s_setprio(0); } while (0)
; #define PG8_WAIT_V(n) asm volatile("s_waitcnt vmcnt(" #n ")" ::: "memory")
; #define PG8_WAIT_L(n) asm volatile("s_waitcnt lgkmcnt(" #n ")" ::: "memory")
; #define PG8_BAR __builtin_amdgcn_s_barrier()
; #define PG8_SCHED __builtin_amdgcn_sched_barrier(0)
; template <class Epi, class Sched, bool ALIGN_EPI = false, bool SP2 = false>
; __device__ __forceinline__ void gemm_phase(PG8_LAS unsigned char* lds, const Gemm g, const Sched& S, const Epi& E) {
;     ...
;             PG8_WAIT_V(8); PG8_WAIT_L(0); PG8_BAR; PG8_MMA(1, 0, At, B0); PG8_MMA(1, 1, At, B1); PG8_BAR; PG8_SCHED;
;             PG8_LDB(B0, 1, 0); PG8_LDB(B1, 1, 1); PG8_SCHED; PG8_LDA(At, 1, 0); PG8_STAGE(PG8_SA(0, 1), a2 + hstepA, voffA);
.Lengw2_e:
	s_waitcnt lgkmcnt(0)
	s_barrier
	s_setprio 3
	s_waitcnt lgkmcnt(0)
	v_mfma_f32_16x16x32_bf16 v[62:65], v[130:133], v[192:195], v[62:65]
	v_mfma_f32_16x16x32_bf16 v[62:65], v[134:137], v[196:199], v[62:65]
	v_mfma_f32_16x16x32_bf16 v[54:57], v[156:159], v[192:195], v[54:57]
	v_mfma_f32_16x16x32_bf16 v[54:57], v[172:175], v[196:199], v[54:57]
	v_mfma_f32_16x16x32_bf16 v[38:41], v[156:159], v[200:203], v[38:41]
	v_mfma_f32_16x16x32_bf16 v[38:41], v[172:175], v[204:207], v[38:41]
	v_mfma_f32_16x16x32_bf16 v[46:49], v[130:133], v[200:203], v[46:49]
	v_mfma_f32_16x16x32_bf16 v[46:49], v[134:137], v[204:207], v[46:49]
	v_mfma_f32_16x16x32_bf16 v[30:33], v[130:133], v[208:211], v[30:33]
	v_mfma_f32_16x16x32_bf16 v[30:33], v[134:137], v[212:215], v[30:33]
	v_mfma_f32_16x16x32_bf16 v[22:25], v[156:159], v[208:211], v[22:25]
	v_mfma_f32_16x16x32_bf16 v[22:25], v[172:175], v[212:215], v[22:25]
	v_mfma_f32_16x16x32_bf16 v[6:9], v[156:159], v[216:219], v[6:9]
	v_mfma_f32_16x16x32_bf16 v[6:9], v[172:175], v[220:223], v[6:9]
	v_mfma_f32_16x16x32_bf16 v[14:17], v[130:133], v[216:219], v[14:17]
	v_mfma_f32_16x16x32_bf16 v[14:17], v[134:137], v[220:223], v[14:17]
	s_setprio 0
	s_setprio 3
	v_mfma_f32_16x16x32_bf16 v[58:61], v[176:179], v[192:195], v[58:61]
	v_mfma_f32_16x16x32_bf16 v[58:61], v[180:183], v[196:199], v[58:61]
	v_mfma_f32_16x16x32_bf16 v[50:53], v[184:187], v[192:195], v[50:53]
	v_mfma_f32_16x16x32_bf16 v[50:53], v[188:191], v[196:199], v[50:53]
	v_mfma_f32_16x16x32_bf16 v[34:37], v[184:187], v[200:203], v[34:37]
	v_mfma_f32_16x16x32_bf16 v[34:37], v[188:191], v[204:207], v[34:37]
	v_mfma_f32_16x16x32_bf16 v[42:45], v[176:179], v[200:203], v[42:45]
	v_mfma_f32_16x16x32_bf16 v[42:45], v[180:183], v[204:207], v[42:45]
	v_mfma_f32_16x16x32_bf16 v[26:29], v[176:179], v[208:211], v[26:29]
	v_mfma_f32_16x16x32_bf16 v[26:29], v[180:183], v[212:215], v[26:29]
	v_mfma_f32_16x16x32_bf16 v[18:21], v[184:187], v[208:211], v[18:21]
	v_mfma_f32_16x16x32_bf16 v[18:21], v[188:191], v[212:215], v[18:21]
	v_mfma_f32_16x16x32_bf16 v[2:5], v[184:187], v[216:219], v[2:5]
	v_mfma_f32_16x16x32_bf16 v[2:5], v[188:191], v[220:223], v[2:5]
	v_mfma_f32_16x16x32_bf16 v[10:13], v[176:179], v[216:219], v[10:13]
	v_mfma_f32_16x16x32_bf16 v[10:13], v[180:183], v[220:223], v[10:13]
	s_setprio 0
	s_barrier
	s_add_i32 s56, 0, 0x18000
	v_add_u32_e32 v146, s56, v164
	s_add_i32 s57, 0, 0x1c000
	ds_read_b128 v[130:133], v146
	ds_read_b128 v[134:137], v146 offset:1024
	ds_read_b128 v[156:159], v146 offset:2048
	ds_read_b128 v[172:175], v146 offset:3072
	v_add_u32_e32 v146, s57, v164
	ds_read_b128 v[176:179], v146
	ds_read_b128 v[180:183], v146 offset:1024
	ds_read_b128 v[184:187], v146 offset:2048
	ds_read_b128 v[188:191], v146 offset:3072
	s_add_u32 s36, s36, 0x100000
	s_addc_u32 s37, s37, 0
	s_mov_b32 m0, s72
	v_lshl_add_u64 v[230:231], s[36:37], 0, v[138:139]
	ds_read_b128 v[192:195], v169 offset:32768
	ds_read_b128 v[196:199], v169 offset:33792
	ds_read_b128 v[200:203], v169 offset:34816
	ds_read_b128 v[204:207], v169 offset:35840
	ds_read_b128 v[208:211], v169 offset:36864
	ds_read_b128 v[212:215], v169 offset:37888
	ds_read_b128 v[216:219], v169 offset:38912
	ds_read_b128 v[220:223], v169 offset:39936
	global_load_lds_dwordx4 v[230:231], off
	v_lshl_add_u64 v[230:231], s[36:37], 0, v[142:143]
	s_mov_b32 m0, s73
	s_nop 0
	global_load_lds_dwordx4 v[230:231], off
	s_cmp_eq_u32 s97, 4
	s_cbranch_scc1 .Lengw3_c
	s_cmp_eq_u32 s97, 8
	s_cbranch_scc1 .Lengw3_d
	s_waitcnt vmcnt(8)
	s_branch .Lengw3_e

; #define PG8_STAGE(bufoff, gbase, voff) do { _Pragma("unroll") for (int _i = 0; _i < 2; ++_i) \
;         __builtin_amdgcn_global_load_lds((const unsigned*)((const char*)(gbase) + (voff)[_i]), (PG8_LAS unsigned*)(lds + (bufoff) + ldsw + _i * 8192), 16, 0, 0); } while (0)
; #define PG8_LDA(dst, b, h) do { _Pragma("unroll") for (int m = 0; m < 4; ++m) _Pragma("unroll") for (int k = 0; k < 2; ++k) dst[m][k] = *(const PG8_LAS bf16x8*)(lds + PG8_SA(b, h) + aoff + m * 2048 + k * 1024); } while (0)
; #define PG8_MMA(ai, bj, At, Bt) do { __builtin_amdgcn_s_setprio(3); _Pragma("unroll") for (int m = 0; m < 4; ++m) _Pragma("unroll") for (int n = 0; n < 2; ++n) _Pragma("unroll") for (int k = 0; k < 2; ++k) \
;         acc[ai][bj][m][n] = __builtin_amdgcn_mfma_f32_16x16x32_bf16(Bt[n][k], At[m][k], acc[ai][bj][m][n], 0, 0, 0); __builtin_amdgcn_s_setprio(0); } while (0)
; #define PG8_WAIT_V(n) asm volatile("s_waitcnt vmcnt(" #n ")" ::: "memory")
; #define PG8_WAIT_L(n) asm volatile("s_waitcnt lgkmcnt(" #n ")" ::: "memory")
; #define PG8_BAR __builtin_amdgcn_s_barrier()
; #define PG8_SCHED __builtin_amdgcn_sched_barrier(0)
; template <class Epi, class Sched, bool ALIGN_EPI = false, bool SP2 = false>
; __device__ __forceinline__ void gemm_phase(PG8_LAS unsigned char* lds, const Gemm g, const Sched& S, const Epi& E) {
;     ...
;             PG8_WAIT_V(8); PG8_WAIT_L(0); PG8_BAR; PG8_MMA(0, 0, At, B0); PG8_MMA(0, 1, At, B1); PG8_BAR; PG8_SCHED;
;             PG8_LDA(At, 1, 1); PG8_STAGE(PG8_SB(1, 0), b3, voffB); PG8_STAGE(PG8_SB(1, 1), b3 + hstepB, voffB); PG8_STAGE(PG8_SA(1, 0), a3, voffA);
;             PG8_WAIT_V(8); PG8_WAIT_L(0); PG8_BAR; PG8_MMA(1, 0, At, B0); PG8_MMA(1, 1, At, B1); PG8_BAR; PG8_SCHED;
;     ...
;         if constexpr (ALIGN_EPI) { if (wr == 0) PG8_BAR; }
;         if constexpr (!Epi::AFTER_DRAIN) { E(acc, cur, wr, wc, fr, fq); S.done(cur); }
.Lengw3_e:
	s_waitcnt lgkmcnt(0)
	s_barrier
	s_setprio 3
	s_waitcnt lgkmcnt(0)
	v_mfma_f32_16x16x32_bf16 v[126:129], v[130:133], v[192:195], v[126:129]
	v_mfma_f32_16x16x32_bf16 v[126:129], v[134:137], v[196:199], v[126:129]
	v_mfma_f32_16x16x32_bf16 v[118:121], v[156:159], v[192:195], v[118:121]
	v_mfma_f32_16x16x32_bf16 v[118:121], v[172:175], v[196:199], v[118:121]
	v_mfma_f32_16x16x32_bf16 v[102:105], v[156:159], v[200:203], v[102:105]
	v_mfma_f32_16x16x32_bf16 v[102:105], v[172:175], v[204:207], v[102:105]
	v_mfma_f32_16x16x32_bf16 v[110:113], v[130:133], v[200:203], v[110:113]
	v_mfma_f32_16x16x32_bf16 v[110:113], v[134:137], v[204:207], v[110:113]
	v_mfma_f32_16x16x32_bf16 v[94:97], v[130:133], v[208:211], v[94:97]
	v_mfma_f32_16x16x32_bf16 v[94:97], v[134:137], v[212:215], v[94:97]
	v_mfma_f32_16x16x32_bf16 v[86:89], v[156:159], v[208:211], v[86:89]
	v_mfma_f32_16x16x32_bf16 v[86:89], v[172:175], v[212:215], v[86:89]
	v_mfma_f32_16x16x32_bf16 v[70:73], v[156:159], v[216:219], v[70:73]
	v_mfma_f32_16x16x32_bf16 v[70:73], v[172:175], v[220:223], v[70:73]
	v_mfma_f32_16x16x32_bf16 v[78:81], v[130:133], v[216:219], v[78:81]
	v_mfma_f32_16x16x32_bf16 v[78:81], v[134:137], v[220:223], v[78:81]
	s_setprio 0
	s_setprio 3
	v_mfma_f32_16x16x32_bf16 v[122:125], v[176:179], v[192:195], v[122:125]
	v_mfma_f32_16x16x32_bf16 v[122:125], v[180:183], v[196:199], v[122:125]
	v_mfma_f32_16x16x32_bf16 v[114:117], v[184:187], v[192:195], v[114:117]
	v_mfma_f32_16x16x32_bf16 v[114:117], v[188:191], v[196:199], v[114:117]
	v_mfma_f32_16x16x32_bf16 v[98:101], v[184:187], v[200:203], v[98:101]
	v_mfma_f32_16x16x32_bf16 v[98:101], v[188:191], v[204:207], v[98:101]
	v_mfma_f32_16x16x32_bf16 v[106:109], v[176:179], v[200:203], v[106:109]
	v_mfma_f32_16x16x32_bf16 v[106:109], v[180:183], v[204:207], v[106:109]
	v_mfma_f32_16x16x32_bf16 v[90:93], v[176:179], v[208:211], v[90:93]
	v_mfma_f32_16x16x32_bf16 v[90:93], v[180:183], v[212:215], v[90:93]
	v_mfma_f32_16x16x32_bf16 v[82:85], v[184:187], v[208:211], v[82:85]
	v_mfma_f32_16x16x32_bf16 v[82:85], v[188:191], v[212:215], v[82:85]
	v_mfma_f32_16x16x32_bf16 v[66:69], v[184:187], v[216:219], v[66:69]
	v_mfma_f32_16x16x32_bf16 v[66:69], v[188:191], v[220:223], v[66:69]
	v_mfma_f32_16x16x32_bf16 v[74:77], v[176:179], v[216:219], v[74:77]
	v_mfma_f32_16x16x32_bf16 v[74:77], v[180:183], v[220:223], v[74:77]
	s_setprio 0
	s_barrier
	s_add_i32 s36, s56, s66
	v_lshl_add_u64 v[160:161], v[160:161], 0, s[18:19]
	s_mov_b32 m0, s36
	ds_read_b128 v[192:195], v169 offset:49152
	ds_read_b128 v[196:199], v169 offset:50176
	ds_read_b128 v[200:203], v169 offset:51200
	ds_read_b128 v[204:207], v169 offset:52224
	ds_read_b128 v[208:211], v169 offset:53248
	ds_read_b128 v[212:215], v169 offset:54272
	ds_read_b128 v[216:219], v169 offset:55296
	ds_read_b128 v[220:223], v169 offset:56320
	global_load_lds_dwordx4 v[160:161], off
	s_add_i32 m0, s36, 0x2000
	s_add_u32 s8, s8, 0x100080
	v_lshl_add_u64 v[160:161], v[224:225], 0, s[18:19]
	s_addc_u32 s9, s9, 0
	s_add_i32 s36, s57, s66
	global_load_lds_dwordx4 v[160:161], off
	v_lshl_add_u64 v[160:161], s[8:9], 0, v[140:141]
	s_mov_b32 m0, s36
	s_nop 0
	global_load_lds_dwordx4 v[160:161], off
	v_lshl_add_u64 v[160:161], s[8:9], 0, v[144:145]
	s_add_i32 m0, s36, 0x2000
	s_nop 0
	global_load_lds_dwordx4 v[160:161], off
	v_lshl_add_u64 v[160:161], v[226:227], 0, s[18:19]
	s_mov_b32 m0, s75
	s_nop 0
	global_load_lds_dwordx4 v[160:161], off
	v_lshl_add_u64 v[160:161], v[228:229], 0, s[18:19]
	s_mov_b32 m0, s76
	s_nop 0
	global_load_lds_dwordx4 v[160:161], off
	s_waitcnt vmcnt(8)
	s_waitcnt lgkmcnt(0)
	s_barrier
	s_setprio 3
	s_waitcnt lgkmcnt(0)
	v_mfma_f32_16x16x32_bf16 v[62:65], v[130:133], v[192:195], v[62:65]
	v_mfma_f32_16x16x32_bf16 v[62:65], v[134:137], v[196:199], v[62:65]
	v_mfma_f32_16x16x32_bf16 v[54:57], v[156:159], v[192:195], v[54:57]
	v_mfma_f32_16x16x32_bf16 v[54:57], v[172:175], v[196:199], v[54:57]
	v_mfma_f32_16x16x32_bf16 v[38:41], v[156:159], v[200:203], v[38:41]
	v_mfma_f32_16x16x32_bf16 v[38:41], v[172:175], v[204:207], v[38:41]
	v_mfma_f32_16x16x32_bf16 v[46:49], v[130:133], v[200:203], v[46:49]
	v_mfma_f32_16x16x32_bf16 v[46:49], v[134:137], v[204:207], v[46:49]
	v_mfma_f32_16x16x32_bf16 v[30:33], v[130:133], v[208:211], v[30:33]
	v_mfma_f32_16x16x32_bf16 v[30:33], v[134:137], v[212:215], v[30:33]
	v_mfma_f32_16x16x32_bf16 v[22:25], v[156:159], v[208:211], v[22:25]
	v_mfma_f32_16x16x32_bf16 v[22:25], v[172:175], v[212:215], v[22:25]
	v_mfma_f32_16x16x32_bf16 v[6:9], v[156:159], v[216:219], v[6:9]
	v_mfma_f32_16x16x32_bf16 v[6:9], v[172:175], v[220:223], v[6:9]
	v_mfma_f32_16x16x32_bf16 v[14:17], v[130:133], v[216:219], v[14:17]
	v_mfma_f32_16x16x32_bf16 v[14:17], v[134:137], v[220:223], v[14:17]
	s_setprio 0
	s_setprio 3
	v_mfma_f32_16x16x32_bf16 v[58:61], v[176:179], v[192:195], v[58:61]
	v_mfma_f32_16x16x32_bf16 v[58:61], v[180:183], v[196:199], v[58:61]
	v_mfma_f32_16x16x32_bf16 v[50:53], v[184:187], v[192:195], v[50:53]
	v_mfma_f32_16x16x32_bf16 v[50:53], v[188:191], v[196:199], v[50:53]
	v_mfma_f32_16x16x32_bf16 v[34:37], v[184:187], v[200:203], v[34:37]
	v_mfma_f32_16x16x32_bf16 v[34:37], v[188:191], v[204:207], v[34:37]
	v_mfma_f32_16x16x32_bf16 v[42:45], v[176:179], v[200:203], v[42:45]
	v_mfma_f32_16x16x32_bf16 v[42:45], v[180:183], v[204:207], v[42:45]
	v_mfma_f32_16x16x32_bf16 v[26:29], v[176:179], v[208:211], v[26:29]
	v_mfma_f32_16x16x32_bf16 v[26:29], v[180:183], v[212:215], v[26:29]
	v_mfma_f32_16x16x32_bf16 v[18:21], v[184:187], v[208:211], v[18:21]
	v_mfma_f32_16x16x32_bf16 v[18:21], v[188:191], v[212:215], v[18:21]
	v_mfma_f32_16x16x32_bf16 v[2:5], v[184:187], v[216:219], v[2:5]
	v_mfma_f32_16x16x32_bf16 v[2:5], v[188:191], v[220:223], v[2:5]
	v_mfma_f32_16x16x32_bf16 v[10:13], v[176:179], v[216:219], v[10:13]
	v_mfma_f32_16x16x32_bf16 v[10:13], v[180:183], v[220:223], v[10:13]
	s_setprio 0
	s_barrier
	s_add_i32 s45, s45, 2
	s_add_u32 s6, s6, 0x100
	s_addc_u32 s7, s7, 0
	s_add_u32 s33, s33, 0x100
	s_addc_u32 s44, s44, 0
	s_cmp_gt_u32 s45, 61
	s_cbranch_scc0 .LBB0_143
	s_and_b64 vcc, exec, s[20:21]
	s_cbranch_vccz .LBB0_148
	s_barrier
	v_lshl_add_u32 v156, s0, 8, v163
	s_cmp_lt_i32 s54, 40
	s_mov_b64 s[0:1], -1
	s_cbranch_scc1 .LBB0_149

; #define PG8_STAGE(bufoff, gbase, voff) do { _Pragma("unroll") for (int _i = 0; _i < 2; ++_i) \
;         __builtin_amdgcn_global_load_lds((const unsigned*)((const char*)(gbase) + (voff)[_i]), (PG8_LAS unsigned*)(lds + (bufoff) + ldsw + _i * 8192), 16, 0, 0); } while (0)
; #define PG8_LDA(dst, b, h) do { _Pragma("unroll") for (int m = 0; m < 4; ++m) _Pragma("unroll") for (int k = 0; k < 2; ++k) dst[m][k] = *(const PG8_LAS bf16x8*)(lds + PG8_SA(b, h) + aoff + m * 2048 + k * 1024); } while (0)
; #define PG8_LDB(dst, b, h) do { _Pragma("unroll") for (int n = 0; n < 2; ++n) _Pragma("unroll") for (int k = 0; k < 2; ++k) dst[n][k] = *(const PG8_LAS bf16x8*)(lds + PG8_SB(b, h) + boff + n * 2048 + k * 1024); } while (0)
; #define PG8_MMA(ai, bj, At, Bt) do { __builtin_amdgcn_s_setprio(3); _Pragma("unroll") for (int m = 0; m < 4; ++m) _Pragma("unroll") for (int n = 0; n < 2; ++n) _Pragma("unroll") for (int k = 0; k < 2; ++k) \
;         acc[ai][bj][m][n] = __builtin_amdgcn_mfma_f32_16x16x32_bf16(Bt[n][k], At[m][k], acc[ai][bj][m][n], 0, 0, 0); __builtin_amdgcn_s_setprio(0); } while (0)
; #define PG8_WAIT_V(n) asm volatile("s_waitcnt vmcnt(" #n ")" ::: "memory")
; #define PG8_WAIT_L(n) asm volatile("s_waitcnt lgkmcnt(" #n ")" ::: "memory")
; #define PG8_BAR __builtin_amdgcn_s_barrier()
; #define PG8_SCHED __builtin_amdgcn_sched_barrier(0)
; template <class Epi, class Sched, bool ALIGN_EPI = false, bool SP2 = false>
; __device__ __forceinline__ void gemm_phase(PG8_LAS unsigned char* lds, const Gemm g, const Sched& S, const Epi& E) {
;     ...
;             const char* a1 = cA + (size_t)(t + 1) * kstep;
;             const char* a2 = last ? nA : cA + (size_t)(t + 2) * kstep; const char* b2 = last ? nB : cB + (size_t)(t + 2) * kstep;
;             const char* a3 = a2 + kstep; const char* b3 = b2 + kstep;
;             if (last && has_next) S.a_ready(nxt);
;             if constexpr (Epi::MIDK) { if (t == E.midk_step(nt)) E.midk(acc, cur, wr, wc, fr, fq); }
;             if constexpr (SP2) {
;             PG8_LDB(B0, 0, 0); PG8_LDB(B1, 0, 1); PG8_SCHED; PG8_LDA(At, 0, 0); PG8_STAGE(PG8_SA(1, 1), a1 + hstepA, voffA);
;             PG8_WAIT_V(8); PG8_WAIT_L(0); PG8_BAR; PG8_MMA(0, 0, At, B0); PG8_MMA(0, 1, At, B1); PG8_BAR; PG8_SCHED;
;             PG8_LDA(At, 0, 1); PG8_STAGE(PG8_SB(0, 0), b2, voffB); PG8_STAGE(PG8_SB(0, 1), b2 + hstepB, voffB); PG8_STAGE(PG8_SA(0, 0), a2, voffA);
.LBB0_478:
	ds_read_b128 v[130:133], v170
	ds_read_b128 v[134:137], v170 offset:1024
	ds_read_b128 v[138:141], v170 offset:2048
	ds_read_b128 v[142:145], v170 offset:3072
	ds_read_b128 v[164:167], v171
	ds_read_b128 v[174:177], v171 offset:1024
	ds_read_b128 v[178:181], v171 offset:2048
	ds_read_b128 v[182:185], v171 offset:3072
	s_add_u32 s36, s6, 0xfff80080
	s_addc_u32 s37, s7, -1
	s_cmp_eq_u32 s79, 4
	s_cselect_b32 s59, s27, s37
	s_cselect_b32 s58, s26, s36
	s_cselect_b32 s37, s23, s78
	s_cselect_b32 s36, s25, s77
	v_lshl_add_u64 v[218:219], s[6:7], 0, v[154:155]
	s_add_i32 m0, s31, 0xc000
	ds_read_b128 v[186:189], v172
	ds_read_b128 v[190:193], v172 offset:1024
	ds_read_b128 v[194:197], v172 offset:2048
	ds_read_b128 v[198:201], v172 offset:3072
	ds_read_b128 v[202:205], v172 offset:4096
	ds_read_b128 v[206:209], v172 offset:5120
	ds_read_b128 v[210:213], v172 offset:6144
	ds_read_b128 v[214:217], v172 offset:7168
	global_load_lds_dwordx4 v[218:219], off
	v_lshl_add_u64 v[218:219], s[6:7], 0, v[156:157]
	s_add_i32 m0, s31, 0xe000
	s_nop 0
	global_load_lds_dwordx4 v[218:219], off
	s_waitcnt vmcnt(8)
	s_waitcnt lgkmcnt(0)
	s_barrier
	s_setprio 3
	s_waitcnt lgkmcnt(0)
	v_mfma_f32_16x16x32_bf16 v[126:129], v[130:133], v[186:189], v[126:129]
	v_mfma_f32_16x16x32_bf16 v[126:129], v[134:137], v[190:193], v[126:129]
	v_mfma_f32_16x16x32_bf16 v[122:125], v[138:141], v[186:189], v[122:125]
	v_mfma_f32_16x16x32_bf16 v[122:125], v[142:145], v[190:193], v[122:125]
	v_mfma_f32_16x16x32_bf16 v[114:117], v[138:141], v[194:197], v[114:117]
	v_mfma_f32_16x16x32_bf16 v[114:117], v[142:145], v[198:201], v[114:117]
	v_mfma_f32_16x16x32_bf16 v[118:121], v[130:133], v[194:197], v[118:121]
	v_mfma_f32_16x16x32_bf16 v[118:121], v[134:137], v[198:201], v[118:121]
	v_mfma_f32_16x16x32_bf16 v[110:113], v[130:133], v[202:205], v[110:113]
	v_mfma_f32_16x16x32_bf16 v[110:113], v[134:137], v[206:209], v[110:113]
	v_mfma_f32_16x16x32_bf16 v[102:105], v[138:141], v[202:205], v[102:105]
	v_mfma_f32_16x16x32_bf16 v[102:105], v[142:145], v[206:209], v[102:105]
	v_mfma_f32_16x16x32_bf16 v[74:77], v[138:141], v[210:213], v[74:77]
	v_mfma_f32_16x16x32_bf16 v[74:77], v[142:145], v[214:217], v[74:77]
	v_mfma_f32_16x16x32_bf16 v[78:81], v[130:133], v[210:213], v[78:81]
	v_mfma_f32_16x16x32_bf16 v[78:81], v[134:137], v[214:217], v[78:81]
	s_setprio 0
	s_setprio 3
	v_mfma_f32_16x16x32_bf16 v[106:109], v[164:167], v[186:189], v[106:109]
	v_mfma_f32_16x16x32_bf16 v[106:109], v[174:177], v[190:193], v[106:109]
	v_mfma_f32_16x16x32_bf16 v[98:101], v[178:181], v[186:189], v[98:101]
	v_mfma_f32_16x16x32_bf16 v[98:101], v[182:185], v[190:193], v[98:101]
	v_mfma_f32_16x16x32_bf16 v[90:93], v[178:181], v[194:197], v[90:93]
	v_mfma_f32_16x16x32_bf16 v[90:93], v[182:185], v[198:201], v[90:93]
	v_mfma_f32_16x16x32_bf16 v[94:97], v[164:167], v[194:197], v[94:97]
	v_mfma_f32_16x16x32_bf16 v[94:97], v[174:177], v[198:201], v[94:97]
	v_mfma_f32_16x16x32_bf16 v[86:89], v[164:167], v[202:205], v[86:89]
	v_mfma_f32_16x16x32_bf16 v[86:89], v[174:177], v[206:209], v[86:89]
	v_mfma_f32_16x16x32_bf16 v[82:85], v[178:181], v[202:205], v[82:85]
	v_mfma_f32_16x16x32_bf16 v[82:85], v[182:185], v[206:209], v[82:85]
	v_mfma_f32_16x16x32_bf16 v[66:69], v[178:181], v[210:213], v[66:69]
	v_mfma_f32_16x16x32_bf16 v[66:69], v[182:185], v[214:217], v[66:69]
	v_mfma_f32_16x16x32_bf16 v[70:73], v[164:167], v[210:213], v[70:73]
	v_mfma_f32_16x16x32_bf16 v[70:73], v[174:177], v[214:217], v[70:73]
	s_setprio 0
	s_barrier
	s_add_i32 s83, s72, s44
	v_lshl_add_u64 v[218:219], s[36:37], 0, v[148:149]
	s_mov_b32 m0, s83
	ds_read_b128 v[186:189], v172 offset:16384
	ds_read_b128 v[190:193], v172 offset:17408
	ds_read_b128 v[194:197], v172 offset:18432
	ds_read_b128 v[198:201], v172 offset:19456
	ds_read_b128 v[202:205], v172 offset:20480
	ds_read_b128 v[206:209], v172 offset:21504
	ds_read_b128 v[210:213], v172 offset:22528
	ds_read_b128 v[214:217], v172 offset:23552
	global_load_lds_dwordx4 v[218:219], off
	s_add_i32 m0, s83, 0x2000
	s_add_u32 s84, s36, 0x20000
	v_lshl_add_u64 v[220:221], s[36:37], 0, v[152:153]
	s_addc_u32 s85, s37, 0
	s_add_i32 s83, s73, s44
	global_load_lds_dwordx4 v[220:221], off
	v_lshl_add_u64 v[222:223], s[84:85], 0, v[148:149]
	s_mov_b32 m0, s83
	v_lshl_add_u64 v[224:225], s[58:59], 0, v[150:151]
	global_load_lds_dwordx4 v[222:223], off
	v_lshl_add_u64 v[222:223], s[84:85], 0, v[152:153]
	s_add_i32 m0, s83, 0x2000
	s_nop 0
	global_load_lds_dwordx4 v[222:223], off
	v_lshl_add_u64 v[222:223], s[58:59], 0, v[146:147]
	s_mov_b32 m0, s31
	s_nop 0
	global_load_lds_dwordx4 v[222:223], off
	s_mov_b32 m0, s45
	s_nop 0
	global_load_lds_dwordx4 v[224:225], off
	s_waitcnt vmcnt(8)
	s_waitcnt lgkmcnt(0)
	s_barrier
; #define PG8_STAGE(bufoff, gbase, voff) do { _Pragma("unroll") for (int _i = 0; _i < 2; ++_i) \
;         __builtin_amdgcn_global_load_lds((const unsigned*)((const char*)(gbase) + (voff)[_i]), (PG8_LAS unsigned*)(lds + (bufoff) + ldsw + _i * 8192), 16, 0, 0); } while (0)
; #define PG8_LDA(dst, b, h) do { _Pragma("unroll") for (int m = 0; m < 4; ++m) _Pragma("unroll") for (int k = 0; k < 2; ++k) dst[m][k] = *(const PG8_LAS bf16x8*)(lds + PG8_SA(b, h) + aoff + m * 2048 + k * 1024); } while (0)
; #define PG8_LDB(dst, b, h) do { _Pragma("unroll") for (int n = 0; n < 2; ++n) _Pragma("unroll") for (int k = 0; k < 2; ++k) dst[n][k] = *(const PG8_LAS bf16x8*)(lds + PG8_SB(b, h) + boff + n * 2048 + k * 1024); } while (0)
; #define PG8_MMA(ai, bj, At, Bt) do { __builtin_amdgcn_s_setprio(3); _Pragma("unroll") for (int m = 0; m < 4; ++m) _Pragma("unroll") for (int n = 0; n < 2; ++n) _Pragma("unroll") for (int k = 0; k < 2; ++k) \
;         acc[ai][bj][m][n] = __builtin_amdgcn_mfma_f32_16x16x32_bf16(Bt[n][k], At[m][k], acc[ai][bj][m][n], 0, 0, 0); __builtin_amdgcn_s_setprio(0); } while (0)
; #define PG8_WAIT_V(n) asm volatile("s_waitcnt vmcnt(" #n ")" ::: "memory")
; #define PG8_WAIT_L(n) asm volatile("s_waitcnt lgkmcnt(" #n ")" ::: "memory")
; #define PG8_BAR __builtin_amdgcn_s_barrier()
; #define PG8_SCHED __builtin_amdgcn_sched_barrier(0)
; template <class Epi, class Sched, bool ALIGN_EPI = false, bool SP2 = false>
; __device__ __forceinline__ void gemm_phase(PG8_LAS unsigned char* lds, const Gemm g, const Sched& S, const Epi& E) {
;     ...
;             PG8_WAIT_V(8); PG8_WAIT_L(0); PG8_BAR; PG8_MMA(1, 0, At, B0); PG8_MMA(1, 1, At, B1); PG8_BAR; PG8_SCHED;
;             PG8_LDB(B0, 1, 0); PG8_LDB(B1, 1, 1); PG8_SCHED; PG8_LDA(At, 1, 0); PG8_STAGE(PG8_SA(0, 1), a2 + hstepA, voffA);
;             PG8_WAIT_V(8); PG8_WAIT_L(0); PG8_BAR; PG8_MMA(0, 0, At, B0); PG8_MMA(0, 1, At, B1); PG8_BAR; PG8_SCHED;
	s_setprio 3
	s_waitcnt lgkmcnt(0)
	v_mfma_f32_16x16x32_bf16 v[62:65], v[130:133], v[186:189], v[62:65]
	v_mfma_f32_16x16x32_bf16 v[62:65], v[134:137], v[190:193], v[62:65]
	v_mfma_f32_16x16x32_bf16 v[58:61], v[138:141], v[186:189], v[58:61]
	v_mfma_f32_16x16x32_bf16 v[58:61], v[142:145], v[190:193], v[58:61]
	v_mfma_f32_16x16x32_bf16 v[46:49], v[138:141], v[194:197], v[46:49]
	v_mfma_f32_16x16x32_bf16 v[46:49], v[142:145], v[198:201], v[46:49]
	v_mfma_f32_16x16x32_bf16 v[54:57], v[130:133], v[194:197], v[54:57]
	v_mfma_f32_16x16x32_bf16 v[54:57], v[134:137], v[198:201], v[54:57]
	v_mfma_f32_16x16x32_bf16 v[38:41], v[130:133], v[202:205], v[38:41]
	v_mfma_f32_16x16x32_bf16 v[38:41], v[134:137], v[206:209], v[38:41]
	v_mfma_f32_16x16x32_bf16 v[30:33], v[138:141], v[202:205], v[30:33]
	v_mfma_f32_16x16x32_bf16 v[30:33], v[142:145], v[206:209], v[30:33]
	v_mfma_f32_16x16x32_bf16 v[14:17], v[138:141], v[210:213], v[14:17]
	v_mfma_f32_16x16x32_bf16 v[14:17], v[142:145], v[214:217], v[14:17]
	v_mfma_f32_16x16x32_bf16 v[22:25], v[130:133], v[210:213], v[22:25]
	v_mfma_f32_16x16x32_bf16 v[22:25], v[134:137], v[214:217], v[22:25]
	s_setprio 0
	s_setprio 3
	v_mfma_f32_16x16x32_bf16 v[50:53], v[164:167], v[186:189], v[50:53]
	v_mfma_f32_16x16x32_bf16 v[50:53], v[174:177], v[190:193], v[50:53]
	v_mfma_f32_16x16x32_bf16 v[42:45], v[178:181], v[186:189], v[42:45]
	v_mfma_f32_16x16x32_bf16 v[42:45], v[182:185], v[190:193], v[42:45]
	v_mfma_f32_16x16x32_bf16 v[26:29], v[178:181], v[194:197], v[26:29]
	v_mfma_f32_16x16x32_bf16 v[26:29], v[182:185], v[198:201], v[26:29]
	v_mfma_f32_16x16x32_bf16 v[34:37], v[164:167], v[194:197], v[34:37]
	v_mfma_f32_16x16x32_bf16 v[34:37], v[174:177], v[198:201], v[34:37]
	v_mfma_f32_16x16x32_bf16 v[18:21], v[164:167], v[202:205], v[18:21]
	v_mfma_f32_16x16x32_bf16 v[18:21], v[174:177], v[206:209], v[18:21]
	v_mfma_f32_16x16x32_bf16 v[10:13], v[178:181], v[202:205], v[10:13]
	v_mfma_f32_16x16x32_bf16 v[10:13], v[182:185], v[206:209], v[10:13]
	v_mfma_f32_16x16x32_bf16 v[2:5], v[178:181], v[210:213], v[2:5]
	v_mfma_f32_16x16x32_bf16 v[2:5], v[182:185], v[214:217], v[2:5]
	v_mfma_f32_16x16x32_bf16 v[6:9], v[164:167], v[210:213], v[6:9]
	v_mfma_f32_16x16x32_bf16 v[6:9], v[174:177], v[214:217], v[6:9]
	s_setprio 0
	s_barrier
	s_add_i32 s83, 0, 0x18000
	s_add_i32 s84, 0, 0x1c000
	v_add_u32_e32 v142, s83, v168
	v_add_u32_e32 v173, s84, v168
	ds_read_b128 v[130:133], v142
	ds_read_b128 v[134:137], v142 offset:1024
	ds_read_b128 v[138:141], v142 offset:2048
	ds_read_b128 v[142:145], v142 offset:3072
	ds_read_b128 v[164:167], v173
	ds_read_b128 v[174:177], v173 offset:1024
	ds_read_b128 v[178:181], v173 offset:2048
	ds_read_b128 v[182:185], v173 offset:3072
	s_add_u32 s58, s58, 0x80000
	s_addc_u32 s59, s59, 0
	s_mov_b32 m0, s54
	v_lshl_add_u64 v[226:227], s[58:59], 0, v[146:147]
	ds_read_b128 v[186:189], v172 offset:32768
	ds_read_b128 v[190:193], v172 offset:33792
	ds_read_b128 v[194:197], v172 offset:34816
	ds_read_b128 v[198:201], v172 offset:35840
	ds_read_b128 v[202:205], v172 offset:36864
	ds_read_b128 v[206:209], v172 offset:37888
	ds_read_b128 v[210:213], v172 offset:38912
	ds_read_b128 v[214:217], v172 offset:39936
	global_load_lds_dwordx4 v[226:227], off
	v_lshl_add_u64 v[226:227], s[58:59], 0, v[150:151]
	s_mov_b32 m0, s55
	s_nop 0
	global_load_lds_dwordx4 v[226:227], off
	s_waitcnt vmcnt(8)
	s_waitcnt lgkmcnt(0)
	s_barrier
	s_setprio 3
	s_waitcnt lgkmcnt(0)
	v_mfma_f32_16x16x32_bf16 v[126:129], v[130:133], v[186:189], v[126:129]
	v_mfma_f32_16x16x32_bf16 v[126:129], v[134:137], v[190:193], v[126:129]
	v_mfma_f32_16x16x32_bf16 v[122:125], v[138:141], v[186:189], v[122:125]
	v_mfma_f32_16x16x32_bf16 v[122:125], v[142:145], v[190:193], v[122:125]
	v_mfma_f32_16x16x32_bf16 v[114:117], v[138:141], v[194:197], v[114:117]
	v_mfma_f32_16x16x32_bf16 v[114:117], v[142:145], v[198:201], v[114:117]
	v_mfma_f32_16x16x32_bf16 v[118:121], v[130:133], v[194:197], v[118:121]
	v_mfma_f32_16x16x32_bf16 v[118:121], v[134:137], v[198:201], v[118:121]
	v_mfma_f32_16x16x32_bf16 v[110:113], v[130:133], v[202:205], v[110:113]
	v_mfma_f32_16x16x32_bf16 v[110:113], v[134:137], v[206:209], v[110:113]
	v_mfma_f32_16x16x32_bf16 v[102:105], v[138:141], v[202:205], v[102:105]
	v_mfma_f32_16x16x32_bf16 v[102:105], v[142:145], v[206:209], v[102:105]
	v_mfma_f32_16x16x32_bf16 v[74:77], v[138:141], v[210:213], v[74:77]
	v_mfma_f32_16x16x32_bf16 v[74:77], v[142:145], v[214:217], v[74:77]
	v_mfma_f32_16x16x32_bf16 v[78:81], v[130:133], v[210:213], v[78:81]
	v_mfma_f32_16x16x32_bf16 v[78:81], v[134:137], v[214:217], v[78:81]
	s_setprio 0
	s_setprio 3
	v_mfma_f32_16x16x32_bf16 v[106:109], v[164:167], v[186:189], v[106:109]
	v_mfma_f32_16x16x32_bf16 v[106:109], v[174:177], v[190:193], v[106:109]
	v_mfma_f32_16x16x32_bf16 v[98:101], v[178:181], v[186:189], v[98:101]
	v_mfma_f32_16x16x32_bf16 v[98:101], v[182:185], v[190:193], v[98:101]
	v_mfma_f32_16x16x32_bf16 v[90:93], v[178:181], v[194:197], v[90:93]
	v_mfma_f32_16x16x32_bf16 v[90:93], v[182:185], v[198:201], v[90:93]
	v_mfma_f32_16x16x32_bf16 v[94:97], v[164:167], v[194:197], v[94:97]
	v_mfma_f32_16x16x32_bf16 v[94:97], v[174:177], v[198:201], v[94:97]
	v_mfma_f32_16x16x32_bf16 v[86:89], v[164:167], v[202:205], v[86:89]
	v_mfma_f32_16x16x32_bf16 v[86:89], v[174:177], v[206:209], v[86:89]
	v_mfma_f32_16x16x32_bf16 v[82:85], v[178:181], v[202:205], v[82:85]
	v_mfma_f32_16x16x32_bf16 v[82:85], v[182:185], v[206:209], v[82:85]
	v_mfma_f32_16x16x32_bf16 v[66:69], v[178:181], v[210:213], v[66:69]
	v_mfma_f32_16x16x32_bf16 v[66:69], v[182:185], v[214:217], v[66:69]
	v_mfma_f32_16x16x32_bf16 v[70:73], v[164:167], v[210:213], v[70:73]
	v_mfma_f32_16x16x32_bf16 v[70:73], v[174:177], v[214:217], v[70:73]
	s_setprio 0
	s_barrier
; #define PG8_STAGE(bufoff, gbase, voff) do { _Pragma("unroll") for (int _i = 0; _i < 2; ++_i) \
;         __builtin_amdgcn_global_load_lds((const unsigned*)((const char*)(gbase) + (voff)[_i]), (PG8_LAS unsigned*)(lds + (bufoff) + ldsw + _i * 8192), 16, 0, 0); } while (0)
; #define PG8_LDA(dst, b, h) do { _Pragma("unroll") for (int m = 0; m < 4; ++m) _Pragma("unroll") for (int k = 0; k < 2; ++k) dst[m][k] = *(const PG8_LAS bf16x8*)(lds + PG8_SA(b, h) + aoff + m * 2048 + k * 1024); } while (0)
; #define PG8_MMA(ai, bj, At, Bt) do { __builtin_amdgcn_s_setprio(3); _Pragma("unroll") for (int m = 0; m < 4; ++m) _Pragma("unroll") for (int n = 0; n < 2; ++n) _Pragma("unroll") for (int k = 0; k < 2; ++k) \
;         acc[ai][bj][m][n] = __builtin_amdgcn_mfma_f32_16x16x32_bf16(Bt[n][k], At[m][k], acc[ai][bj][m][n], 0, 0, 0); __builtin_amdgcn_s_setprio(0); } while (0)
; #define PG8_WAIT_V(n) asm volatile("s_waitcnt vmcnt(" #n ")" ::: "memory")
; #define PG8_WAIT_L(n) asm volatile("s_waitcnt lgkmcnt(" #n ")" ::: "memory")
; #define PG8_BAR __builtin_amdgcn_s_barrier()
; #define PG8_SCHED __builtin_amdgcn_sched_barrier(0)
; template <class Epi, class Sched, bool ALIGN_EPI = false, bool SP2 = false>
; __device__ __forceinline__ void gemm_phase(PG8_LAS unsigned char* lds, const Gemm g, const Sched& S, const Epi& E) {
;     ...
;             PG8_LDA(At, 1, 1); PG8_STAGE(PG8_SB(1, 0), b3, voffB); PG8_STAGE(PG8_SB(1, 1), b3 + hstepB, voffB); PG8_STAGE(PG8_SA(1, 0), a3, voffA);
;             PG8_WAIT_V(8); PG8_WAIT_L(0); PG8_BAR; PG8_MMA(1, 0, At, B0); PG8_MMA(1, 1, At, B1); PG8_BAR; PG8_SCHED;
	s_add_i32 s58, s83, s44
	v_lshl_add_u64 v[218:219], v[218:219], 0, s[18:19]
	s_mov_b32 m0, s58
	ds_read_b128 v[186:189], v172 offset:49152
	ds_read_b128 v[190:193], v172 offset:50176
	ds_read_b128 v[194:197], v172 offset:51200
	ds_read_b128 v[198:201], v172 offset:52224
	ds_read_b128 v[202:205], v172 offset:53248
	ds_read_b128 v[206:209], v172 offset:54272
	ds_read_b128 v[210:213], v172 offset:55296
	ds_read_b128 v[214:217], v172 offset:56320
	global_load_lds_dwordx4 v[218:219], off
	s_add_i32 m0, s58, 0x2000
	s_add_u32 s36, s36, 0x20080
	v_lshl_add_u64 v[218:219], v[220:221], 0, s[18:19]
	s_addc_u32 s37, s37, 0
	s_add_i32 s58, s84, s44
	global_load_lds_dwordx4 v[218:219], off
	v_lshl_add_u64 v[218:219], s[36:37], 0, v[148:149]
	s_mov_b32 m0, s58
	s_nop 0
	global_load_lds_dwordx4 v[218:219], off
	v_lshl_add_u64 v[218:219], s[36:37], 0, v[152:153]
	s_add_i32 m0, s58, 0x2000
	s_nop 0
	global_load_lds_dwordx4 v[218:219], off
	v_lshl_add_u64 v[218:219], v[222:223], 0, s[18:19]
	s_mov_b32 m0, s63
	s_nop 0
	global_load_lds_dwordx4 v[218:219], off
	v_lshl_add_u64 v[218:219], v[224:225], 0, s[18:19]
	s_mov_b32 m0, s66
	s_nop 0
	global_load_lds_dwordx4 v[218:219], off
	s_waitcnt vmcnt(8)
	s_waitcnt lgkmcnt(0)
	s_barrier
	s_setprio 3
	s_waitcnt lgkmcnt(0)
	v_mfma_f32_16x16x32_bf16 v[62:65], v[130:133], v[186:189], v[62:65]
	v_mfma_f32_16x16x32_bf16 v[62:65], v[134:137], v[190:193], v[62:65]
	v_mfma_f32_16x16x32_bf16 v[58:61], v[138:141], v[186:189], v[58:61]
	v_mfma_f32_16x16x32_bf16 v[58:61], v[142:145], v[190:193], v[58:61]
	v_mfma_f32_16x16x32_bf16 v[46:49], v[138:141], v[194:197], v[46:49]
	v_mfma_f32_16x16x32_bf16 v[46:49], v[142:145], v[198:201], v[46:49]
	v_mfma_f32_16x16x32_bf16 v[54:57], v[130:133], v[194:197], v[54:57]
	v_mfma_f32_16x16x32_bf16 v[54:57], v[134:137], v[198:201], v[54:57]
	v_mfma_f32_16x16x32_bf16 v[38:41], v[130:133], v[202:205], v[38:41]
	v_mfma_f32_16x16x32_bf16 v[38:41], v[134:137], v[206:209], v[38:41]
	v_mfma_f32_16x16x32_bf16 v[30:33], v[138:141], v[202:205], v[30:33]
	v_mfma_f32_16x16x32_bf16 v[30:33], v[142:145], v[206:209], v[30:33]
	v_mfma_f32_16x16x32_bf16 v[14:17], v[138:141], v[210:213], v[14:17]
	v_mfma_f32_16x16x32_bf16 v[14:17], v[142:145], v[214:217], v[14:17]
	v_mfma_f32_16x16x32_bf16 v[22:25], v[130:133], v[210:213], v[22:25]
	v_mfma_f32_16x16x32_bf16 v[22:25], v[134:137], v[214:217], v[22:25]
	s_setprio 0
	s_setprio 3
	v_mfma_f32_16x16x32_bf16 v[50:53], v[164:167], v[186:189], v[50:53]
	v_mfma_f32_16x16x32_bf16 v[50:53], v[174:177], v[190:193], v[50:53]
	v_mfma_f32_16x16x32_bf16 v[42:45], v[178:181], v[186:189], v[42:45]
	v_mfma_f32_16x16x32_bf16 v[42:45], v[182:185], v[190:193], v[42:45]
	v_mfma_f32_16x16x32_bf16 v[26:29], v[178:181], v[194:197], v[26:29]
	v_mfma_f32_16x16x32_bf16 v[26:29], v[182:185], v[198:201], v[26:29]
	v_mfma_f32_16x16x32_bf16 v[34:37], v[164:167], v[194:197], v[34:37]
	v_mfma_f32_16x16x32_bf16 v[34:37], v[174:177], v[198:201], v[34:37]
	v_mfma_f32_16x16x32_bf16 v[18:21], v[164:167], v[202:205], v[18:21]
	v_mfma_f32_16x16x32_bf16 v[18:21], v[174:177], v[206:209], v[18:21]
	v_mfma_f32_16x16x32_bf16 v[10:13], v[178:181], v[202:205], v[10:13]
	v_mfma_f32_16x16x32_bf16 v[10:13], v[182:185], v[206:209], v[10:13]
	v_mfma_f32_16x16x32_bf16 v[2:5], v[178:181], v[210:213], v[2:5]
	v_mfma_f32_16x16x32_bf16 v[2:5], v[182:185], v[214:217], v[2:5]
	v_mfma_f32_16x16x32_bf16 v[6:9], v[164:167], v[210:213], v[6:9]
	v_mfma_f32_16x16x32_bf16 v[6:9], v[174:177], v[214:217], v[6:9]
	s_setprio 0
	s_barrier
	s_add_i32 s79, s79, 2
	s_add_u32 s6, s6, 0x100
	s_addc_u32 s7, s7, 0
	s_add_u32 s77, s77, 0x100
	s_addc_u32 s78, s78, 0
	s_cmp_gt_u32 s79, 5
	s_cbranch_scc0 .LBB0_478
	s_and_b64 vcc, exec, s[20:21]
	s_cbranch_vccz .LBB0_481
	s_barrier

; #define PG8_STAGE(bufoff, gbase, voff) do { _Pragma("unroll") for (int _i = 0; _i < 2; ++_i) \
;         __builtin_amdgcn_global_load_lds((const unsigned*)((const char*)(gbase) + (voff)[_i]), (PG8_LAS unsigned*)(lds + (bufoff) + ldsw + _i * 8192), 16, 0, 0); } while (0)
; #define PG8_LDA(dst, b, h) do { _Pragma("unroll") for (int m = 0; m < 4; ++m) _Pragma("unroll") for (int k = 0; k < 2; ++k) dst[m][k] = *(const PG8_LAS bf16x8*)(lds + PG8_SA(b, h) + aoff + m * 2048 + k * 1024); } while (0)
; #define PG8_LDB(dst, b, h) do { _Pragma("unroll") for (int n = 0; n < 2; ++n) _Pragma("unroll") for (int k = 0; k < 2; ++k) dst[n][k] = *(const PG8_LAS bf16x8*)(lds + PG8_SB(b, h) + boff + n * 2048 + k * 1024); } while (0)
; #define PG8_MMA(ai, bj, At, Bt) do { __builtin_amdgcn_s_setprio(3); _Pragma("unroll") for (int m = 0; m < 4; ++m) _Pragma("unroll") for (int n = 0; n < 2; ++n) _Pragma("unroll") for (int k = 0; k < 2; ++k) \
;         acc[ai][bj][m][n] = __builtin_amdgcn_mfma_f32_16x16x32_bf16(Bt[n][k], At[m][k], acc[ai][bj][m][n], 0, 0, 0); __builtin_amdgcn_s_setprio(0); } while (0)
; #define PG8_WAIT_V(n) asm volatile("s_waitcnt vmcnt(" #n ")" ::: "memory")
; #define PG8_WAIT_L(n) asm volatile("s_waitcnt lgkmcnt(" #n ")" ::: "memory")
; template <class Epi, class Sched, bool ALIGN_EPI = false, bool SP2 = false>
; __device__ __forceinline__ void gemm_phase(PG8_LAS unsigned char* lds, const Gemm g, const Sched& S, const Epi& E) {
;     ...
;         for (int t = 0; t < nt; t += 2) {
;             const bool last = (t == nt - 2);
;             const char* a1 = cA + (size_t)(t + 1) * kstep;
;             const char* a2 = last ? nA : cA + (size_t)(t + 2) * kstep; const char* b2 = last ? nB : cB + (size_t)(t + 2) * kstep;
;             const char* a3 = a2 + kstep; const char* b3 = b2 + kstep;
;             if (last && has_next) S.a_ready(nxt);
;             if constexpr (Epi::MIDK) { if (t == E.midk_step(nt)) E.midk(acc, cur, wr, wc, fr, fq); }
;             if constexpr (SP2) {
;             PG8_LDB(B0, 0, 0); PG8_LDB(B1, 0, 1); PG8_SCHED; PG8_LDA(At, 0, 0); PG8_STAGE(PG8_SA(1, 1), a1 + hstepA, voffA);
;             PG8_WAIT_V(8); PG8_WAIT_L(0); PG8_BAR; PG8_MMA(0, 0, At, B0); PG8_MMA(0, 1, At, B1); PG8_BAR; PG8_SCHED;
;             PG8_LDA(At, 0, 1); PG8_STAGE(PG8_SB(0, 0), b2, voffB); PG8_STAGE(PG8_SB(0, 1), b2 + hstepB, voffB); PG8_STAGE(PG8_SA(0, 0), a2, voffA);
.LBB0_727:
	v_add_u32_e32 v160, s66, v157
	ds_read_b128 v[130:133], v160
	ds_read_b128 v[164:167], v160 offset:1024
	ds_read_b128 v[168:171], v160 offset:2048
	ds_read_b128 v[172:175], v160 offset:3072
	v_add_u32_e32 v160, s67, v157
	s_add_u32 s0, s28, s30
	ds_read_b128 v[176:179], v160
	ds_read_b128 v[180:183], v160 offset:1024
	ds_read_b128 v[184:187], v160 offset:2048
	ds_read_b128 v[188:191], v160 offset:3072
	s_addc_u32 s1, s29, s31
	s_add_u32 s0, s0, 0x100
	s_addc_u32 s1, s1, 0
	s_add_u32 s84, s79, s30
	s_addc_u32 s85, s81, s31
	s_cmpk_eq_i32 s30, 0x1f00
	s_cselect_b32 s37, s23, s1
	s_cselect_b32 s36, s72, s0
	s_cselect_b32 s1, s75, s85
	s_cselect_b32 s0, s76, s84
	v_lshl_add_u64 v[160:161], v[150:151], 0, s[30:31]
	s_add_i32 m0, s44, 0xc000
	ds_read_b128 v[192:195], v159
	ds_read_b128 v[196:199], v159 offset:1024
	ds_read_b128 v[200:203], v159 offset:2048
	ds_read_b128 v[204:207], v159 offset:3072
	ds_read_b128 v[208:211], v159 offset:4096
	ds_read_b128 v[212:215], v159 offset:5120
	ds_read_b128 v[216:219], v159 offset:6144
	ds_read_b128 v[220:223], v159 offset:7168
	global_load_lds_dwordx4 v[160:161], off
	v_lshl_add_u64 v[160:161], v[152:153], 0, s[30:31]
	s_add_i32 m0, s44, 0xe000
	s_nop 0
	global_load_lds_dwordx4 v[160:161], off
	s_waitcnt vmcnt(8)
	s_waitcnt lgkmcnt(0)
	s_barrier
	s_setprio 3
	s_waitcnt lgkmcnt(0)
	v_mfma_f32_16x16x32_bf16 v[126:129], v[130:133], v[192:195], v[126:129]
	v_mfma_f32_16x16x32_bf16 v[126:129], v[164:167], v[196:199], v[126:129]
	v_mfma_f32_16x16x32_bf16 v[122:125], v[168:171], v[192:195], v[122:125]
	v_mfma_f32_16x16x32_bf16 v[122:125], v[172:175], v[196:199], v[122:125]
	v_mfma_f32_16x16x32_bf16 v[106:109], v[168:171], v[200:203], v[106:109]
	v_mfma_f32_16x16x32_bf16 v[106:109], v[172:175], v[204:207], v[106:109]
	v_mfma_f32_16x16x32_bf16 v[110:113], v[130:133], v[200:203], v[110:113]
	v_mfma_f32_16x16x32_bf16 v[110:113], v[164:167], v[204:207], v[110:113]
	v_mfma_f32_16x16x32_bf16 v[94:97], v[130:133], v[208:211], v[94:97]
	v_mfma_f32_16x16x32_bf16 v[94:97], v[164:167], v[212:215], v[94:97]
	v_mfma_f32_16x16x32_bf16 v[90:93], v[168:171], v[208:211], v[90:93]
	v_mfma_f32_16x16x32_bf16 v[90:93], v[172:175], v[212:215], v[90:93]
	v_mfma_f32_16x16x32_bf16 v[74:77], v[168:171], v[216:219], v[74:77]
	v_mfma_f32_16x16x32_bf16 v[74:77], v[172:175], v[220:223], v[74:77]
	v_mfma_f32_16x16x32_bf16 v[78:81], v[130:133], v[216:219], v[78:81]
	v_mfma_f32_16x16x32_bf16 v[78:81], v[164:167], v[220:223], v[78:81]
	s_setprio 0
	s_setprio 3
	v_mfma_f32_16x16x32_bf16 v[118:121], v[176:179], v[192:195], v[118:121]
	v_mfma_f32_16x16x32_bf16 v[118:121], v[180:183], v[196:199], v[118:121]
	v_mfma_f32_16x16x32_bf16 v[114:117], v[184:187], v[192:195], v[114:117]
	v_mfma_f32_16x16x32_bf16 v[114:117], v[188:191], v[196:199], v[114:117]
	v_mfma_f32_16x16x32_bf16 v[98:101], v[184:187], v[200:203], v[98:101]
	v_mfma_f32_16x16x32_bf16 v[98:101], v[188:191], v[204:207], v[98:101]
	v_mfma_f32_16x16x32_bf16 v[102:105], v[176:179], v[200:203], v[102:105]
	v_mfma_f32_16x16x32_bf16 v[102:105], v[180:183], v[204:207], v[102:105]
	v_mfma_f32_16x16x32_bf16 v[86:89], v[176:179], v[208:211], v[86:89]
	v_mfma_f32_16x16x32_bf16 v[86:89], v[180:183], v[212:215], v[86:89]
	v_mfma_f32_16x16x32_bf16 v[82:85], v[184:187], v[208:211], v[82:85]
	v_mfma_f32_16x16x32_bf16 v[82:85], v[188:191], v[212:215], v[82:85]
	v_mfma_f32_16x16x32_bf16 v[66:69], v[184:187], v[216:219], v[66:69]
	v_mfma_f32_16x16x32_bf16 v[66:69], v[188:191], v[220:223], v[66:69]
	v_mfma_f32_16x16x32_bf16 v[70:73], v[176:179], v[216:219], v[70:73]
	v_mfma_f32_16x16x32_bf16 v[70:73], v[180:183], v[220:223], v[70:73]
	s_setprio 0
	s_barrier
	s_add_i32 s84, s66, s33
	v_lshl_add_u64 v[160:161], s[0:1], 0, v[136:137]
	s_mov_b32 m0, s84
	ds_read_b128 v[192:195], v159 offset:16384
	ds_read_b128 v[196:199], v159 offset:17408
	ds_read_b128 v[200:203], v159 offset:18432
	ds_read_b128 v[204:207], v159 offset:19456
	ds_read_b128 v[208:211], v159 offset:20480
	ds_read_b128 v[212:215], v159 offset:21504
	ds_read_b128 v[216:219], v159 offset:22528
	ds_read_b128 v[220:223], v159 offset:23552
	global_load_lds_dwordx4 v[160:161], off
	s_add_i32 m0, s84, 0x2000
	s_add_u32 s84, s0, 0x100000
	v_lshl_add_u64 v[224:225], s[0:1], 0, v[140:141]
	s_addc_u32 s85, s1, 0
	s_add_i32 s86, s67, s33
	global_load_lds_dwordx4 v[224:225], off
	v_lshl_add_u64 v[226:227], s[84:85], 0, v[136:137]
	s_mov_b32 m0, s86
	v_lshl_add_u64 v[228:229], s[36:37], 0, v[138:139]
	global_load_lds_dwordx4 v[226:227], off
	v_lshl_add_u64 v[226:227], s[84:85], 0, v[140:141]
	s_add_i32 m0, s86, 0x2000
	s_nop 0
	global_load_lds_dwordx4 v[226:227], off
	v_lshl_add_u64 v[226:227], s[36:37], 0, v[134:135]
	s_mov_b32 m0, s44
	s_nop 0
	global_load_lds_dwordx4 v[226:227], off
	s_mov_b32 m0, s45
	s_nop 0
	global_load_lds_dwordx4 v[228:229], off
	s_waitcnt vmcnt(8)
	s_waitcnt lgkmcnt(0)
	s_barrier
; #define PG8_STAGE(bufoff, gbase, voff) do { _Pragma("unroll") for (int _i = 0; _i < 2; ++_i) \
;         __builtin_amdgcn_global_load_lds((const unsigned*)((const char*)(gbase) + (voff)[_i]), (PG8_LAS unsigned*)(lds + (bufoff) + ldsw + _i * 8192), 16, 0, 0); } while (0)
; #define PG8_LDA(dst, b, h) do { _Pragma("unroll") for (int m = 0; m < 4; ++m) _Pragma("unroll") for (int k = 0; k < 2; ++k) dst[m][k] = *(const PG8_LAS bf16x8*)(lds + PG8_SA(b, h) + aoff + m * 2048 + k * 1024); } while (0)
; #define PG8_LDB(dst, b, h) do { _Pragma("unroll") for (int n = 0; n < 2; ++n) _Pragma("unroll") for (int k = 0; k < 2; ++k) dst[n][k] = *(const PG8_LAS bf16x8*)(lds + PG8_SB(b, h) + boff + n * 2048 + k * 1024); } while (0)
; #define PG8_MMA(ai, bj, At, Bt) do { __builtin_amdgcn_s_setprio(3); _Pragma("unroll") for (int m = 0; m < 4; ++m) _Pragma("unroll") for (int n = 0; n < 2; ++n) _Pragma("unroll") for (int k = 0; k < 2; ++k) \
;         acc[ai][bj][m][n] = __builtin_amdgcn_mfma_f32_16x16x32_bf16(Bt[n][k], At[m][k], acc[ai][bj][m][n], 0, 0, 0); __builtin_amdgcn_s_setprio(0); } while (0)
; #define PG8_WAIT_V(n) asm volatile("s_waitcnt vmcnt(" #n ")" ::: "memory")
; #define PG8_WAIT_L(n) asm volatile("s_waitcnt lgkmcnt(" #n ")" ::: "memory")
; #define PG8_BAR __builtin_amdgcn_s_barrier()
; #define PG8_SCHED __builtin_amdgcn_sched_barrier(0)
; template <class Epi, class Sched, bool ALIGN_EPI = false, bool SP2 = false>
; __device__ __forceinline__ void gemm_phase(PG8_LAS unsigned char* lds, const Gemm g, const Sched& S, const Epi& E) {
;     ...
;             PG8_WAIT_V(8); PG8_WAIT_L(0); PG8_BAR; PG8_MMA(1, 0, At, B0); PG8_MMA(1, 1, At, B1); PG8_BAR; PG8_SCHED;
;             PG8_LDB(B0, 1, 0); PG8_LDB(B1, 1, 1); PG8_SCHED; PG8_LDA(At, 1, 0); PG8_STAGE(PG8_SA(0, 1), a2 + hstepA, voffA);
;             PG8_WAIT_V(8); PG8_WAIT_L(0); PG8_BAR; PG8_MMA(0, 0, At, B0); PG8_MMA(0, 1, At, B1); PG8_BAR; PG8_SCHED;
	s_setprio 3
	s_waitcnt lgkmcnt(0)
	v_mfma_f32_16x16x32_bf16 v[62:65], v[130:133], v[192:195], v[62:65]
	v_mfma_f32_16x16x32_bf16 v[62:65], v[164:167], v[196:199], v[62:65]
	v_mfma_f32_16x16x32_bf16 v[58:61], v[168:171], v[192:195], v[58:61]
	v_mfma_f32_16x16x32_bf16 v[58:61], v[172:175], v[196:199], v[58:61]
	v_mfma_f32_16x16x32_bf16 v[42:45], v[168:171], v[200:203], v[42:45]
	v_mfma_f32_16x16x32_bf16 v[42:45], v[172:175], v[204:207], v[42:45]
	v_mfma_f32_16x16x32_bf16 v[46:49], v[130:133], v[200:203], v[46:49]
	v_mfma_f32_16x16x32_bf16 v[46:49], v[164:167], v[204:207], v[46:49]
	v_mfma_f32_16x16x32_bf16 v[30:33], v[130:133], v[208:211], v[30:33]
	v_mfma_f32_16x16x32_bf16 v[30:33], v[164:167], v[212:215], v[30:33]
	v_mfma_f32_16x16x32_bf16 v[26:29], v[168:171], v[208:211], v[26:29]
	v_mfma_f32_16x16x32_bf16 v[26:29], v[172:175], v[212:215], v[26:29]
	v_mfma_f32_16x16x32_bf16 v[10:13], v[168:171], v[216:219], v[10:13]
	v_mfma_f32_16x16x32_bf16 v[10:13], v[172:175], v[220:223], v[10:13]
	v_mfma_f32_16x16x32_bf16 v[14:17], v[130:133], v[216:219], v[14:17]
	v_mfma_f32_16x16x32_bf16 v[14:17], v[164:167], v[220:223], v[14:17]
	s_setprio 0
	s_setprio 3
	v_mfma_f32_16x16x32_bf16 v[54:57], v[176:179], v[192:195], v[54:57]
	v_mfma_f32_16x16x32_bf16 v[54:57], v[180:183], v[196:199], v[54:57]
	v_mfma_f32_16x16x32_bf16 v[50:53], v[184:187], v[192:195], v[50:53]
	v_mfma_f32_16x16x32_bf16 v[50:53], v[188:191], v[196:199], v[50:53]
	v_mfma_f32_16x16x32_bf16 v[34:37], v[184:187], v[200:203], v[34:37]
	v_mfma_f32_16x16x32_bf16 v[34:37], v[188:191], v[204:207], v[34:37]
	v_mfma_f32_16x16x32_bf16 v[38:41], v[176:179], v[200:203], v[38:41]
	v_mfma_f32_16x16x32_bf16 v[38:41], v[180:183], v[204:207], v[38:41]
	v_mfma_f32_16x16x32_bf16 v[22:25], v[176:179], v[208:211], v[22:25]
	v_mfma_f32_16x16x32_bf16 v[22:25], v[180:183], v[212:215], v[22:25]
	v_mfma_f32_16x16x32_bf16 v[18:21], v[184:187], v[208:211], v[18:21]
	v_mfma_f32_16x16x32_bf16 v[18:21], v[188:191], v[212:215], v[18:21]
	v_mfma_f32_16x16x32_bf16 v[2:5], v[184:187], v[216:219], v[2:5]
	v_mfma_f32_16x16x32_bf16 v[2:5], v[188:191], v[220:223], v[2:5]
	v_mfma_f32_16x16x32_bf16 v[6:9], v[176:179], v[216:219], v[6:9]
	v_mfma_f32_16x16x32_bf16 v[6:9], v[180:183], v[220:223], v[6:9]
	s_setprio 0
	s_barrier
	s_add_i32 s84, 0, 0x18000
	v_add_u32_e32 v163, s84, v157
	s_add_i32 s85, 0, 0x1c000
	ds_read_b128 v[130:133], v163
	ds_read_b128 v[164:167], v163 offset:1024
	ds_read_b128 v[168:171], v163 offset:2048
	ds_read_b128 v[172:175], v163 offset:3072
	v_add_u32_e32 v163, s85, v157
	ds_read_b128 v[176:179], v163
	ds_read_b128 v[180:183], v163 offset:1024
	ds_read_b128 v[184:187], v163 offset:2048
	ds_read_b128 v[188:191], v163 offset:3072
	s_add_u32 s36, s36, 0x100000
	s_addc_u32 s37, s37, 0
	s_mov_b32 m0, s54
	v_lshl_add_u64 v[230:231], s[36:37], 0, v[134:135]
	ds_read_b128 v[192:195], v159 offset:32768
	ds_read_b128 v[196:199], v159 offset:33792
	ds_read_b128 v[200:203], v159 offset:34816
	ds_read_b128 v[204:207], v159 offset:35840
	ds_read_b128 v[208:211], v159 offset:36864
	ds_read_b128 v[212:215], v159 offset:37888
	ds_read_b128 v[216:219], v159 offset:38912
	ds_read_b128 v[220:223], v159 offset:39936
	global_load_lds_dwordx4 v[230:231], off
	v_lshl_add_u64 v[230:231], s[36:37], 0, v[138:139]
	s_mov_b32 m0, s55
	s_nop 0
	global_load_lds_dwordx4 v[230:231], off
	s_waitcnt vmcnt(8)
	s_waitcnt lgkmcnt(0)
	s_barrier
	s_setprio 3
	s_waitcnt lgkmcnt(0)
	v_mfma_f32_16x16x32_bf16 v[126:129], v[130:133], v[192:195], v[126:129]
	v_mfma_f32_16x16x32_bf16 v[126:129], v[164:167], v[196:199], v[126:129]
	v_mfma_f32_16x16x32_bf16 v[122:125], v[168:171], v[192:195], v[122:125]
	v_mfma_f32_16x16x32_bf16 v[122:125], v[172:175], v[196:199], v[122:125]
	v_mfma_f32_16x16x32_bf16 v[106:109], v[168:171], v[200:203], v[106:109]
	v_mfma_f32_16x16x32_bf16 v[106:109], v[172:175], v[204:207], v[106:109]
	v_mfma_f32_16x16x32_bf16 v[110:113], v[130:133], v[200:203], v[110:113]
	v_mfma_f32_16x16x32_bf16 v[110:113], v[164:167], v[204:207], v[110:113]
	v_mfma_f32_16x16x32_bf16 v[94:97], v[130:133], v[208:211], v[94:97]
	v_mfma_f32_16x16x32_bf16 v[94:97], v[164:167], v[212:215], v[94:97]
	v_mfma_f32_16x16x32_bf16 v[90:93], v[168:171], v[208:211], v[90:93]
	v_mfma_f32_16x16x32_bf16 v[90:93], v[172:175], v[212:215], v[90:93]
	v_mfma_f32_16x16x32_bf16 v[74:77], v[168:171], v[216:219], v[74:77]
	v_mfma_f32_16x16x32_bf16 v[74:77], v[172:175], v[220:223], v[74:77]
	v_mfma_f32_16x16x32_bf16 v[78:81], v[130:133], v[216:219], v[78:81]
	v_mfma_f32_16x16x32_bf16 v[78:81], v[164:167], v[220:223], v[78:81]
	s_setprio 0
	s_setprio 3
	v_mfma_f32_16x16x32_bf16 v[118:121], v[176:179], v[192:195], v[118:121]
	v_mfma_f32_16x16x32_bf16 v[118:121], v[180:183], v[196:199], v[118:121]
	v_mfma_f32_16x16x32_bf16 v[114:117], v[184:187], v[192:195], v[114:117]
	v_mfma_f32_16x16x32_bf16 v[114:117], v[188:191], v[196:199], v[114:117]
	v_mfma_f32_16x16x32_bf16 v[98:101], v[184:187], v[200:203], v[98:101]
	v_mfma_f32_16x16x32_bf16 v[98:101], v[188:191], v[204:207], v[98:101]
	v_mfma_f32_16x16x32_bf16 v[102:105], v[176:179], v[200:203], v[102:105]
	v_mfma_f32_16x16x32_bf16 v[102:105], v[180:183], v[204:207], v[102:105]
	v_mfma_f32_16x16x32_bf16 v[86:89], v[176:179], v[208:211], v[86:89]
	v_mfma_f32_16x16x32_bf16 v[86:89], v[180:183], v[212:215], v[86:89]
	v_mfma_f32_16x16x32_bf16 v[82:85], v[184:187], v[208:211], v[82:85]
	v_mfma_f32_16x16x32_bf16 v[82:85], v[188:191], v[212:215], v[82:85]
	v_mfma_f32_16x16x32_bf16 v[66:69], v[184:187], v[216:219], v[66:69]
	v_mfma_f32_16x16x32_bf16 v[66:69], v[188:191], v[220:223], v[66:69]
	v_mfma_f32_16x16x32_bf16 v[70:73], v[176:179], v[216:219], v[70:73]
	v_mfma_f32_16x16x32_bf16 v[70:73], v[180:183], v[220:223], v[70:73]
	s_setprio 0
	s_barrier
; #define PG8_STAGE(bufoff, gbase, voff) do { _Pragma("unroll") for (int _i = 0; _i < 2; ++_i) \
;         __builtin_amdgcn_global_load_lds((const unsigned*)((const char*)(gbase) + (voff)[_i]), (PG8_LAS unsigned*)(lds + (bufoff) + ldsw + _i * 8192), 16, 0, 0); } while (0)
; #define PG8_LDA(dst, b, h) do { _Pragma("unroll") for (int m = 0; m < 4; ++m) _Pragma("unroll") for (int k = 0; k < 2; ++k) dst[m][k] = *(const PG8_LAS bf16x8*)(lds + PG8_SA(b, h) + aoff + m * 2048 + k * 1024); } while (0)
; #define PG8_MMA(ai, bj, At, Bt) do { __builtin_amdgcn_s_setprio(3); _Pragma("unroll") for (int m = 0; m < 4; ++m) _Pragma("unroll") for (int n = 0; n < 2; ++n) _Pragma("unroll") for (int k = 0; k < 2; ++k) \
;         acc[ai][bj][m][n] = __builtin_amdgcn_mfma_f32_16x16x32_bf16(Bt[n][k], At[m][k], acc[ai][bj][m][n], 0, 0, 0); __builtin_amdgcn_s_setprio(0); } while (0)
; #define PG8_WAIT_V(n) asm volatile("s_waitcnt vmcnt(" #n ")" ::: "memory")
; #define PG8_WAIT_L(n) asm volatile("s_waitcnt lgkmcnt(" #n ")" ::: "memory")
; #define PG8_BAR __builtin_amdgcn_s_barrier()
; #define PG8_SCHED __builtin_amdgcn_sched_barrier(0)
; template <class Epi, class Sched, bool ALIGN_EPI = false, bool SP2 = false>
; __device__ __forceinline__ void gemm_phase(PG8_LAS unsigned char* lds, const Gemm g, const Sched& S, const Epi& E) {
;     ...
;         for (int t = 0; t < nt; t += 2) {
;             const bool last = (t == nt - 2);
;     ...
;             PG8_LDA(At, 1, 1); PG8_STAGE(PG8_SB(1, 0), b3, voffB); PG8_STAGE(PG8_SB(1, 1), b3 + hstepB, voffB); PG8_STAGE(PG8_SA(1, 0), a3, voffA);
;             PG8_WAIT_V(8); PG8_WAIT_L(0); PG8_BAR; PG8_MMA(1, 0, At, B0); PG8_MMA(1, 1, At, B1); PG8_BAR; PG8_SCHED;
	s_add_i32 s36, s84, s33
	v_lshl_add_u64 v[160:161], v[160:161], 0, s[10:11]
	s_mov_b32 m0, s36
	ds_read_b128 v[192:195], v159 offset:49152
	ds_read_b128 v[196:199], v159 offset:50176
	ds_read_b128 v[200:203], v159 offset:51200
	ds_read_b128 v[204:207], v159 offset:52224
	ds_read_b128 v[208:211], v159 offset:53248
	ds_read_b128 v[212:215], v159 offset:54272
	ds_read_b128 v[216:219], v159 offset:55296
	ds_read_b128 v[220:223], v159 offset:56320
	global_load_lds_dwordx4 v[160:161], off
	s_add_i32 m0, s36, 0x2000
	s_add_u32 s0, s0, 0x100080
	v_lshl_add_u64 v[160:161], v[224:225], 0, s[10:11]
	s_addc_u32 s1, s1, 0
	s_add_i32 s36, s85, s33
	global_load_lds_dwordx4 v[160:161], off
	v_lshl_add_u64 v[160:161], s[0:1], 0, v[136:137]
	s_mov_b32 m0, s36
	s_nop 0
	global_load_lds_dwordx4 v[160:161], off
	v_lshl_add_u64 v[160:161], s[0:1], 0, v[140:141]
	s_add_i32 m0, s36, 0x2000
	s_nop 0
	global_load_lds_dwordx4 v[160:161], off
	v_lshl_add_u64 v[160:161], v[226:227], 0, s[10:11]
	s_mov_b32 m0, s61
	s_nop 0
	global_load_lds_dwordx4 v[160:161], off
	v_lshl_add_u64 v[160:161], v[228:229], 0, s[10:11]
	s_mov_b32 m0, s62
	s_nop 0
	global_load_lds_dwordx4 v[160:161], off
	s_waitcnt vmcnt(8)
	s_waitcnt lgkmcnt(0)
	s_barrier
	s_setprio 3
	s_waitcnt lgkmcnt(0)
	v_mfma_f32_16x16x32_bf16 v[62:65], v[130:133], v[192:195], v[62:65]
	v_mfma_f32_16x16x32_bf16 v[62:65], v[164:167], v[196:199], v[62:65]
	v_mfma_f32_16x16x32_bf16 v[58:61], v[168:171], v[192:195], v[58:61]
	v_mfma_f32_16x16x32_bf16 v[58:61], v[172:175], v[196:199], v[58:61]
	v_mfma_f32_16x16x32_bf16 v[42:45], v[168:171], v[200:203], v[42:45]
	v_mfma_f32_16x16x32_bf16 v[42:45], v[172:175], v[204:207], v[42:45]
	v_mfma_f32_16x16x32_bf16 v[46:49], v[130:133], v[200:203], v[46:49]
	v_mfma_f32_16x16x32_bf16 v[46:49], v[164:167], v[204:207], v[46:49]
	v_mfma_f32_16x16x32_bf16 v[30:33], v[130:133], v[208:211], v[30:33]
	v_mfma_f32_16x16x32_bf16 v[30:33], v[164:167], v[212:215], v[30:33]
	v_mfma_f32_16x16x32_bf16 v[26:29], v[168:171], v[208:211], v[26:29]
	v_mfma_f32_16x16x32_bf16 v[26:29], v[172:175], v[212:215], v[26:29]
	v_mfma_f32_16x16x32_bf16 v[10:13], v[168:171], v[216:219], v[10:13]
	v_mfma_f32_16x16x32_bf16 v[10:13], v[172:175], v[220:223], v[10:13]
	v_mfma_f32_16x16x32_bf16 v[14:17], v[130:133], v[216:219], v[14:17]
	v_mfma_f32_16x16x32_bf16 v[14:17], v[164:167], v[220:223], v[14:17]
	s_setprio 0
	s_setprio 3
	v_mfma_f32_16x16x32_bf16 v[54:57], v[176:179], v[192:195], v[54:57]
	v_mfma_f32_16x16x32_bf16 v[54:57], v[180:183], v[196:199], v[54:57]
	v_mfma_f32_16x16x32_bf16 v[50:53], v[184:187], v[192:195], v[50:53]
	v_mfma_f32_16x16x32_bf16 v[50:53], v[188:191], v[196:199], v[50:53]
	v_mfma_f32_16x16x32_bf16 v[34:37], v[184:187], v[200:203], v[34:37]
	v_mfma_f32_16x16x32_bf16 v[34:37], v[188:191], v[204:207], v[34:37]
	v_mfma_f32_16x16x32_bf16 v[38:41], v[176:179], v[200:203], v[38:41]
	v_mfma_f32_16x16x32_bf16 v[38:41], v[180:183], v[204:207], v[38:41]
	v_mfma_f32_16x16x32_bf16 v[22:25], v[176:179], v[208:211], v[22:25]
	v_mfma_f32_16x16x32_bf16 v[22:25], v[180:183], v[212:215], v[22:25]
	v_mfma_f32_16x16x32_bf16 v[18:21], v[184:187], v[208:211], v[18:21]
	v_mfma_f32_16x16x32_bf16 v[18:21], v[188:191], v[212:215], v[18:21]
	v_mfma_f32_16x16x32_bf16 v[2:5], v[184:187], v[216:219], v[2:5]
	v_mfma_f32_16x16x32_bf16 v[2:5], v[188:191], v[220:223], v[2:5]
	v_mfma_f32_16x16x32_bf16 v[6:9], v[176:179], v[216:219], v[6:9]
	v_mfma_f32_16x16x32_bf16 v[6:9], v[180:183], v[220:223], v[6:9]
	s_setprio 0
	s_barrier
	s_add_i32 s83, s83, 2
	s_add_u32 s30, s30, 0x100
	s_addc_u32 s31, s31, 0
	s_cmp_gt_u32 s83, 61
	s_cbranch_scc1 .LBB0_730

; #define PG8_STAGE(bufoff, gbase, voff) do { _Pragma("unroll") for (int _i = 0; _i < 2; ++_i) \
;         __builtin_amdgcn_global_load_lds((const unsigned*)((const char*)(gbase) + (voff)[_i]), (PG8_LAS unsigned*)(lds + (bufoff) + ldsw + _i * 8192), 16, 0, 0); } while (0)
; #define PG8_LDA(dst, b, h) do { _Pragma("unroll") for (int m = 0; m < 4; ++m) _Pragma("unroll") for (int k = 0; k < 2; ++k) dst[m][k] = *(const PG8_LAS bf16x8*)(lds + PG8_SA(b, h) + aoff + m * 2048 + k * 1024); } while (0)
; #define PG8_LDB(dst, b, h) do { _Pragma("unroll") for (int n = 0; n < 2; ++n) _Pragma("unroll") for (int k = 0; k < 2; ++k) dst[n][k] = *(const PG8_LAS bf16x8*)(lds + PG8_SB(b, h) + boff + n * 2048 + k * 1024); } while (0)
; #define PG8_MMA(ai, bj, At, Bt) do { __builtin_amdgcn_s_setprio(3); _Pragma("unroll") for (int m = 0; m < 4; ++m) _Pragma("unroll") for (int n = 0; n < 2; ++n) _Pragma("unroll") for (int k = 0; k < 2; ++k) \
;         acc[ai][bj][m][n] = __builtin_amdgcn_mfma_f32_16x16x32_bf16(Bt[n][k], At[m][k], acc[ai][bj][m][n], 0, 0, 0); __builtin_amdgcn_s_setprio(0); } while (0)
; #define PG8_WAIT_V(n) asm volatile("s_waitcnt vmcnt(" #n ")" ::: "memory")
; #define PG8_WAIT_L(n) asm volatile("s_waitcnt lgkmcnt(" #n ")" ::: "memory")
; template <class Epi, class Sched, bool ALIGN_EPI = false, bool SP2 = false>
; __device__ __forceinline__ void gemm_phase(PG8_LAS unsigned char* lds, const Gemm g, const Sched& S, const Epi& E) {
;     ...
;         for (int t = 0; t < nt; t += 2) {
;             const bool last = (t == nt - 2);
;             const char* a1 = cA + (size_t)(t + 1) * kstep;
;             const char* a2 = last ? nA : cA + (size_t)(t + 2) * kstep; const char* b2 = last ? nB : cB + (size_t)(t + 2) * kstep;
;             const char* a3 = a2 + kstep; const char* b3 = b2 + kstep;
;             if (last && has_next) S.a_ready(nxt);
;             if constexpr (Epi::MIDK) { if (t == E.midk_step(nt)) E.midk(acc, cur, wr, wc, fr, fq); }
;             if constexpr (SP2) {
;             PG8_LDB(B0, 0, 0); PG8_LDB(B1, 0, 1); PG8_SCHED; PG8_LDA(At, 0, 0); PG8_STAGE(PG8_SA(1, 1), a1 + hstepA, voffA);
;             PG8_WAIT_V(8); PG8_WAIT_L(0); PG8_BAR; PG8_MMA(0, 0, At, B0); PG8_MMA(0, 1, At, B1); PG8_BAR; PG8_SCHED;
;             PG8_LDA(At, 0, 1); PG8_STAGE(PG8_SB(0, 0), b2, voffB); PG8_STAGE(PG8_SB(0, 1), b2 + hstepB, voffB); PG8_STAGE(PG8_SA(0, 0), a2, voffA);
.LBB0_808:
	v_add_u32_e32 v3, s65, v186
	ds_read_b128 v[134:137], v3
	ds_read_b128 v[138:141], v3 offset:1024
	ds_read_b128 v[142:145], v3 offset:2048
	ds_read_b128 v[146:149], v3 offset:3072
	v_add_u32_e32 v3, s66, v186
	s_add_u32 s36, s28, s30
	ds_read_b128 v[150:153], v3
	ds_read_b128 v[154:157], v3 offset:1024
	ds_read_b128 v[158:161], v3 offset:2048
	ds_read_b128 v[190:193], v3 offset:3072
	s_addc_u32 s37, s29, s31
	s_add_u32 s36, s36, 0x100
	s_addc_u32 s37, s37, 0
	s_add_u32 s86, s83, s30
	s_addc_u32 s87, s84, s31
	s_cmpk_eq_i32 s30, 0x1f00
	s_cselect_b32 s41, s23, s37
	s_cselect_b32 s40, s75, s36
	s_cselect_b32 s37, s77, s87
	s_cselect_b32 s36, s78, s86
	v_lshl_add_u64 v[4:5], v[180:181], 0, s[30:31]
	s_add_i32 m0, s42, 0xc000
	ds_read_b128 v[194:197], v188
	ds_read_b128 v[198:201], v188 offset:1024
	ds_read_b128 v[202:205], v188 offset:2048
	ds_read_b128 v[206:209], v188 offset:3072
	ds_read_b128 v[210:213], v188 offset:4096
	ds_read_b128 v[214:217], v188 offset:5120
	ds_read_b128 v[218:221], v188 offset:6144
	ds_read_b128 v[222:225], v188 offset:7168
	global_load_lds_dwordx4 v[4:5], off
	v_lshl_add_u64 v[4:5], v[182:183], 0, s[30:31]
	s_add_i32 m0, s42, 0xe000
	s_nop 0
	global_load_lds_dwordx4 v[4:5], off
	s_waitcnt vmcnt(8)
	s_waitcnt lgkmcnt(0)
	s_barrier
	s_setprio 3
	s_waitcnt lgkmcnt(0)
	v_mfma_f32_16x16x32_bf16 v[130:133], v[134:137], v[194:197], v[130:133]
	v_mfma_f32_16x16x32_bf16 v[130:133], v[138:141], v[198:201], v[130:133]
	v_mfma_f32_16x16x32_bf16 v[126:129], v[142:145], v[194:197], v[126:129]
	v_mfma_f32_16x16x32_bf16 v[126:129], v[146:149], v[198:201], v[126:129]
	v_mfma_f32_16x16x32_bf16 v[110:113], v[142:145], v[202:205], v[110:113]
	v_mfma_f32_16x16x32_bf16 v[110:113], v[146:149], v[206:209], v[110:113]
	v_mfma_f32_16x16x32_bf16 v[114:117], v[134:137], v[202:205], v[114:117]
	v_mfma_f32_16x16x32_bf16 v[114:117], v[138:141], v[206:209], v[114:117]
	v_mfma_f32_16x16x32_bf16 v[98:101], v[134:137], v[210:213], v[98:101]
	v_mfma_f32_16x16x32_bf16 v[98:101], v[138:141], v[214:217], v[98:101]
	v_mfma_f32_16x16x32_bf16 v[94:97], v[142:145], v[210:213], v[94:97]
	v_mfma_f32_16x16x32_bf16 v[94:97], v[146:149], v[214:217], v[94:97]
	v_mfma_f32_16x16x32_bf16 v[78:81], v[142:145], v[218:221], v[78:81]
	v_mfma_f32_16x16x32_bf16 v[78:81], v[146:149], v[222:225], v[78:81]
	v_mfma_f32_16x16x32_bf16 v[82:85], v[134:137], v[218:221], v[82:85]
	v_mfma_f32_16x16x32_bf16 v[82:85], v[138:141], v[222:225], v[82:85]
	s_setprio 0
	s_setprio 3
	v_mfma_f32_16x16x32_bf16 v[122:125], v[150:153], v[194:197], v[122:125]
	v_mfma_f32_16x16x32_bf16 v[122:125], v[154:157], v[198:201], v[122:125]
	v_mfma_f32_16x16x32_bf16 v[118:121], v[158:161], v[194:197], v[118:121]
	v_mfma_f32_16x16x32_bf16 v[118:121], v[190:193], v[198:201], v[118:121]
	v_mfma_f32_16x16x32_bf16 v[102:105], v[158:161], v[202:205], v[102:105]
	v_mfma_f32_16x16x32_bf16 v[102:105], v[190:193], v[206:209], v[102:105]
	v_mfma_f32_16x16x32_bf16 v[106:109], v[150:153], v[202:205], v[106:109]
	v_mfma_f32_16x16x32_bf16 v[106:109], v[154:157], v[206:209], v[106:109]
	v_mfma_f32_16x16x32_bf16 v[90:93], v[150:153], v[210:213], v[90:93]
	v_mfma_f32_16x16x32_bf16 v[90:93], v[154:157], v[214:217], v[90:93]
	v_mfma_f32_16x16x32_bf16 v[86:89], v[158:161], v[210:213], v[86:89]
	v_mfma_f32_16x16x32_bf16 v[86:89], v[190:193], v[214:217], v[86:89]
	v_mfma_f32_16x16x32_bf16 v[70:73], v[158:161], v[218:221], v[70:73]
	v_mfma_f32_16x16x32_bf16 v[70:73], v[190:193], v[222:225], v[70:73]
	v_mfma_f32_16x16x32_bf16 v[74:77], v[150:153], v[218:221], v[74:77]
	v_mfma_f32_16x16x32_bf16 v[74:77], v[154:157], v[222:225], v[74:77]
	s_setprio 0
	s_barrier
	s_add_i32 s86, s65, s33
	v_lshl_add_u64 v[226:227], s[36:37], 0, v[166:167]
	s_mov_b32 m0, s86
	ds_read_b128 v[194:197], v188 offset:16384
	ds_read_b128 v[198:201], v188 offset:17408
	ds_read_b128 v[202:205], v188 offset:18432
	ds_read_b128 v[206:209], v188 offset:19456
	ds_read_b128 v[210:213], v188 offset:20480
	ds_read_b128 v[214:217], v188 offset:21504
	ds_read_b128 v[218:221], v188 offset:22528
	ds_read_b128 v[222:225], v188 offset:23552
	global_load_lds_dwordx4 v[226:227], off
	s_add_i32 m0, s86, 0x2000
	s_add_u32 s86, s36, 0x100000
	v_lshl_add_u64 v[228:229], s[36:37], 0, v[170:171]
	s_addc_u32 s87, s37, 0
	s_add_i32 s88, s66, s33
	global_load_lds_dwordx4 v[228:229], off
	v_lshl_add_u64 v[4:5], s[86:87], 0, v[166:167]
	s_mov_b32 m0, s88
	v_lshl_add_u64 v[230:231], s[40:41], 0, v[164:165]
	global_load_lds_dwordx4 v[4:5], off
	v_lshl_add_u64 v[4:5], s[86:87], 0, v[170:171]
	s_add_i32 m0, s88, 0x2000
	v_lshl_add_u64 v[232:233], s[40:41], 0, v[168:169]
	global_load_lds_dwordx4 v[4:5], off
	s_mov_b32 m0, s42
	s_nop 0
	global_load_lds_dwordx4 v[230:231], off
	s_mov_b32 m0, s43
	s_nop 0
	global_load_lds_dwordx4 v[232:233], off
	s_waitcnt vmcnt(8)
	s_waitcnt lgkmcnt(0)
	s_barrier
; #define PG8_STAGE(bufoff, gbase, voff) do { _Pragma("unroll") for (int _i = 0; _i < 2; ++_i) \
;         __builtin_amdgcn_global_load_lds((const unsigned*)((const char*)(gbase) + (voff)[_i]), (PG8_LAS unsigned*)(lds + (bufoff) + ldsw + _i * 8192), 16, 0, 0); } while (0)
; #define PG8_LDA(dst, b, h) do { _Pragma("unroll") for (int m = 0; m < 4; ++m) _Pragma("unroll") for (int k = 0; k < 2; ++k) dst[m][k] = *(const PG8_LAS bf16x8*)(lds + PG8_SA(b, h) + aoff + m * 2048 + k * 1024); } while (0)
; #define PG8_LDB(dst, b, h) do { _Pragma("unroll") for (int n = 0; n < 2; ++n) _Pragma("unroll") for (int k = 0; k < 2; ++k) dst[n][k] = *(const PG8_LAS bf16x8*)(lds + PG8_SB(b, h) + boff + n * 2048 + k * 1024); } while (0)
; #define PG8_MMA(ai, bj, At, Bt) do { __builtin_amdgcn_s_setprio(3); _Pragma("unroll") for (int m = 0; m < 4; ++m) _Pragma("unroll") for (int n = 0; n < 2; ++n) _Pragma("unroll") for (int k = 0; k < 2; ++k) \
;         acc[ai][bj][m][n] = __builtin_amdgcn_mfma_f32_16x16x32_bf16(Bt[n][k], At[m][k], acc[ai][bj][m][n], 0, 0, 0); __builtin_amdgcn_s_setprio(0); } while (0)
; #define PG8_WAIT_V(n) asm volatile("s_waitcnt vmcnt(" #n ")" ::: "memory")
; #define PG8_WAIT_L(n) asm volatile("s_waitcnt lgkmcnt(" #n ")" ::: "memory")
; #define PG8_BAR __builtin_amdgcn_s_barrier()
; #define PG8_SCHED __builtin_amdgcn_sched_barrier(0)
; template <class Epi, class Sched, bool ALIGN_EPI = false, bool SP2 = false>
; __device__ __forceinline__ void gemm_phase(PG8_LAS unsigned char* lds, const Gemm g, const Sched& S, const Epi& E) {
;     ...
;             PG8_WAIT_V(8); PG8_WAIT_L(0); PG8_BAR; PG8_MMA(1, 0, At, B0); PG8_MMA(1, 1, At, B1); PG8_BAR; PG8_SCHED;
;             PG8_LDB(B0, 1, 0); PG8_LDB(B1, 1, 1); PG8_SCHED; PG8_LDA(At, 1, 0); PG8_STAGE(PG8_SA(0, 1), a2 + hstepA, voffA);
;             PG8_WAIT_V(8); PG8_WAIT_L(0); PG8_BAR; PG8_MMA(0, 0, At, B0); PG8_MMA(0, 1, At, B1); PG8_BAR; PG8_SCHED;
	s_setprio 3
	s_waitcnt lgkmcnt(0)
	v_mfma_f32_16x16x32_bf16 v[66:69], v[134:137], v[194:197], v[66:69]
	v_mfma_f32_16x16x32_bf16 v[66:69], v[138:141], v[198:201], v[66:69]
	v_mfma_f32_16x16x32_bf16 v[62:65], v[142:145], v[194:197], v[62:65]
	v_mfma_f32_16x16x32_bf16 v[62:65], v[146:149], v[198:201], v[62:65]
	v_mfma_f32_16x16x32_bf16 v[46:49], v[142:145], v[202:205], v[46:49]
	v_mfma_f32_16x16x32_bf16 v[46:49], v[146:149], v[206:209], v[46:49]
	v_mfma_f32_16x16x32_bf16 v[50:53], v[134:137], v[202:205], v[50:53]
	v_mfma_f32_16x16x32_bf16 v[50:53], v[138:141], v[206:209], v[50:53]
	v_mfma_f32_16x16x32_bf16 v[34:37], v[134:137], v[210:213], v[34:37]
	v_mfma_f32_16x16x32_bf16 v[34:37], v[138:141], v[214:217], v[34:37]
	v_mfma_f32_16x16x32_bf16 v[30:33], v[142:145], v[210:213], v[30:33]
	v_mfma_f32_16x16x32_bf16 v[30:33], v[146:149], v[214:217], v[30:33]
	v_mfma_f32_16x16x32_bf16 v[14:17], v[142:145], v[218:221], v[14:17]
	v_mfma_f32_16x16x32_bf16 v[14:17], v[146:149], v[222:225], v[14:17]
	v_mfma_f32_16x16x32_bf16 v[18:21], v[134:137], v[218:221], v[18:21]
	v_mfma_f32_16x16x32_bf16 v[18:21], v[138:141], v[222:225], v[18:21]
	s_setprio 0
	s_setprio 3
	v_mfma_f32_16x16x32_bf16 v[58:61], v[150:153], v[194:197], v[58:61]
	v_mfma_f32_16x16x32_bf16 v[58:61], v[154:157], v[198:201], v[58:61]
	v_mfma_f32_16x16x32_bf16 v[54:57], v[158:161], v[194:197], v[54:57]
	v_mfma_f32_16x16x32_bf16 v[54:57], v[190:193], v[198:201], v[54:57]
	v_mfma_f32_16x16x32_bf16 v[38:41], v[158:161], v[202:205], v[38:41]
	v_mfma_f32_16x16x32_bf16 v[38:41], v[190:193], v[206:209], v[38:41]
	v_mfma_f32_16x16x32_bf16 v[42:45], v[150:153], v[202:205], v[42:45]
	v_mfma_f32_16x16x32_bf16 v[42:45], v[154:157], v[206:209], v[42:45]
	v_mfma_f32_16x16x32_bf16 v[26:29], v[150:153], v[210:213], v[26:29]
	v_mfma_f32_16x16x32_bf16 v[26:29], v[154:157], v[214:217], v[26:29]
	v_mfma_f32_16x16x32_bf16 v[22:25], v[158:161], v[210:213], v[22:25]
	v_mfma_f32_16x16x32_bf16 v[22:25], v[190:193], v[214:217], v[22:25]
	v_mfma_f32_16x16x32_bf16 v[4:7], v[158:161], v[218:221], v[6:9]
	v_mfma_f32_16x16x32_bf16 v[4:7], v[190:193], v[222:225], v[4:7]
	v_mfma_f32_16x16x32_bf16 v[10:13], v[150:153], v[218:221], v[10:13]
	v_mfma_f32_16x16x32_bf16 v[10:13], v[154:157], v[222:225], v[10:13]
	s_setprio 0
	s_barrier
	s_add_i32 s86, 0, 0x18000
	v_add_u32_e32 v3, s86, v186
	s_add_i32 s87, 0, 0x1c000
	ds_read_b128 v[134:137], v3
	ds_read_b128 v[138:141], v3 offset:1024
	ds_read_b128 v[142:145], v3 offset:2048
	ds_read_b128 v[146:149], v3 offset:3072
	v_add_u32_e32 v3, s87, v186
	ds_read_b128 v[150:153], v3
	ds_read_b128 v[154:157], v3 offset:1024
	ds_read_b128 v[158:161], v3 offset:2048
	ds_read_b128 v[190:193], v3 offset:3072
	s_add_u32 s40, s40, 0x100000
	s_addc_u32 s41, s41, 0
	s_mov_b32 m0, s44
	v_lshl_add_u64 v[8:9], s[40:41], 0, v[164:165]
	ds_read_b128 v[194:197], v188 offset:32768
	ds_read_b128 v[198:201], v188 offset:33792
	ds_read_b128 v[202:205], v188 offset:34816
	ds_read_b128 v[206:209], v188 offset:35840
	ds_read_b128 v[210:213], v188 offset:36864
	ds_read_b128 v[214:217], v188 offset:37888
	ds_read_b128 v[218:221], v188 offset:38912
	ds_read_b128 v[222:225], v188 offset:39936
	global_load_lds_dwordx4 v[8:9], off
	v_lshl_add_u64 v[8:9], s[40:41], 0, v[168:169]
	s_mov_b32 m0, s45
	s_nop 0
	global_load_lds_dwordx4 v[8:9], off
	s_waitcnt vmcnt(8)
	s_waitcnt lgkmcnt(0)
	s_barrier
	s_setprio 3
	s_waitcnt lgkmcnt(0)
	v_mfma_f32_16x16x32_bf16 v[130:133], v[134:137], v[194:197], v[130:133]
	v_mfma_f32_16x16x32_bf16 v[130:133], v[138:141], v[198:201], v[130:133]
	v_mfma_f32_16x16x32_bf16 v[126:129], v[142:145], v[194:197], v[126:129]
	v_mfma_f32_16x16x32_bf16 v[126:129], v[146:149], v[198:201], v[126:129]
	v_mfma_f32_16x16x32_bf16 v[110:113], v[142:145], v[202:205], v[110:113]
	v_mfma_f32_16x16x32_bf16 v[110:113], v[146:149], v[206:209], v[110:113]
	v_mfma_f32_16x16x32_bf16 v[114:117], v[134:137], v[202:205], v[114:117]
	v_mfma_f32_16x16x32_bf16 v[114:117], v[138:141], v[206:209], v[114:117]
	v_mfma_f32_16x16x32_bf16 v[98:101], v[134:137], v[210:213], v[98:101]
	v_mfma_f32_16x16x32_bf16 v[98:101], v[138:141], v[214:217], v[98:101]
	v_mfma_f32_16x16x32_bf16 v[94:97], v[142:145], v[210:213], v[94:97]
	v_mfma_f32_16x16x32_bf16 v[94:97], v[146:149], v[214:217], v[94:97]
	v_mfma_f32_16x16x32_bf16 v[78:81], v[142:145], v[218:221], v[78:81]
	v_mfma_f32_16x16x32_bf16 v[78:81], v[146:149], v[222:225], v[78:81]
	v_mfma_f32_16x16x32_bf16 v[82:85], v[134:137], v[218:221], v[82:85]
	v_mfma_f32_16x16x32_bf16 v[82:85], v[138:141], v[222:225], v[82:85]
	s_setprio 0
	s_setprio 3
	v_mfma_f32_16x16x32_bf16 v[122:125], v[150:153], v[194:197], v[122:125]
	v_mfma_f32_16x16x32_bf16 v[122:125], v[154:157], v[198:201], v[122:125]
	v_mfma_f32_16x16x32_bf16 v[118:121], v[158:161], v[194:197], v[118:121]
	v_mfma_f32_16x16x32_bf16 v[118:121], v[190:193], v[198:201], v[118:121]
	v_mfma_f32_16x16x32_bf16 v[102:105], v[158:161], v[202:205], v[102:105]
	v_mfma_f32_16x16x32_bf16 v[102:105], v[190:193], v[206:209], v[102:105]
	v_mfma_f32_16x16x32_bf16 v[106:109], v[150:153], v[202:205], v[106:109]
	v_mfma_f32_16x16x32_bf16 v[106:109], v[154:157], v[206:209], v[106:109]
	v_mfma_f32_16x16x32_bf16 v[90:93], v[150:153], v[210:213], v[90:93]
	v_mfma_f32_16x16x32_bf16 v[90:93], v[154:157], v[214:217], v[90:93]
	v_mfma_f32_16x16x32_bf16 v[86:89], v[158:161], v[210:213], v[86:89]
	v_mfma_f32_16x16x32_bf16 v[86:89], v[190:193], v[214:217], v[86:89]
	v_mfma_f32_16x16x32_bf16 v[70:73], v[158:161], v[218:221], v[70:73]
	v_mfma_f32_16x16x32_bf16 v[70:73], v[190:193], v[222:225], v[70:73]
	v_mfma_f32_16x16x32_bf16 v[74:77], v[150:153], v[218:221], v[74:77]
	v_mfma_f32_16x16x32_bf16 v[74:77], v[154:157], v[222:225], v[74:77]
	s_setprio 0
	s_barrier
; #define PG8_STAGE(bufoff, gbase, voff) do { _Pragma("unroll") for (int _i = 0; _i < 2; ++_i) \
;         __builtin_amdgcn_global_load_lds((const unsigned*)((const char*)(gbase) + (voff)[_i]), (PG8_LAS unsigned*)(lds + (bufoff) + ldsw + _i * 8192), 16, 0, 0); } while (0)
; #define PG8_LDA(dst, b, h) do { _Pragma("unroll") for (int m = 0; m < 4; ++m) _Pragma("unroll") for (int k = 0; k < 2; ++k) dst[m][k] = *(const PG8_LAS bf16x8*)(lds + PG8_SA(b, h) + aoff + m * 2048 + k * 1024); } while (0)
; #define PG8_MMA(ai, bj, At, Bt) do { __builtin_amdgcn_s_setprio(3); _Pragma("unroll") for (int m = 0; m < 4; ++m) _Pragma("unroll") for (int n = 0; n < 2; ++n) _Pragma("unroll") for (int k = 0; k < 2; ++k) \
;         acc[ai][bj][m][n] = __builtin_amdgcn_mfma_f32_16x16x32_bf16(Bt[n][k], At[m][k], acc[ai][bj][m][n], 0, 0, 0); __builtin_amdgcn_s_setprio(0); } while (0)
; #define PG8_WAIT_V(n) asm volatile("s_waitcnt vmcnt(" #n ")" ::: "memory")
; #define PG8_WAIT_L(n) asm volatile("s_waitcnt lgkmcnt(" #n ")" ::: "memory")
; #define PG8_BAR __builtin_amdgcn_s_barrier()
; #define PG8_SCHED __builtin_amdgcn_sched_barrier(0)
; template <class Epi, class Sched, bool ALIGN_EPI = false, bool SP2 = false>
; __device__ __forceinline__ void gemm_phase(PG8_LAS unsigned char* lds, const Gemm g, const Sched& S, const Epi& E) {
;     ...
;         for (int t = 0; t < nt; t += 2) {
;             const bool last = (t == nt - 2);
;     ...
;             PG8_LDA(At, 1, 1); PG8_STAGE(PG8_SB(1, 0), b3, voffB); PG8_STAGE(PG8_SB(1, 1), b3 + hstepB, voffB); PG8_STAGE(PG8_SA(1, 0), a3, voffA);
;             PG8_WAIT_V(8); PG8_WAIT_L(0); PG8_BAR; PG8_MMA(1, 0, At, B0); PG8_MMA(1, 1, At, B1); PG8_BAR; PG8_SCHED;
	s_add_i32 s40, s86, s33
	v_lshl_add_u64 v[8:9], v[226:227], 0, s[10:11]
	s_mov_b32 m0, s40
	ds_read_b128 v[194:197], v188 offset:49152
	ds_read_b128 v[198:201], v188 offset:50176
	ds_read_b128 v[202:205], v188 offset:51200
	ds_read_b128 v[206:209], v188 offset:52224
	ds_read_b128 v[210:213], v188 offset:53248
	ds_read_b128 v[214:217], v188 offset:54272
	ds_read_b128 v[218:221], v188 offset:55296
	ds_read_b128 v[222:225], v188 offset:56320
	global_load_lds_dwordx4 v[8:9], off
	s_add_i32 m0, s40, 0x2000
	s_add_u32 s36, s36, 0x100080
	v_lshl_add_u64 v[8:9], v[228:229], 0, s[10:11]
	s_addc_u32 s37, s37, 0
	s_add_i32 s40, s87, s33
	global_load_lds_dwordx4 v[8:9], off
	v_lshl_add_u64 v[8:9], s[36:37], 0, v[166:167]
	s_mov_b32 m0, s40
	s_nop 0
	global_load_lds_dwordx4 v[8:9], off
	v_lshl_add_u64 v[8:9], s[36:37], 0, v[170:171]
	s_add_i32 m0, s40, 0x2000
	s_nop 0
	global_load_lds_dwordx4 v[8:9], off
	v_lshl_add_u64 v[8:9], v[230:231], 0, s[10:11]
	s_mov_b32 m0, s60
	s_nop 0
	global_load_lds_dwordx4 v[8:9], off
	v_lshl_add_u64 v[8:9], v[232:233], 0, s[10:11]
	s_mov_b32 m0, s61
	s_nop 0
	global_load_lds_dwordx4 v[8:9], off
	s_waitcnt vmcnt(8)
	s_waitcnt lgkmcnt(0)
	s_barrier
	s_setprio 3
	s_waitcnt lgkmcnt(0)
	v_mfma_f32_16x16x32_bf16 v[66:69], v[134:137], v[194:197], v[66:69]
	v_mfma_f32_16x16x32_bf16 v[66:69], v[138:141], v[198:201], v[66:69]
	v_mfma_f32_16x16x32_bf16 v[62:65], v[142:145], v[194:197], v[62:65]
	v_mfma_f32_16x16x32_bf16 v[62:65], v[146:149], v[198:201], v[62:65]
	v_mfma_f32_16x16x32_bf16 v[46:49], v[142:145], v[202:205], v[46:49]
	v_mfma_f32_16x16x32_bf16 v[46:49], v[146:149], v[206:209], v[46:49]
	v_mfma_f32_16x16x32_bf16 v[50:53], v[134:137], v[202:205], v[50:53]
	v_mfma_f32_16x16x32_bf16 v[50:53], v[138:141], v[206:209], v[50:53]
	v_mfma_f32_16x16x32_bf16 v[34:37], v[134:137], v[210:213], v[34:37]
	v_mfma_f32_16x16x32_bf16 v[34:37], v[138:141], v[214:217], v[34:37]
	v_mfma_f32_16x16x32_bf16 v[30:33], v[142:145], v[210:213], v[30:33]
	v_mfma_f32_16x16x32_bf16 v[30:33], v[146:149], v[214:217], v[30:33]
	v_mfma_f32_16x16x32_bf16 v[14:17], v[142:145], v[218:221], v[14:17]
	v_mfma_f32_16x16x32_bf16 v[14:17], v[146:149], v[222:225], v[14:17]
	v_mfma_f32_16x16x32_bf16 v[18:21], v[134:137], v[218:221], v[18:21]
	v_mfma_f32_16x16x32_bf16 v[18:21], v[138:141], v[222:225], v[18:21]
	s_setprio 0
	s_setprio 3
	v_mfma_f32_16x16x32_bf16 v[58:61], v[150:153], v[194:197], v[58:61]
	v_mfma_f32_16x16x32_bf16 v[54:57], v[158:161], v[194:197], v[54:57]
	v_mfma_f32_16x16x32_bf16 v[42:45], v[150:153], v[202:205], v[42:45]
	v_mfma_f32_16x16x32_bf16 v[38:41], v[158:161], v[202:205], v[38:41]
	v_mfma_f32_16x16x32_bf16 v[26:29], v[150:153], v[210:213], v[26:29]
	v_mfma_f32_16x16x32_bf16 v[22:25], v[158:161], v[210:213], v[22:25]
	v_mfma_f32_16x16x32_bf16 v[8:11], v[150:153], v[218:221], v[10:13]
	v_mfma_f32_16x16x32_bf16 v[4:7], v[158:161], v[218:221], v[4:7]
	v_mfma_f32_16x16x32_bf16 v[58:61], v[154:157], v[198:201], v[58:61]
	v_mfma_f32_16x16x32_bf16 v[54:57], v[190:193], v[198:201], v[54:57]
	v_mfma_f32_16x16x32_bf16 v[42:45], v[154:157], v[206:209], v[42:45]
	v_mfma_f32_16x16x32_bf16 v[38:41], v[190:193], v[206:209], v[38:41]
	v_mfma_f32_16x16x32_bf16 v[26:29], v[154:157], v[214:217], v[26:29]
	v_mfma_f32_16x16x32_bf16 v[22:25], v[190:193], v[214:217], v[22:25]
	v_mfma_f32_16x16x32_bf16 v[10:13], v[154:157], v[222:225], v[8:11]
	v_mfma_f32_16x16x32_bf16 v[6:9], v[190:193], v[222:225], v[4:7]
	s_setprio 0
	s_barrier
	s_add_i32 s85, s85, 2
	s_add_u32 s30, s30, 0x100
	s_addc_u32 s31, s31, 0
	s_cmp_gt_u32 s85, 61
	s_cbranch_scc1 .LBB0_811

; #define PG8_STAGE(bufoff, gbase, voff) do { _Pragma("unroll") for (int _i = 0; _i < 2; ++_i) \
;         __builtin_amdgcn_global_load_lds((const unsigned*)((const char*)(gbase) + (voff)[_i]), (PG8_LAS unsigned*)(lds + (bufoff) + ldsw + _i * 8192), 16, 0, 0); } while (0)
; #define PG8_LDA(dst, b, h) do { _Pragma("unroll") for (int m = 0; m < 4; ++m) _Pragma("unroll") for (int k = 0; k < 2; ++k) dst[m][k] = *(const PG8_LAS bf16x8*)(lds + PG8_SA(b, h) + aoff + m * 2048 + k * 1024); } while (0)
; #define PG8_LDB(dst, b, h) do { _Pragma("unroll") for (int n = 0; n < 2; ++n) _Pragma("unroll") for (int k = 0; k < 2; ++k) dst[n][k] = *(const PG8_LAS bf16x8*)(lds + PG8_SB(b, h) + boff + n * 2048 + k * 1024); } while (0)
; #define PG8_MMA(ai, bj, At, Bt) do { __builtin_amdgcn_s_setprio(3); _Pragma("unroll") for (int m = 0; m < 4; ++m) _Pragma("unroll") for (int n = 0; n < 2; ++n) _Pragma("unroll") for (int k = 0; k < 2; ++k) \
;         acc[ai][bj][m][n] = __builtin_amdgcn_mfma_f32_16x16x32_bf16(Bt[n][k], At[m][k], acc[ai][bj][m][n], 0, 0, 0); __builtin_amdgcn_s_setprio(0); } while (0)
; #define PG8_WAIT_V(n) asm volatile("s_waitcnt vmcnt(" #n ")" ::: "memory")
; #define PG8_WAIT_L(n) asm volatile("s_waitcnt lgkmcnt(" #n ")" ::: "memory")
; template <class Epi, class Sched, bool ALIGN_EPI = false, bool SP2 = false>
; __device__ __forceinline__ void gemm_phase(PG8_LAS unsigned char* lds, const Gemm g, const Sched& S, const Epi& E) {
;     ...
;         for (int t = 0; t < nt; t += 2) {
;             const bool last = (t == nt - 2);
;             const char* a1 = cA + (size_t)(t + 1) * kstep;
;             const char* a2 = last ? nA : cA + (size_t)(t + 2) * kstep; const char* b2 = last ? nB : cB + (size_t)(t + 2) * kstep;
;             const char* a3 = a2 + kstep; const char* b3 = b2 + kstep;
;             if (last && has_next) S.a_ready(nxt);
;             if constexpr (Epi::MIDK) { if (t == E.midk_step(nt)) E.midk(acc, cur, wr, wc, fr, fq); }
;             if constexpr (SP2) {
;             PG8_LDB(B0, 0, 0); PG8_LDB(B1, 0, 1); PG8_SCHED; PG8_LDA(At, 0, 0); PG8_STAGE(PG8_SA(1, 1), a1 + hstepA, voffA);
;             PG8_WAIT_V(8); PG8_WAIT_L(0); PG8_BAR; PG8_MMA(0, 0, At, B0); PG8_MMA(0, 1, At, B1); PG8_BAR; PG8_SCHED;
;             PG8_LDA(At, 0, 1); PG8_STAGE(PG8_SB(0, 0), b2, voffB); PG8_STAGE(PG8_SB(0, 1), b2 + hstepB, voffB); PG8_STAGE(PG8_SA(0, 0), a2, voffA);
.LBB0_908:
	ds_read_b128 v[158:161], v155
	ds_read_b128 v[164:167], v155 offset:1024
	ds_read_b128 v[168:171], v155 offset:2048
	ds_read_b128 v[172:175], v155 offset:3072
	ds_read_b128 v[176:179], v156
	ds_read_b128 v[180:183], v156 offset:1024
	ds_read_b128 v[184:187], v156 offset:2048
	ds_read_b128 v[188:191], v156 offset:3072
	s_add_u32 s26, s24, 0xfff00080
	s_addc_u32 s27, s25, -1
	s_cmp_eq_u32 s55, 60
	s_cselect_b32 s29, s17, s27
	s_cselect_b32 s28, s47, s26
	s_cselect_b32 s27, s15, s54
	s_cselect_b32 s26, s52, s53
	v_lshl_add_u64 v[146:147], s[24:25], 0, v[138:139]
	s_add_i32 m0, s23, 0xc000
	ds_read_b128 v[192:195], v157
	ds_read_b128 v[196:199], v157 offset:1024
	ds_read_b128 v[200:203], v157 offset:2048
	ds_read_b128 v[204:207], v157 offset:3072
	ds_read_b128 v[208:211], v157 offset:4096
	ds_read_b128 v[212:215], v157 offset:5120
	ds_read_b128 v[216:219], v157 offset:6144
	ds_read_b128 v[220:223], v157 offset:7168
	global_load_lds_dwordx4 v[146:147], off
	v_lshl_add_u64 v[146:147], s[24:25], 0, v[140:141]
	s_add_i32 m0, s23, 0xe000
	s_nop 0
	global_load_lds_dwordx4 v[146:147], off
	s_waitcnt vmcnt(8)
	s_waitcnt lgkmcnt(0)
	s_barrier
	s_setprio 3
	s_waitcnt lgkmcnt(0)
	v_mfma_f32_16x16x32_bf16 v[126:129], v[158:161], v[192:195], v[126:129]
	v_mfma_f32_16x16x32_bf16 v[126:129], v[164:167], v[196:199], v[126:129]
	v_mfma_f32_16x16x32_bf16 v[122:125], v[168:171], v[192:195], v[122:125]
	v_mfma_f32_16x16x32_bf16 v[122:125], v[172:175], v[196:199], v[122:125]
	v_mfma_f32_16x16x32_bf16 v[106:109], v[168:171], v[200:203], v[106:109]
	v_mfma_f32_16x16x32_bf16 v[106:109], v[172:175], v[204:207], v[106:109]
	v_mfma_f32_16x16x32_bf16 v[114:117], v[158:161], v[200:203], v[114:117]
	v_mfma_f32_16x16x32_bf16 v[114:117], v[164:167], v[204:207], v[114:117]
	v_mfma_f32_16x16x32_bf16 v[98:101], v[158:161], v[208:211], v[98:101]
	v_mfma_f32_16x16x32_bf16 v[98:101], v[164:167], v[212:215], v[98:101]
	v_mfma_f32_16x16x32_bf16 v[90:93], v[168:171], v[208:211], v[90:93]
	v_mfma_f32_16x16x32_bf16 v[90:93], v[172:175], v[212:215], v[90:93]
	v_mfma_f32_16x16x32_bf16 v[74:77], v[168:171], v[216:219], v[74:77]
	v_mfma_f32_16x16x32_bf16 v[74:77], v[172:175], v[220:223], v[74:77]
	v_mfma_f32_16x16x32_bf16 v[82:85], v[158:161], v[216:219], v[82:85]
	v_mfma_f32_16x16x32_bf16 v[82:85], v[164:167], v[220:223], v[82:85]
	s_setprio 0
	s_setprio 3
	v_mfma_f32_16x16x32_bf16 v[118:121], v[176:179], v[192:195], v[118:121]
	v_mfma_f32_16x16x32_bf16 v[118:121], v[180:183], v[196:199], v[118:121]
	v_mfma_f32_16x16x32_bf16 v[110:113], v[184:187], v[192:195], v[110:113]
	v_mfma_f32_16x16x32_bf16 v[110:113], v[188:191], v[196:199], v[110:113]
	v_mfma_f32_16x16x32_bf16 v[94:97], v[184:187], v[200:203], v[94:97]
	v_mfma_f32_16x16x32_bf16 v[94:97], v[188:191], v[204:207], v[94:97]
	v_mfma_f32_16x16x32_bf16 v[102:105], v[176:179], v[200:203], v[102:105]
	v_mfma_f32_16x16x32_bf16 v[102:105], v[180:183], v[204:207], v[102:105]
	v_mfma_f32_16x16x32_bf16 v[86:89], v[176:179], v[208:211], v[86:89]
	v_mfma_f32_16x16x32_bf16 v[86:89], v[180:183], v[212:215], v[86:89]
	v_mfma_f32_16x16x32_bf16 v[78:81], v[184:187], v[208:211], v[78:81]
	v_mfma_f32_16x16x32_bf16 v[78:81], v[188:191], v[212:215], v[78:81]
	v_mfma_f32_16x16x32_bf16 v[66:69], v[184:187], v[216:219], v[66:69]
	v_mfma_f32_16x16x32_bf16 v[66:69], v[188:191], v[220:223], v[66:69]
	v_mfma_f32_16x16x32_bf16 v[70:73], v[176:179], v[216:219], v[70:73]
	v_mfma_f32_16x16x32_bf16 v[70:73], v[180:183], v[220:223], v[70:73]
	s_setprio 0
	s_barrier
	s_add_i32 s56, s42, s30
	v_lshl_add_u64 v[146:147], s[26:27], 0, v[134:135]
	s_mov_b32 m0, s56
	ds_read_b128 v[192:195], v157 offset:16384
	ds_read_b128 v[196:199], v157 offset:17408
	ds_read_b128 v[200:203], v157 offset:18432
	ds_read_b128 v[204:207], v157 offset:19456
	ds_read_b128 v[208:211], v157 offset:20480
	ds_read_b128 v[212:215], v157 offset:21504
	ds_read_b128 v[216:219], v157 offset:22528
	ds_read_b128 v[220:223], v157 offset:23552
	global_load_lds_dwordx4 v[146:147], off
	s_add_i32 m0, s56, 0x2000
	s_add_u32 s56, s26, 0x100000
	v_lshl_add_u64 v[224:225], s[26:27], 0, v[130:131]
	s_addc_u32 s57, s27, 0
	s_add_i32 s58, s43, s30
	global_load_lds_dwordx4 v[224:225], off
	v_lshl_add_u64 v[226:227], s[56:57], 0, v[134:135]
	s_mov_b32 m0, s58
	v_lshl_add_u64 v[228:229], s[28:29], 0, v[132:133]
	global_load_lds_dwordx4 v[226:227], off
	v_lshl_add_u64 v[226:227], s[56:57], 0, v[130:131]
	s_add_i32 m0, s58, 0x2000
	s_nop 0
	global_load_lds_dwordx4 v[226:227], off
	v_lshl_add_u64 v[226:227], s[28:29], 0, v[136:137]
	s_mov_b32 m0, s23
	s_nop 0
	global_load_lds_dwordx4 v[226:227], off
	s_mov_b32 m0, s33
	s_nop 0
	global_load_lds_dwordx4 v[228:229], off
	s_waitcnt vmcnt(8)
	s_waitcnt lgkmcnt(0)
	s_barrier
; #define PG8_STAGE(bufoff, gbase, voff) do { _Pragma("unroll") for (int _i = 0; _i < 2; ++_i) \
;         __builtin_amdgcn_global_load_lds((const unsigned*)((const char*)(gbase) + (voff)[_i]), (PG8_LAS unsigned*)(lds + (bufoff) + ldsw + _i * 8192), 16, 0, 0); } while (0)
; #define PG8_LDA(dst, b, h) do { _Pragma("unroll") for (int m = 0; m < 4; ++m) _Pragma("unroll") for (int k = 0; k < 2; ++k) dst[m][k] = *(const PG8_LAS bf16x8*)(lds + PG8_SA(b, h) + aoff + m * 2048 + k * 1024); } while (0)
; #define PG8_LDB(dst, b, h) do { _Pragma("unroll") for (int n = 0; n < 2; ++n) _Pragma("unroll") for (int k = 0; k < 2; ++k) dst[n][k] = *(const PG8_LAS bf16x8*)(lds + PG8_SB(b, h) + boff + n * 2048 + k * 1024); } while (0)
; #define PG8_MMA(ai, bj, At, Bt) do { __builtin_amdgcn_s_setprio(3); _Pragma("unroll") for (int m = 0; m < 4; ++m) _Pragma("unroll") for (int n = 0; n < 2; ++n) _Pragma("unroll") for (int k = 0; k < 2; ++k) \
;         acc[ai][bj][m][n] = __builtin_amdgcn_mfma_f32_16x16x32_bf16(Bt[n][k], At[m][k], acc[ai][bj][m][n], 0, 0, 0); __builtin_amdgcn_s_setprio(0); } while (0)
; #define PG8_WAIT_V(n) asm volatile("s_waitcnt vmcnt(" #n ")" ::: "memory")
; #define PG8_WAIT_L(n) asm volatile("s_waitcnt lgkmcnt(" #n ")" ::: "memory")
; #define PG8_BAR __builtin_amdgcn_s_barrier()
; #define PG8_SCHED __builtin_amdgcn_sched_barrier(0)
; template <class Epi, class Sched, bool ALIGN_EPI = false, bool SP2 = false>
; __device__ __forceinline__ void gemm_phase(PG8_LAS unsigned char* lds, const Gemm g, const Sched& S, const Epi& E) {
;     ...
;             PG8_WAIT_V(8); PG8_WAIT_L(0); PG8_BAR; PG8_MMA(1, 0, At, B0); PG8_MMA(1, 1, At, B1); PG8_BAR; PG8_SCHED;
;             PG8_LDB(B0, 1, 0); PG8_LDB(B1, 1, 1); PG8_SCHED; PG8_LDA(At, 1, 0); PG8_STAGE(PG8_SA(0, 1), a2 + hstepA, voffA);
;             PG8_WAIT_V(8); PG8_WAIT_L(0); PG8_BAR; PG8_MMA(0, 0, At, B0); PG8_MMA(0, 1, At, B1); PG8_BAR; PG8_SCHED;
	s_setprio 3
	s_waitcnt lgkmcnt(0)
	v_mfma_f32_16x16x32_bf16 v[62:65], v[158:161], v[192:195], v[62:65]
	v_mfma_f32_16x16x32_bf16 v[62:65], v[164:167], v[196:199], v[62:65]
	v_mfma_f32_16x16x32_bf16 v[58:61], v[168:171], v[192:195], v[58:61]
	v_mfma_f32_16x16x32_bf16 v[58:61], v[172:175], v[196:199], v[58:61]
	v_mfma_f32_16x16x32_bf16 v[42:45], v[168:171], v[200:203], v[42:45]
	v_mfma_f32_16x16x32_bf16 v[42:45], v[172:175], v[204:207], v[42:45]
	v_mfma_f32_16x16x32_bf16 v[50:53], v[158:161], v[200:203], v[50:53]
	v_mfma_f32_16x16x32_bf16 v[50:53], v[164:167], v[204:207], v[50:53]
	v_mfma_f32_16x16x32_bf16 v[34:37], v[158:161], v[208:211], v[34:37]
	v_mfma_f32_16x16x32_bf16 v[34:37], v[164:167], v[212:215], v[34:37]
	v_mfma_f32_16x16x32_bf16 v[26:29], v[168:171], v[208:211], v[26:29]
	v_mfma_f32_16x16x32_bf16 v[26:29], v[172:175], v[212:215], v[26:29]
	v_mfma_f32_16x16x32_bf16 v[10:13], v[168:171], v[216:219], v[10:13]
	v_mfma_f32_16x16x32_bf16 v[10:13], v[172:175], v[220:223], v[10:13]
	v_mfma_f32_16x16x32_bf16 v[14:17], v[158:161], v[216:219], v[14:17]
	v_mfma_f32_16x16x32_bf16 v[14:17], v[164:167], v[220:223], v[14:17]
	s_setprio 0
	s_setprio 3
	v_mfma_f32_16x16x32_bf16 v[54:57], v[176:179], v[192:195], v[54:57]
	v_mfma_f32_16x16x32_bf16 v[54:57], v[180:183], v[196:199], v[54:57]
	v_mfma_f32_16x16x32_bf16 v[46:49], v[184:187], v[192:195], v[46:49]
	v_mfma_f32_16x16x32_bf16 v[46:49], v[188:191], v[196:199], v[46:49]
	v_mfma_f32_16x16x32_bf16 v[30:33], v[184:187], v[200:203], v[30:33]
	v_mfma_f32_16x16x32_bf16 v[30:33], v[188:191], v[204:207], v[30:33]
	v_mfma_f32_16x16x32_bf16 v[38:41], v[176:179], v[200:203], v[38:41]
	v_mfma_f32_16x16x32_bf16 v[38:41], v[180:183], v[204:207], v[38:41]
	v_mfma_f32_16x16x32_bf16 v[22:25], v[176:179], v[208:211], v[22:25]
	v_mfma_f32_16x16x32_bf16 v[22:25], v[180:183], v[212:215], v[22:25]
	v_mfma_f32_16x16x32_bf16 v[18:21], v[184:187], v[208:211], v[18:21]
	v_mfma_f32_16x16x32_bf16 v[18:21], v[188:191], v[212:215], v[18:21]
	v_mfma_f32_16x16x32_bf16 v[2:5], v[184:187], v[216:219], v[2:5]
	v_mfma_f32_16x16x32_bf16 v[2:5], v[188:191], v[220:223], v[2:5]
	v_mfma_f32_16x16x32_bf16 v[6:9], v[176:179], v[216:219], v[6:9]
	v_mfma_f32_16x16x32_bf16 v[6:9], v[180:183], v[220:223], v[6:9]
	s_setprio 0
	s_barrier
	s_add_i32 s56, 0, 0x18000
	v_add_u32_e32 v148, s56, v151
	s_add_i32 s57, 0, 0x1c000
	ds_read_b128 v[158:161], v148
	ds_read_b128 v[164:167], v148 offset:1024
	ds_read_b128 v[168:171], v148 offset:2048
	ds_read_b128 v[172:175], v148 offset:3072
	v_add_u32_e32 v148, s57, v151
	ds_read_b128 v[176:179], v148
	ds_read_b128 v[180:183], v148 offset:1024
	ds_read_b128 v[184:187], v148 offset:2048
	ds_read_b128 v[188:191], v148 offset:3072
	s_add_u32 s28, s28, 0x100000
	s_addc_u32 s29, s29, 0
	s_mov_b32 m0, s36
	v_lshl_add_u64 v[230:231], s[28:29], 0, v[136:137]
	ds_read_b128 v[192:195], v157 offset:32768
	ds_read_b128 v[196:199], v157 offset:33792
	ds_read_b128 v[200:203], v157 offset:34816
	ds_read_b128 v[204:207], v157 offset:35840
	ds_read_b128 v[208:211], v157 offset:36864
	ds_read_b128 v[212:215], v157 offset:37888
	ds_read_b128 v[216:219], v157 offset:38912
	ds_read_b128 v[220:223], v157 offset:39936
	global_load_lds_dwordx4 v[230:231], off
	v_lshl_add_u64 v[230:231], s[28:29], 0, v[132:133]
	s_mov_b32 m0, s37
	s_nop 0
	global_load_lds_dwordx4 v[230:231], off
	s_waitcnt vmcnt(8)
	s_waitcnt lgkmcnt(0)
	s_barrier
	s_setprio 3
	s_waitcnt lgkmcnt(0)
	v_mfma_f32_16x16x32_bf16 v[126:129], v[158:161], v[192:195], v[126:129]
	v_mfma_f32_16x16x32_bf16 v[126:129], v[164:167], v[196:199], v[126:129]
	v_mfma_f32_16x16x32_bf16 v[122:125], v[168:171], v[192:195], v[122:125]
	v_mfma_f32_16x16x32_bf16 v[122:125], v[172:175], v[196:199], v[122:125]
	v_mfma_f32_16x16x32_bf16 v[106:109], v[168:171], v[200:203], v[106:109]
	v_mfma_f32_16x16x32_bf16 v[106:109], v[172:175], v[204:207], v[106:109]
	v_mfma_f32_16x16x32_bf16 v[114:117], v[158:161], v[200:203], v[114:117]
	v_mfma_f32_16x16x32_bf16 v[114:117], v[164:167], v[204:207], v[114:117]
	v_mfma_f32_16x16x32_bf16 v[98:101], v[158:161], v[208:211], v[98:101]
	v_mfma_f32_16x16x32_bf16 v[98:101], v[164:167], v[212:215], v[98:101]
	v_mfma_f32_16x16x32_bf16 v[90:93], v[168:171], v[208:211], v[90:93]
	v_mfma_f32_16x16x32_bf16 v[90:93], v[172:175], v[212:215], v[90:93]
	v_mfma_f32_16x16x32_bf16 v[74:77], v[168:171], v[216:219], v[74:77]
	v_mfma_f32_16x16x32_bf16 v[74:77], v[172:175], v[220:223], v[74:77]
	v_mfma_f32_16x16x32_bf16 v[82:85], v[158:161], v[216:219], v[82:85]
	v_mfma_f32_16x16x32_bf16 v[82:85], v[164:167], v[220:223], v[82:85]
	s_setprio 0
	s_setprio 3
	v_mfma_f32_16x16x32_bf16 v[118:121], v[176:179], v[192:195], v[118:121]
	v_mfma_f32_16x16x32_bf16 v[118:121], v[180:183], v[196:199], v[118:121]
	v_mfma_f32_16x16x32_bf16 v[110:113], v[184:187], v[192:195], v[110:113]
	v_mfma_f32_16x16x32_bf16 v[110:113], v[188:191], v[196:199], v[110:113]
	v_mfma_f32_16x16x32_bf16 v[94:97], v[184:187], v[200:203], v[94:97]
	v_mfma_f32_16x16x32_bf16 v[94:97], v[188:191], v[204:207], v[94:97]
	v_mfma_f32_16x16x32_bf16 v[102:105], v[176:179], v[200:203], v[102:105]
	v_mfma_f32_16x16x32_bf16 v[102:105], v[180:183], v[204:207], v[102:105]
	v_mfma_f32_16x16x32_bf16 v[86:89], v[176:179], v[208:211], v[86:89]
	v_mfma_f32_16x16x32_bf16 v[86:89], v[180:183], v[212:215], v[86:89]
	v_mfma_f32_16x16x32_bf16 v[78:81], v[184:187], v[208:211], v[78:81]
	v_mfma_f32_16x16x32_bf16 v[78:81], v[188:191], v[212:215], v[78:81]
	v_mfma_f32_16x16x32_bf16 v[66:69], v[184:187], v[216:219], v[66:69]
	v_mfma_f32_16x16x32_bf16 v[66:69], v[188:191], v[220:223], v[66:69]
	v_mfma_f32_16x16x32_bf16 v[70:73], v[176:179], v[216:219], v[70:73]
	v_mfma_f32_16x16x32_bf16 v[70:73], v[180:183], v[220:223], v[70:73]
	s_setprio 0
	s_barrier
; #define PG8_STAGE(bufoff, gbase, voff) do { _Pragma("unroll") for (int _i = 0; _i < 2; ++_i) \
;         __builtin_amdgcn_global_load_lds((const unsigned*)((const char*)(gbase) + (voff)[_i]), (PG8_LAS unsigned*)(lds + (bufoff) + ldsw + _i * 8192), 16, 0, 0); } while (0)
; #define PG8_LDA(dst, b, h) do { _Pragma("unroll") for (int m = 0; m < 4; ++m) _Pragma("unroll") for (int k = 0; k < 2; ++k) dst[m][k] = *(const PG8_LAS bf16x8*)(lds + PG8_SA(b, h) + aoff + m * 2048 + k * 1024); } while (0)
; #define PG8_MMA(ai, bj, At, Bt) do { __builtin_amdgcn_s_setprio(3); _Pragma("unroll") for (int m = 0; m < 4; ++m) _Pragma("unroll") for (int n = 0; n < 2; ++n) _Pragma("unroll") for (int k = 0; k < 2; ++k) \
;         acc[ai][bj][m][n] = __builtin_amdgcn_mfma_f32_16x16x32_bf16(Bt[n][k], At[m][k], acc[ai][bj][m][n], 0, 0, 0); __builtin_amdgcn_s_setprio(0); } while (0)
; #define PG8_WAIT_V(n) asm volatile("s_waitcnt vmcnt(" #n ")" ::: "memory")
; #define PG8_WAIT_L(n) asm volatile("s_waitcnt lgkmcnt(" #n ")" ::: "memory")
; #define PG8_BAR __builtin_amdgcn_s_barrier()
; #define PG8_SCHED __builtin_amdgcn_sched_barrier(0)
; template <class Epi, class Sched, bool ALIGN_EPI = false, bool SP2 = false>
; __device__ __forceinline__ void gemm_phase(PG8_LAS unsigned char* lds, const Gemm g, const Sched& S, const Epi& E) {
;     ...
;             PG8_LDA(At, 1, 1); PG8_STAGE(PG8_SB(1, 0), b3, voffB); PG8_STAGE(PG8_SB(1, 1), b3 + hstepB, voffB); PG8_STAGE(PG8_SA(1, 0), a3, voffA);
;             PG8_WAIT_V(8); PG8_WAIT_L(0); PG8_BAR; PG8_MMA(1, 0, At, B0); PG8_MMA(1, 1, At, B1); PG8_BAR; PG8_SCHED;
;     ...
;         if constexpr (ALIGN_EPI) { if (wr == 0) PG8_BAR; }
	s_add_i32 s28, s56, s30
	v_lshl_add_u64 v[146:147], v[146:147], 0, s[12:13]
	s_mov_b32 m0, s28
	ds_read_b128 v[192:195], v157 offset:49152
	ds_read_b128 v[196:199], v157 offset:50176
	ds_read_b128 v[200:203], v157 offset:51200
	ds_read_b128 v[204:207], v157 offset:52224
	ds_read_b128 v[208:211], v157 offset:53248
	ds_read_b128 v[212:215], v157 offset:54272
	ds_read_b128 v[216:219], v157 offset:55296
	ds_read_b128 v[220:223], v157 offset:56320
	global_load_lds_dwordx4 v[146:147], off
	s_add_i32 m0, s28, 0x2000
	s_add_u32 s26, s26, 0x100080
	v_lshl_add_u64 v[146:147], v[224:225], 0, s[12:13]
	s_addc_u32 s27, s27, 0
	s_add_i32 s28, s57, s30
	global_load_lds_dwordx4 v[146:147], off
	v_lshl_add_u64 v[146:147], s[26:27], 0, v[134:135]
	s_mov_b32 m0, s28
	s_nop 0
	global_load_lds_dwordx4 v[146:147], off
	v_lshl_add_u64 v[146:147], s[26:27], 0, v[130:131]
	s_add_i32 m0, s28, 0x2000
	s_nop 0
	global_load_lds_dwordx4 v[146:147], off
	v_lshl_add_u64 v[146:147], v[226:227], 0, s[12:13]
	s_mov_b32 m0, s39
	s_nop 0
	global_load_lds_dwordx4 v[146:147], off
	v_lshl_add_u64 v[146:147], v[228:229], 0, s[12:13]
	s_mov_b32 m0, s40
	s_nop 0
	global_load_lds_dwordx4 v[146:147], off
	s_waitcnt vmcnt(8)
	s_waitcnt lgkmcnt(0)
	s_barrier
	s_setprio 3
	s_waitcnt lgkmcnt(0)
	v_mfma_f32_16x16x32_bf16 v[62:65], v[158:161], v[192:195], v[62:65]
	v_mfma_f32_16x16x32_bf16 v[62:65], v[164:167], v[196:199], v[62:65]
	v_mfma_f32_16x16x32_bf16 v[58:61], v[168:171], v[192:195], v[58:61]
	v_mfma_f32_16x16x32_bf16 v[58:61], v[172:175], v[196:199], v[58:61]
	v_mfma_f32_16x16x32_bf16 v[42:45], v[168:171], v[200:203], v[42:45]
	v_mfma_f32_16x16x32_bf16 v[42:45], v[172:175], v[204:207], v[42:45]
	v_mfma_f32_16x16x32_bf16 v[50:53], v[158:161], v[200:203], v[50:53]
	v_mfma_f32_16x16x32_bf16 v[50:53], v[164:167], v[204:207], v[50:53]
	v_mfma_f32_16x16x32_bf16 v[34:37], v[158:161], v[208:211], v[34:37]
	v_mfma_f32_16x16x32_bf16 v[34:37], v[164:167], v[212:215], v[34:37]
	v_mfma_f32_16x16x32_bf16 v[26:29], v[168:171], v[208:211], v[26:29]
	v_mfma_f32_16x16x32_bf16 v[26:29], v[172:175], v[212:215], v[26:29]
	v_mfma_f32_16x16x32_bf16 v[10:13], v[168:171], v[216:219], v[10:13]
	v_mfma_f32_16x16x32_bf16 v[10:13], v[172:175], v[220:223], v[10:13]
	v_mfma_f32_16x16x32_bf16 v[14:17], v[158:161], v[216:219], v[14:17]
	v_mfma_f32_16x16x32_bf16 v[14:17], v[164:167], v[220:223], v[14:17]
	s_setprio 0
	s_setprio 3
	v_mfma_f32_16x16x32_bf16 v[54:57], v[176:179], v[192:195], v[54:57]
	v_mfma_f32_16x16x32_bf16 v[54:57], v[180:183], v[196:199], v[54:57]
	v_mfma_f32_16x16x32_bf16 v[46:49], v[184:187], v[192:195], v[46:49]
	v_mfma_f32_16x16x32_bf16 v[46:49], v[188:191], v[196:199], v[46:49]
	v_mfma_f32_16x16x32_bf16 v[30:33], v[184:187], v[200:203], v[30:33]
	v_mfma_f32_16x16x32_bf16 v[30:33], v[188:191], v[204:207], v[30:33]
	v_mfma_f32_16x16x32_bf16 v[38:41], v[176:179], v[200:203], v[38:41]
	v_mfma_f32_16x16x32_bf16 v[38:41], v[180:183], v[204:207], v[38:41]
	v_mfma_f32_16x16x32_bf16 v[22:25], v[176:179], v[208:211], v[22:25]
	v_mfma_f32_16x16x32_bf16 v[22:25], v[180:183], v[212:215], v[22:25]
	v_mfma_f32_16x16x32_bf16 v[18:21], v[184:187], v[208:211], v[18:21]
	v_mfma_f32_16x16x32_bf16 v[18:21], v[188:191], v[212:215], v[18:21]
	v_mfma_f32_16x16x32_bf16 v[2:5], v[184:187], v[216:219], v[2:5]
	v_mfma_f32_16x16x32_bf16 v[2:5], v[188:191], v[220:223], v[2:5]
	v_mfma_f32_16x16x32_bf16 v[6:9], v[176:179], v[216:219], v[6:9]
	v_mfma_f32_16x16x32_bf16 v[6:9], v[180:183], v[220:223], v[6:9]
	s_setprio 0
	s_barrier
	s_add_i32 s55, s55, 2
	s_add_u32 s24, s24, 0x100
	s_addc_u32 s25, s25, 0
	s_add_u32 s53, s53, 0x100
	s_addc_u32 s54, s54, 0
	s_cmp_gt_u32 s55, 61
	s_cbranch_scc0 .LBB0_908
	s_and_b64 vcc, exec, s[0:1]
	s_cbranch_vccz .LBB0_911
	s_barrier

; #define PG8_STAGE(bufoff, gbase, voff) do { _Pragma("unroll") for (int _i = 0; _i < 2; ++_i) \
;         __builtin_amdgcn_global_load_lds((const unsigned*)((const char*)(gbase) + (voff)[_i]), (PG8_LAS unsigned*)(lds + (bufoff) + ldsw + _i * 8192), 16, 0, 0); } while (0)
; #define PG8_LDA(dst, b, h) do { _Pragma("unroll") for (int m = 0; m < 4; ++m) _Pragma("unroll") for (int k = 0; k < 2; ++k) dst[m][k] = *(const PG8_LAS bf16x8*)(lds + PG8_SA(b, h) + aoff + m * 2048 + k * 1024); } while (0)
; #define PG8_LDB(dst, b, h) do { _Pragma("unroll") for (int n = 0; n < 2; ++n) _Pragma("unroll") for (int k = 0; k < 2; ++k) dst[n][k] = *(const PG8_LAS bf16x8*)(lds + PG8_SB(b, h) + boff + n * 2048 + k * 1024); } while (0)
; #define PG8_MMA(ai, bj, At, Bt) do { __builtin_amdgcn_s_setprio(3); _Pragma("unroll") for (int m = 0; m < 4; ++m) _Pragma("unroll") for (int n = 0; n < 2; ++n) _Pragma("unroll") for (int k = 0; k < 2; ++k) \
;         acc[ai][bj][m][n] = __builtin_amdgcn_mfma_f32_16x16x32_bf16(Bt[n][k], At[m][k], acc[ai][bj][m][n], 0, 0, 0); __builtin_amdgcn_s_setprio(0); } while (0)
; #define PG8_WAIT_V(n) asm volatile("s_waitcnt vmcnt(" #n ")" ::: "memory")
; #define PG8_WAIT_L(n) asm volatile("s_waitcnt lgkmcnt(" #n ")" ::: "memory")
; template <class Epi, class Sched, bool ALIGN_EPI = false, bool SP2 = false>
; __device__ __forceinline__ void gemm_phase(PG8_LAS unsigned char* lds, const Gemm g, const Sched& S, const Epi& E) {
;     ...
;         for (int t = 0; t < nt; t += 2) {
;             const bool last = (t == nt - 2);
;             const char* a1 = cA + (size_t)(t + 1) * kstep;
;             const char* a2 = last ? nA : cA + (size_t)(t + 2) * kstep; const char* b2 = last ? nB : cB + (size_t)(t + 2) * kstep;
;             const char* a3 = a2 + kstep; const char* b3 = b2 + kstep;
;             if (last && has_next) S.a_ready(nxt);
;             if constexpr (Epi::MIDK) { if (t == E.midk_step(nt)) E.midk(acc, cur, wr, wc, fr, fq); }
;             if constexpr (SP2) {
;             PG8_LDB(B0, 0, 0); PG8_LDB(B1, 0, 1); PG8_SCHED; PG8_LDA(At, 0, 0); PG8_STAGE(PG8_SA(1, 1), a1 + hstepA, voffA);
;             PG8_WAIT_V(8); PG8_WAIT_L(0); PG8_BAR; PG8_MMA(0, 0, At, B0); PG8_MMA(0, 1, At, B1); PG8_BAR; PG8_SCHED;
;             PG8_LDA(At, 0, 1); PG8_STAGE(PG8_SB(0, 0), b2, voffB); PG8_STAGE(PG8_SB(0, 1), b2 + hstepB, voffB); PG8_STAGE(PG8_SA(0, 0), a2, voffA);
.LBB0_975:
	v_add_u32_e32 v144, s46, v206
	v_add_u32_e32 v160, s47, v206
	s_add_u32 s28, s2, s12
	ds_read_b128 v[132:135], v144
	ds_read_b128 v[136:139], v144 offset:1024
	ds_read_b128 v[140:143], v144 offset:2048
	ds_read_b128 v[144:147], v144 offset:3072
	ds_read_b128 v[148:151], v160
	ds_read_b128 v[152:155], v160 offset:1024
	ds_read_b128 v[156:159], v160 offset:2048
	ds_read_b128 v[160:163], v160 offset:3072
	s_addc_u32 s29, s3, s13
	s_add_u32 s28, s28, 0x21500100
	s_addc_u32 s29, s29, 0
	s_add_u32 s81, s44, s12
	s_addc_u32 s82, s45, s13
	s_cmpk_eq_i32 s12, 0x5500
	s_cselect_b32 s31, s1, s29
	s_cselect_b32 s30, s0, s28
	s_cselect_b32 s29, s11, s82
	s_cselect_b32 s28, s10, s81
	s_mov_b32 m0, s71
	v_lshl_add_u64 v[234:235], v[2:3], 0, s[12:13]
	ds_read_b128 v[164:167], v207
	ds_read_b128 v[168:171], v207 offset:1024
	ds_read_b128 v[210:213], v207 offset:2048
	ds_read_b128 v[214:217], v207 offset:3072
	ds_read_b128 v[218:221], v207 offset:4096
	ds_read_b128 v[222:225], v207 offset:5120
	ds_read_b128 v[226:229], v207 offset:6144
	ds_read_b128 v[230:233], v207 offset:7168
	global_load_lds_dwordx4 v[234:235], off
	v_lshl_add_u64 v[234:235], v[200:201], 0, s[12:13]
	s_mov_b32 m0, s72
	s_nop 0
	global_load_lds_dwordx4 v[234:235], off
	s_waitcnt vmcnt(8)
	s_waitcnt lgkmcnt(0)
	s_barrier
	s_setprio 3
	s_waitcnt lgkmcnt(0)
	v_mfma_f32_16x16x32_bf16 v[128:131], v[132:135], v[164:167], v[128:131]
	v_mfma_f32_16x16x32_bf16 v[128:131], v[136:139], v[168:171], v[128:131]
	v_mfma_f32_16x16x32_bf16 v[124:127], v[140:143], v[164:167], v[124:127]
	v_mfma_f32_16x16x32_bf16 v[124:127], v[144:147], v[168:171], v[124:127]
	v_mfma_f32_16x16x32_bf16 v[96:99], v[140:143], v[210:213], v[96:99]
	v_mfma_f32_16x16x32_bf16 v[96:99], v[144:147], v[214:217], v[96:99]
	v_mfma_f32_16x16x32_bf16 v[100:103], v[132:135], v[210:213], v[100:103]
	v_mfma_f32_16x16x32_bf16 v[100:103], v[136:139], v[214:217], v[100:103]
	v_mfma_f32_16x16x32_bf16 v[112:115], v[132:135], v[218:221], v[112:115]
	v_mfma_f32_16x16x32_bf16 v[112:115], v[136:139], v[222:225], v[112:115]
	v_mfma_f32_16x16x32_bf16 v[108:111], v[140:143], v[218:221], v[108:111]
	v_mfma_f32_16x16x32_bf16 v[108:111], v[144:147], v[222:225], v[108:111]
	v_mfma_f32_16x16x32_bf16 v[76:79], v[140:143], v[226:229], v[76:79]
	v_mfma_f32_16x16x32_bf16 v[76:79], v[144:147], v[230:233], v[76:79]
	v_mfma_f32_16x16x32_bf16 v[80:83], v[132:135], v[226:229], v[80:83]
	v_mfma_f32_16x16x32_bf16 v[80:83], v[136:139], v[230:233], v[80:83]
	s_setprio 0
	s_setprio 3
	v_mfma_f32_16x16x32_bf16 v[120:123], v[148:151], v[164:167], v[120:123]
	v_mfma_f32_16x16x32_bf16 v[120:123], v[152:155], v[168:171], v[120:123]
	v_mfma_f32_16x16x32_bf16 v[116:119], v[156:159], v[164:167], v[116:119]
	v_mfma_f32_16x16x32_bf16 v[116:119], v[160:163], v[168:171], v[116:119]
	v_mfma_f32_16x16x32_bf16 v[88:91], v[156:159], v[210:213], v[88:91]
	v_mfma_f32_16x16x32_bf16 v[88:91], v[160:163], v[214:217], v[88:91]
	v_mfma_f32_16x16x32_bf16 v[92:95], v[148:151], v[210:213], v[92:95]
	v_mfma_f32_16x16x32_bf16 v[92:95], v[152:155], v[214:217], v[92:95]
	v_mfma_f32_16x16x32_bf16 v[104:107], v[148:151], v[218:221], v[104:107]
	v_mfma_f32_16x16x32_bf16 v[104:107], v[152:155], v[222:225], v[104:107]
	v_mfma_f32_16x16x32_bf16 v[84:87], v[156:159], v[218:221], v[84:87]
	v_mfma_f32_16x16x32_bf16 v[84:87], v[160:163], v[222:225], v[84:87]
	v_mfma_f32_16x16x32_bf16 v[68:71], v[156:159], v[226:229], v[68:71]
	v_mfma_f32_16x16x32_bf16 v[68:71], v[160:163], v[230:233], v[68:71]
	v_mfma_f32_16x16x32_bf16 v[72:75], v[148:151], v[226:229], v[72:75]
	v_mfma_f32_16x16x32_bf16 v[72:75], v[152:155], v[230:233], v[72:75]
	s_setprio 0
	s_barrier
	s_mov_b32 m0, s73
	v_lshl_add_u64 v[234:235], s[28:29], 0, v[174:175]
	s_add_u32 s82, s28, 0x2b0000
	ds_read_b128 v[164:167], v207 offset:16384
	ds_read_b128 v[168:171], v207 offset:17408
	ds_read_b128 v[210:213], v207 offset:18432
	ds_read_b128 v[214:217], v207 offset:19456
	ds_read_b128 v[218:221], v207 offset:20480
	ds_read_b128 v[222:225], v207 offset:21504
	ds_read_b128 v[226:229], v207 offset:22528
	ds_read_b128 v[230:233], v207 offset:23552
	global_load_lds_dwordx4 v[234:235], off
	v_lshl_add_u64 v[236:237], s[28:29], 0, v[178:179]
	s_mov_b32 m0, s74
	s_addc_u32 s83, s29, 0
	global_load_lds_dwordx4 v[236:237], off
	v_lshl_add_u64 v[238:239], s[82:83], 0, v[174:175]
	s_mov_b32 m0, s75
	v_lshl_add_u64 v[240:241], s[30:31], 0, v[176:177]
	global_load_lds_dwordx4 v[238:239], off
	v_lshl_add_u64 v[238:239], s[82:83], 0, v[178:179]
	s_mov_b32 m0, s76
	s_nop 0
	global_load_lds_dwordx4 v[238:239], off
	v_lshl_add_u64 v[238:239], s[30:31], 0, v[172:173]
	s_mov_b32 m0, s42
	s_nop 0
	global_load_lds_dwordx4 v[238:239], off
	s_mov_b32 m0, s54
	s_nop 0
	global_load_lds_dwordx4 v[240:241], off
	s_waitcnt vmcnt(8)
	s_waitcnt lgkmcnt(0)
	s_barrier
; #define PG8_STAGE(bufoff, gbase, voff) do { _Pragma("unroll") for (int _i = 0; _i < 2; ++_i) \
;         __builtin_amdgcn_global_load_lds((const unsigned*)((const char*)(gbase) + (voff)[_i]), (PG8_LAS unsigned*)(lds + (bufoff) + ldsw + _i * 8192), 16, 0, 0); } while (0)
; #define PG8_LDA(dst, b, h) do { _Pragma("unroll") for (int m = 0; m < 4; ++m) _Pragma("unroll") for (int k = 0; k < 2; ++k) dst[m][k] = *(const PG8_LAS bf16x8*)(lds + PG8_SA(b, h) + aoff + m * 2048 + k * 1024); } while (0)
; #define PG8_LDB(dst, b, h) do { _Pragma("unroll") for (int n = 0; n < 2; ++n) _Pragma("unroll") for (int k = 0; k < 2; ++k) dst[n][k] = *(const PG8_LAS bf16x8*)(lds + PG8_SB(b, h) + boff + n * 2048 + k * 1024); } while (0)
; #define PG8_MMA(ai, bj, At, Bt) do { __builtin_amdgcn_s_setprio(3); _Pragma("unroll") for (int m = 0; m < 4; ++m) _Pragma("unroll") for (int n = 0; n < 2; ++n) _Pragma("unroll") for (int k = 0; k < 2; ++k) \
;         acc[ai][bj][m][n] = __builtin_amdgcn_mfma_f32_16x16x32_bf16(Bt[n][k], At[m][k], acc[ai][bj][m][n], 0, 0, 0); __builtin_amdgcn_s_setprio(0); } while (0)
; #define PG8_WAIT_V(n) asm volatile("s_waitcnt vmcnt(" #n ")" ::: "memory")
; #define PG8_WAIT_L(n) asm volatile("s_waitcnt lgkmcnt(" #n ")" ::: "memory")
; #define PG8_BAR __builtin_amdgcn_s_barrier()
; #define PG8_SCHED __builtin_amdgcn_sched_barrier(0)
; template <class Epi, class Sched, bool ALIGN_EPI = false, bool SP2 = false>
; __device__ __forceinline__ void gemm_phase(PG8_LAS unsigned char* lds, const Gemm g, const Sched& S, const Epi& E) {
;     ...
;             PG8_WAIT_V(8); PG8_WAIT_L(0); PG8_BAR; PG8_MMA(1, 0, At, B0); PG8_MMA(1, 1, At, B1); PG8_BAR; PG8_SCHED;
;             PG8_LDB(B0, 1, 0); PG8_LDB(B1, 1, 1); PG8_SCHED; PG8_LDA(At, 1, 0); PG8_STAGE(PG8_SA(0, 1), a2 + hstepA, voffA);
;             PG8_WAIT_V(8); PG8_WAIT_L(0); PG8_BAR; PG8_MMA(0, 0, At, B0); PG8_MMA(0, 1, At, B1); PG8_BAR; PG8_SCHED;
	s_setprio 3
	s_waitcnt lgkmcnt(0)
	v_mfma_f32_16x16x32_bf16 v[64:67], v[132:135], v[164:167], v[64:67]
	v_mfma_f32_16x16x32_bf16 v[64:67], v[136:139], v[168:171], v[64:67]
	v_mfma_f32_16x16x32_bf16 v[60:63], v[140:143], v[164:167], v[60:63]
	v_mfma_f32_16x16x32_bf16 v[60:63], v[144:147], v[168:171], v[60:63]
	v_mfma_f32_16x16x32_bf16 v[44:47], v[140:143], v[210:213], v[44:47]
	v_mfma_f32_16x16x32_bf16 v[44:47], v[144:147], v[214:217], v[44:47]
	v_mfma_f32_16x16x32_bf16 v[48:51], v[132:135], v[210:213], v[48:51]
	v_mfma_f32_16x16x32_bf16 v[48:51], v[136:139], v[214:217], v[48:51]
	v_mfma_f32_16x16x32_bf16 v[32:35], v[132:135], v[218:221], v[32:35]
	v_mfma_f32_16x16x32_bf16 v[32:35], v[136:139], v[222:225], v[32:35]
	v_mfma_f32_16x16x32_bf16 v[28:31], v[140:143], v[218:221], v[28:31]
	v_mfma_f32_16x16x32_bf16 v[28:31], v[144:147], v[222:225], v[28:31]
	v_mfma_f32_16x16x32_bf16 v[12:15], v[140:143], v[226:229], v[12:15]
	v_mfma_f32_16x16x32_bf16 v[12:15], v[144:147], v[230:233], v[12:15]
	v_mfma_f32_16x16x32_bf16 v[16:19], v[132:135], v[226:229], v[16:19]
	v_mfma_f32_16x16x32_bf16 v[16:19], v[136:139], v[230:233], v[16:19]
	s_setprio 0
	s_setprio 3
	v_mfma_f32_16x16x32_bf16 v[56:59], v[148:151], v[164:167], v[56:59]
	v_mfma_f32_16x16x32_bf16 v[56:59], v[152:155], v[168:171], v[56:59]
	v_mfma_f32_16x16x32_bf16 v[52:55], v[156:159], v[164:167], v[52:55]
	v_mfma_f32_16x16x32_bf16 v[52:55], v[160:163], v[168:171], v[52:55]
	v_mfma_f32_16x16x32_bf16 v[36:39], v[156:159], v[210:213], v[36:39]
	v_mfma_f32_16x16x32_bf16 v[36:39], v[160:163], v[214:217], v[36:39]
	v_mfma_f32_16x16x32_bf16 v[40:43], v[148:151], v[210:213], v[40:43]
	v_mfma_f32_16x16x32_bf16 v[40:43], v[152:155], v[214:217], v[40:43]
	v_mfma_f32_16x16x32_bf16 v[24:27], v[148:151], v[218:221], v[24:27]
	v_mfma_f32_16x16x32_bf16 v[24:27], v[152:155], v[222:225], v[24:27]
	v_mfma_f32_16x16x32_bf16 v[20:23], v[156:159], v[218:221], v[20:23]
	v_mfma_f32_16x16x32_bf16 v[20:23], v[160:163], v[222:225], v[20:23]
	v_mfma_f32_16x16x32_bf16 v[4:7], v[156:159], v[226:229], v[4:7]
	v_mfma_f32_16x16x32_bf16 v[4:7], v[160:163], v[230:233], v[4:7]
	v_mfma_f32_16x16x32_bf16 v[8:11], v[148:151], v[226:229], v[8:11]
	v_mfma_f32_16x16x32_bf16 v[8:11], v[152:155], v[230:233], v[8:11]
	s_setprio 0
	s_barrier
	v_add_u32_e32 v144, s52, v206
	v_add_u32_e32 v160, s53, v206
	ds_read_b128 v[132:135], v144
	ds_read_b128 v[136:139], v144 offset:1024
	ds_read_b128 v[140:143], v144 offset:2048
	ds_read_b128 v[144:147], v144 offset:3072
	ds_read_b128 v[148:151], v160
	ds_read_b128 v[152:155], v160 offset:1024
	ds_read_b128 v[156:159], v160 offset:2048
	ds_read_b128 v[160:163], v160 offset:3072
	s_add_u32 s30, s30, 0x2b0000
	s_addc_u32 s31, s31, 0
	s_mov_b32 m0, s55
	v_lshl_add_u64 v[242:243], s[30:31], 0, v[172:173]
	ds_read_b128 v[164:167], v207 offset:32768
	ds_read_b128 v[168:171], v207 offset:33792
	ds_read_b128 v[210:213], v207 offset:34816
	ds_read_b128 v[214:217], v207 offset:35840
	ds_read_b128 v[218:221], v207 offset:36864
	ds_read_b128 v[222:225], v207 offset:37888
	ds_read_b128 v[226:229], v207 offset:38912
	ds_read_b128 v[230:233], v207 offset:39936
	global_load_lds_dwordx4 v[242:243], off
	v_lshl_add_u64 v[242:243], s[30:31], 0, v[176:177]
	s_mov_b32 m0, s56
	s_nop 0
	global_load_lds_dwordx4 v[242:243], off
	s_waitcnt vmcnt(8)
	s_waitcnt lgkmcnt(0)
	s_barrier
	s_setprio 3
	s_waitcnt lgkmcnt(0)
	v_mfma_f32_16x16x32_bf16 v[128:131], v[132:135], v[164:167], v[128:131]
	v_mfma_f32_16x16x32_bf16 v[128:131], v[136:139], v[168:171], v[128:131]
	v_mfma_f32_16x16x32_bf16 v[124:127], v[140:143], v[164:167], v[124:127]
	v_mfma_f32_16x16x32_bf16 v[124:127], v[144:147], v[168:171], v[124:127]
	v_mfma_f32_16x16x32_bf16 v[96:99], v[140:143], v[210:213], v[96:99]
	v_mfma_f32_16x16x32_bf16 v[96:99], v[144:147], v[214:217], v[96:99]
	v_mfma_f32_16x16x32_bf16 v[100:103], v[132:135], v[210:213], v[100:103]
	v_mfma_f32_16x16x32_bf16 v[100:103], v[136:139], v[214:217], v[100:103]
	v_mfma_f32_16x16x32_bf16 v[112:115], v[132:135], v[218:221], v[112:115]
	v_mfma_f32_16x16x32_bf16 v[112:115], v[136:139], v[222:225], v[112:115]
	v_mfma_f32_16x16x32_bf16 v[108:111], v[140:143], v[218:221], v[108:111]
	v_mfma_f32_16x16x32_bf16 v[108:111], v[144:147], v[222:225], v[108:111]
	v_mfma_f32_16x16x32_bf16 v[76:79], v[140:143], v[226:229], v[76:79]
	v_mfma_f32_16x16x32_bf16 v[76:79], v[144:147], v[230:233], v[76:79]
	v_mfma_f32_16x16x32_bf16 v[80:83], v[132:135], v[226:229], v[80:83]
	v_mfma_f32_16x16x32_bf16 v[80:83], v[136:139], v[230:233], v[80:83]
	s_setprio 0
	s_setprio 3
	v_mfma_f32_16x16x32_bf16 v[120:123], v[148:151], v[164:167], v[120:123]
	v_mfma_f32_16x16x32_bf16 v[120:123], v[152:155], v[168:171], v[120:123]
	v_mfma_f32_16x16x32_bf16 v[116:119], v[156:159], v[164:167], v[116:119]
	v_mfma_f32_16x16x32_bf16 v[116:119], v[160:163], v[168:171], v[116:119]
	v_mfma_f32_16x16x32_bf16 v[88:91], v[156:159], v[210:213], v[88:91]
	v_mfma_f32_16x16x32_bf16 v[88:91], v[160:163], v[214:217], v[88:91]
	v_mfma_f32_16x16x32_bf16 v[92:95], v[148:151], v[210:213], v[92:95]
	v_mfma_f32_16x16x32_bf16 v[92:95], v[152:155], v[214:217], v[92:95]
	v_mfma_f32_16x16x32_bf16 v[104:107], v[148:151], v[218:221], v[104:107]
	v_mfma_f32_16x16x32_bf16 v[104:107], v[152:155], v[222:225], v[104:107]
	v_mfma_f32_16x16x32_bf16 v[84:87], v[156:159], v[218:221], v[84:87]
	v_mfma_f32_16x16x32_bf16 v[84:87], v[160:163], v[222:225], v[84:87]
	v_mfma_f32_16x16x32_bf16 v[68:71], v[156:159], v[226:229], v[68:71]
	v_mfma_f32_16x16x32_bf16 v[68:71], v[160:163], v[230:233], v[68:71]
	v_mfma_f32_16x16x32_bf16 v[72:75], v[148:151], v[226:229], v[72:75]
	v_mfma_f32_16x16x32_bf16 v[72:75], v[152:155], v[230:233], v[72:75]
	s_setprio 0
	s_barrier
; #define PG8_STAGE(bufoff, gbase, voff) do { _Pragma("unroll") for (int _i = 0; _i < 2; ++_i) \
;         __builtin_amdgcn_global_load_lds((const unsigned*)((const char*)(gbase) + (voff)[_i]), (PG8_LAS unsigned*)(lds + (bufoff) + ldsw + _i * 8192), 16, 0, 0); } while (0)
; #define PG8_LDA(dst, b, h) do { _Pragma("unroll") for (int m = 0; m < 4; ++m) _Pragma("unroll") for (int k = 0; k < 2; ++k) dst[m][k] = *(const PG8_LAS bf16x8*)(lds + PG8_SA(b, h) + aoff + m * 2048 + k * 1024); } while (0)
; #define PG8_MMA(ai, bj, At, Bt) do { __builtin_amdgcn_s_setprio(3); _Pragma("unroll") for (int m = 0; m < 4; ++m) _Pragma("unroll") for (int n = 0; n < 2; ++n) _Pragma("unroll") for (int k = 0; k < 2; ++k) \
;         acc[ai][bj][m][n] = __builtin_amdgcn_mfma_f32_16x16x32_bf16(Bt[n][k], At[m][k], acc[ai][bj][m][n], 0, 0, 0); __builtin_amdgcn_s_setprio(0); } while (0)
; #define PG8_WAIT_V(n) asm volatile("s_waitcnt vmcnt(" #n ")" ::: "memory")
; #define PG8_WAIT_L(n) asm volatile("s_waitcnt lgkmcnt(" #n ")" ::: "memory")
; #define PG8_BAR __builtin_amdgcn_s_barrier()
; #define PG8_SCHED __builtin_amdgcn_sched_barrier(0)
; template <class Epi, class Sched, bool ALIGN_EPI = false, bool SP2 = false>
; __device__ __forceinline__ void gemm_phase(PG8_LAS unsigned char* lds, const Gemm g, const Sched& S, const Epi& E) {
;     ...
;         for (int t = 0; t < nt; t += 2) {
;             const bool last = (t == nt - 2);
;     ...
;             PG8_LDA(At, 1, 1); PG8_STAGE(PG8_SB(1, 0), b3, voffB); PG8_STAGE(PG8_SB(1, 1), b3 + hstepB, voffB); PG8_STAGE(PG8_SA(1, 0), a3, voffA);
;             PG8_WAIT_V(8); PG8_WAIT_L(0); PG8_BAR; PG8_MMA(1, 0, At, B0); PG8_MMA(1, 1, At, B1); PG8_BAR; PG8_SCHED;
	s_mov_b32 m0, s77
	v_lshl_add_u64 v[234:235], v[234:235], 0, s[4:5]
	s_add_u32 s28, s28, 0x2b0080
	ds_read_b128 v[164:167], v207 offset:49152
	ds_read_b128 v[168:171], v207 offset:50176
	ds_read_b128 v[210:213], v207 offset:51200
	ds_read_b128 v[214:217], v207 offset:52224
	ds_read_b128 v[218:221], v207 offset:53248
	ds_read_b128 v[222:225], v207 offset:54272
	ds_read_b128 v[226:229], v207 offset:55296
	ds_read_b128 v[230:233], v207 offset:56320
	global_load_lds_dwordx4 v[234:235], off
	v_lshl_add_u64 v[234:235], v[236:237], 0, s[4:5]
	s_mov_b32 m0, s78
	s_addc_u32 s29, s29, 0
	global_load_lds_dwordx4 v[234:235], off
	v_lshl_add_u64 v[234:235], s[28:29], 0, v[174:175]
	s_mov_b32 m0, s79
	s_nop 0
	global_load_lds_dwordx4 v[234:235], off
	v_lshl_add_u64 v[234:235], s[28:29], 0, v[178:179]
	s_mov_b32 m0, s80
	s_nop 0
	global_load_lds_dwordx4 v[234:235], off
	v_lshl_add_u64 v[234:235], v[238:239], 0, s[4:5]
	s_mov_b32 m0, s57
	s_nop 0
	global_load_lds_dwordx4 v[234:235], off
	v_lshl_add_u64 v[234:235], v[240:241], 0, s[4:5]
	s_mov_b32 m0, s58
	s_nop 0
	global_load_lds_dwordx4 v[234:235], off
	s_waitcnt vmcnt(8)
	s_waitcnt lgkmcnt(0)
	s_barrier
	s_setprio 3
	s_waitcnt lgkmcnt(0)
	v_mfma_f32_16x16x32_bf16 v[64:67], v[132:135], v[164:167], v[64:67]
	v_mfma_f32_16x16x32_bf16 v[64:67], v[136:139], v[168:171], v[64:67]
	v_mfma_f32_16x16x32_bf16 v[60:63], v[140:143], v[164:167], v[60:63]
	v_mfma_f32_16x16x32_bf16 v[60:63], v[144:147], v[168:171], v[60:63]
	v_mfma_f32_16x16x32_bf16 v[44:47], v[140:143], v[210:213], v[44:47]
	v_mfma_f32_16x16x32_bf16 v[44:47], v[144:147], v[214:217], v[44:47]
	v_mfma_f32_16x16x32_bf16 v[48:51], v[132:135], v[210:213], v[48:51]
	v_mfma_f32_16x16x32_bf16 v[48:51], v[136:139], v[214:217], v[48:51]
	v_mfma_f32_16x16x32_bf16 v[32:35], v[132:135], v[218:221], v[32:35]
	v_mfma_f32_16x16x32_bf16 v[32:35], v[136:139], v[222:225], v[32:35]
	v_mfma_f32_16x16x32_bf16 v[28:31], v[140:143], v[218:221], v[28:31]
	v_mfma_f32_16x16x32_bf16 v[28:31], v[144:147], v[222:225], v[28:31]
	v_mfma_f32_16x16x32_bf16 v[12:15], v[140:143], v[226:229], v[12:15]
	v_mfma_f32_16x16x32_bf16 v[12:15], v[144:147], v[230:233], v[12:15]
	v_mfma_f32_16x16x32_bf16 v[16:19], v[132:135], v[226:229], v[16:19]
	v_mfma_f32_16x16x32_bf16 v[16:19], v[136:139], v[230:233], v[16:19]
	s_setprio 0
	s_setprio 3
	v_mfma_f32_16x16x32_bf16 v[56:59], v[148:151], v[164:167], v[56:59]
	v_mfma_f32_16x16x32_bf16 v[56:59], v[152:155], v[168:171], v[56:59]
	v_mfma_f32_16x16x32_bf16 v[52:55], v[156:159], v[164:167], v[52:55]
	v_mfma_f32_16x16x32_bf16 v[52:55], v[160:163], v[168:171], v[52:55]
	v_mfma_f32_16x16x32_bf16 v[36:39], v[156:159], v[210:213], v[36:39]
	v_mfma_f32_16x16x32_bf16 v[36:39], v[160:163], v[214:217], v[36:39]
	v_mfma_f32_16x16x32_bf16 v[40:43], v[148:151], v[210:213], v[40:43]
	v_mfma_f32_16x16x32_bf16 v[40:43], v[152:155], v[214:217], v[40:43]
	v_mfma_f32_16x16x32_bf16 v[24:27], v[148:151], v[218:221], v[24:27]
	v_mfma_f32_16x16x32_bf16 v[24:27], v[152:155], v[222:225], v[24:27]
	v_mfma_f32_16x16x32_bf16 v[20:23], v[156:159], v[218:221], v[20:23]
	v_mfma_f32_16x16x32_bf16 v[20:23], v[160:163], v[222:225], v[20:23]
	v_mfma_f32_16x16x32_bf16 v[4:7], v[156:159], v[226:229], v[4:7]
	v_mfma_f32_16x16x32_bf16 v[4:7], v[160:163], v[230:233], v[4:7]
	v_mfma_f32_16x16x32_bf16 v[8:11], v[148:151], v[226:229], v[8:11]
	v_mfma_f32_16x16x32_bf16 v[8:11], v[152:155], v[230:233], v[8:11]
	s_setprio 0
	s_barrier
	s_add_i32 s61, s61, 2
	s_add_u32 s12, s12, 0x100
	s_addc_u32 s13, s13, 0
	s_cmpk_gt_u32 s61, 0xa9
	s_cbranch_scc1 .LBB0_978

; #define PG8_STAGE(bufoff, gbase, voff) do { _Pragma("unroll") for (int _i = 0; _i < 2; ++_i) \
;         __builtin_amdgcn_global_load_lds((const unsigned*)((const char*)(gbase) + (voff)[_i]), (PG8_LAS unsigned*)(lds + (bufoff) + ldsw + _i * 8192), 16, 0, 0); } while (0)
; #define PG8_LDA(dst, b, h) do { _Pragma("unroll") for (int m = 0; m < 4; ++m) _Pragma("unroll") for (int k = 0; k < 2; ++k) dst[m][k] = *(const PG8_LAS bf16x8*)(lds + PG8_SA(b, h) + aoff + m * 2048 + k * 1024); } while (0)
; #define PG8_LDB(dst, b, h) do { _Pragma("unroll") for (int n = 0; n < 2; ++n) _Pragma("unroll") for (int k = 0; k < 2; ++k) dst[n][k] = *(const PG8_LAS bf16x8*)(lds + PG8_SB(b, h) + boff + n * 2048 + k * 1024); } while (0)
; #define PG8_MMA(ai, bj, At, Bt) do { __builtin_amdgcn_s_setprio(3); _Pragma("unroll") for (int m = 0; m < 4; ++m) _Pragma("unroll") for (int n = 0; n < 2; ++n) _Pragma("unroll") for (int k = 0; k < 2; ++k) \
;         acc[ai][bj][m][n] = __builtin_amdgcn_mfma_f32_16x16x32_bf16(Bt[n][k], At[m][k], acc[ai][bj][m][n], 0, 0, 0); __builtin_amdgcn_s_setprio(0); } while (0)
; #define PG8_WAIT_V(n) asm volatile("s_waitcnt vmcnt(" #n ")" ::: "memory")
; #define PG8_WAIT_L(n) asm volatile("s_waitcnt lgkmcnt(" #n ")" ::: "memory")
; template <class Epi, class Sched, bool ALIGN_EPI = false, bool SP2 = false>
; __device__ __forceinline__ void gemm_phase(PG8_LAS unsigned char* lds, const Gemm g, const Sched& S, const Epi& E) {
;     ...
;         for (int t = 0; t < nt; t += 2) {
;             const bool last = (t == nt - 2);
;             const char* a1 = cA + (size_t)(t + 1) * kstep;
;             const char* a2 = last ? nA : cA + (size_t)(t + 2) * kstep; const char* b2 = last ? nB : cB + (size_t)(t + 2) * kstep;
;             const char* a3 = a2 + kstep; const char* b3 = b2 + kstep;
;             if (last && has_next) S.a_ready(nxt);
;             if constexpr (Epi::MIDK) { if (t == E.midk_step(nt)) E.midk(acc, cur, wr, wc, fr, fq); }
;             if constexpr (SP2) {
;             PG8_LDB(B0, 0, 0); PG8_LDB(B1, 0, 1); PG8_SCHED; PG8_LDA(At, 0, 0); PG8_STAGE(PG8_SA(1, 1), a1 + hstepA, voffA);
;             PG8_WAIT_V(8); PG8_WAIT_L(0); PG8_BAR; PG8_MMA(0, 0, At, B0); PG8_MMA(0, 1, At, B1); PG8_BAR; PG8_SCHED;
;             PG8_LDA(At, 0, 1); PG8_STAGE(PG8_SB(0, 0), b2, voffB); PG8_STAGE(PG8_SB(0, 1), b2 + hstepB, voffB); PG8_STAGE(PG8_SA(0, 0), a2, voffA);
.LBB0_1018:
	v_add_u32_e32 v142, s46, v189
	v_add_u32_e32 v158, s47, v189
	s_add_u32 s40, s20, s22
	ds_read_b128 v[130:133], v142
	ds_read_b128 v[134:137], v142 offset:1024
	ds_read_b128 v[138:141], v142 offset:2048
	ds_read_b128 v[142:145], v142 offset:3072
	ds_read_b128 v[146:149], v158
	ds_read_b128 v[150:153], v158 offset:1024
	ds_read_b128 v[154:157], v158 offset:2048
	ds_read_b128 v[158:161], v158 offset:3072
	s_addc_u32 s41, s21, s23
	s_add_u32 s40, s40, 0x21500100
	s_addc_u32 s41, s41, 0
	s_add_u32 s87, s44, s22
	s_addc_u32 s88, s45, s23
	s_cmpk_eq_i32 s22, 0x5500
	s_cselect_b32 s43, s17, s41
	s_cselect_b32 s42, s16, s40
	s_cselect_b32 s41, s11, s88
	s_cselect_b32 s40, s10, s87
	s_mov_b32 m0, s77
	v_lshl_add_u64 v[186:187], v[0:1], 0, s[22:23]
	ds_read_b128 v[162:165], v180
	ds_read_b128 v[166:169], v180 offset:1024
	ds_read_b128 v[182:185], v180 offset:2048
	ds_read_b128 v[190:193], v180 offset:3072
	ds_read_b128 v[194:197], v180 offset:4096
	ds_read_b128 v[208:211], v180 offset:5120
	ds_read_b128 v[212:215], v180 offset:6144
	ds_read_b128 v[216:219], v180 offset:7168
	global_load_lds_dwordx4 v[186:187], off
	v_lshl_add_u64 v[186:187], v[170:171], 0, s[22:23]
	s_mov_b32 m0, s78
	s_nop 0
	global_load_lds_dwordx4 v[186:187], off
	s_waitcnt vmcnt(8)
	s_waitcnt lgkmcnt(0)
	s_barrier
	s_setprio 3
	s_waitcnt lgkmcnt(0)
	v_mfma_f32_16x16x32_bf16 v[126:129], v[130:133], v[162:165], v[126:129]
	v_mfma_f32_16x16x32_bf16 v[126:129], v[134:137], v[166:169], v[126:129]
	v_mfma_f32_16x16x32_bf16 v[122:125], v[138:141], v[162:165], v[122:125]
	v_mfma_f32_16x16x32_bf16 v[122:125], v[142:145], v[166:169], v[122:125]
	v_mfma_f32_16x16x32_bf16 v[94:97], v[138:141], v[182:185], v[94:97]
	v_mfma_f32_16x16x32_bf16 v[94:97], v[142:145], v[190:193], v[94:97]
	v_mfma_f32_16x16x32_bf16 v[98:101], v[130:133], v[182:185], v[98:101]
	v_mfma_f32_16x16x32_bf16 v[98:101], v[134:137], v[190:193], v[98:101]
	v_mfma_f32_16x16x32_bf16 v[110:113], v[130:133], v[194:197], v[110:113]
	v_mfma_f32_16x16x32_bf16 v[110:113], v[134:137], v[208:211], v[110:113]
	v_mfma_f32_16x16x32_bf16 v[106:109], v[138:141], v[194:197], v[106:109]
	v_mfma_f32_16x16x32_bf16 v[106:109], v[142:145], v[208:211], v[106:109]
	v_mfma_f32_16x16x32_bf16 v[74:77], v[138:141], v[212:215], v[74:77]
	v_mfma_f32_16x16x32_bf16 v[74:77], v[142:145], v[216:219], v[74:77]
	v_mfma_f32_16x16x32_bf16 v[78:81], v[130:133], v[212:215], v[78:81]
	v_mfma_f32_16x16x32_bf16 v[78:81], v[134:137], v[216:219], v[78:81]
	s_setprio 0
	s_setprio 3
	v_mfma_f32_16x16x32_bf16 v[118:121], v[146:149], v[162:165], v[118:121]
	v_mfma_f32_16x16x32_bf16 v[118:121], v[150:153], v[166:169], v[118:121]
	v_mfma_f32_16x16x32_bf16 v[114:117], v[154:157], v[162:165], v[114:117]
	v_mfma_f32_16x16x32_bf16 v[114:117], v[158:161], v[166:169], v[114:117]
	v_mfma_f32_16x16x32_bf16 v[86:89], v[154:157], v[182:185], v[86:89]
	v_mfma_f32_16x16x32_bf16 v[86:89], v[158:161], v[190:193], v[86:89]
	v_mfma_f32_16x16x32_bf16 v[90:93], v[146:149], v[182:185], v[90:93]
	v_mfma_f32_16x16x32_bf16 v[90:93], v[150:153], v[190:193], v[90:93]
	v_mfma_f32_16x16x32_bf16 v[102:105], v[146:149], v[194:197], v[102:105]
	v_mfma_f32_16x16x32_bf16 v[102:105], v[150:153], v[208:211], v[102:105]
	v_mfma_f32_16x16x32_bf16 v[82:85], v[154:157], v[194:197], v[82:85]
	v_mfma_f32_16x16x32_bf16 v[82:85], v[158:161], v[208:211], v[82:85]
	v_mfma_f32_16x16x32_bf16 v[66:69], v[154:157], v[212:215], v[66:69]
	v_mfma_f32_16x16x32_bf16 v[66:69], v[158:161], v[216:219], v[66:69]
	v_mfma_f32_16x16x32_bf16 v[70:73], v[146:149], v[212:215], v[70:73]
	v_mfma_f32_16x16x32_bf16 v[70:73], v[150:153], v[216:219], v[70:73]
	s_setprio 0
	s_barrier
	s_mov_b32 m0, s79
	v_lshl_add_u64 v[186:187], s[40:41], 0, v[174:175]
	s_add_u32 s88, s40, 0x2b0000
	ds_read_b128 v[162:165], v180 offset:16384
	ds_read_b128 v[166:169], v180 offset:17408
	ds_read_b128 v[182:185], v180 offset:18432
	ds_read_b128 v[190:193], v180 offset:19456
	ds_read_b128 v[194:197], v180 offset:20480
	ds_read_b128 v[208:211], v180 offset:21504
	ds_read_b128 v[212:215], v180 offset:22528
	ds_read_b128 v[216:219], v180 offset:23552
	global_load_lds_dwordx4 v[186:187], off
	v_lshl_add_u64 v[198:199], s[40:41], 0, v[178:179]
	s_mov_b32 m0, s80
	s_addc_u32 s89, s41, 0
	global_load_lds_dwordx4 v[198:199], off
	v_lshl_add_u64 v[204:205], s[88:89], 0, v[174:175]
	s_mov_b32 m0, s81
	v_lshl_add_u64 v[220:221], s[42:43], 0, v[176:177]
	global_load_lds_dwordx4 v[204:205], off
	v_lshl_add_u64 v[204:205], s[88:89], 0, v[178:179]
	s_mov_b32 m0, s82
	s_nop 0
	global_load_lds_dwordx4 v[204:205], off
	v_lshl_add_u64 v[204:205], s[42:43], 0, v[172:173]
	s_mov_b32 m0, s58
	s_nop 0
	global_load_lds_dwordx4 v[204:205], off
	s_mov_b32 m0, s60
	s_nop 0
	global_load_lds_dwordx4 v[220:221], off
	s_waitcnt vmcnt(8)
	s_waitcnt lgkmcnt(0)
	s_barrier
; #define PG8_STAGE(bufoff, gbase, voff) do { _Pragma("unroll") for (int _i = 0; _i < 2; ++_i) \
;         __builtin_amdgcn_global_load_lds((const unsigned*)((const char*)(gbase) + (voff)[_i]), (PG8_LAS unsigned*)(lds + (bufoff) + ldsw + _i * 8192), 16, 0, 0); } while (0)
; #define PG8_LDA(dst, b, h) do { _Pragma("unroll") for (int m = 0; m < 4; ++m) _Pragma("unroll") for (int k = 0; k < 2; ++k) dst[m][k] = *(const PG8_LAS bf16x8*)(lds + PG8_SA(b, h) + aoff + m * 2048 + k * 1024); } while (0)
; #define PG8_LDB(dst, b, h) do { _Pragma("unroll") for (int n = 0; n < 2; ++n) _Pragma("unroll") for (int k = 0; k < 2; ++k) dst[n][k] = *(const PG8_LAS bf16x8*)(lds + PG8_SB(b, h) + boff + n * 2048 + k * 1024); } while (0)
; #define PG8_MMA(ai, bj, At, Bt) do { __builtin_amdgcn_s_setprio(3); _Pragma("unroll") for (int m = 0; m < 4; ++m) _Pragma("unroll") for (int n = 0; n < 2; ++n) _Pragma("unroll") for (int k = 0; k < 2; ++k) \
;         acc[ai][bj][m][n] = __builtin_amdgcn_mfma_f32_16x16x32_bf16(Bt[n][k], At[m][k], acc[ai][bj][m][n], 0, 0, 0); __builtin_amdgcn_s_setprio(0); } while (0)
; #define PG8_WAIT_V(n) asm volatile("s_waitcnt vmcnt(" #n ")" ::: "memory")
; #define PG8_WAIT_L(n) asm volatile("s_waitcnt lgkmcnt(" #n ")" ::: "memory")
; #define PG8_BAR __builtin_amdgcn_s_barrier()
; #define PG8_SCHED __builtin_amdgcn_sched_barrier(0)
; template <class Epi, class Sched, bool ALIGN_EPI = false, bool SP2 = false>
; __device__ __forceinline__ void gemm_phase(PG8_LAS unsigned char* lds, const Gemm g, const Sched& S, const Epi& E) {
;     ...
;             PG8_WAIT_V(8); PG8_WAIT_L(0); PG8_BAR; PG8_MMA(1, 0, At, B0); PG8_MMA(1, 1, At, B1); PG8_BAR; PG8_SCHED;
;             PG8_LDB(B0, 1, 0); PG8_LDB(B1, 1, 1); PG8_SCHED; PG8_LDA(At, 1, 0); PG8_STAGE(PG8_SA(0, 1), a2 + hstepA, voffA);
;             PG8_WAIT_V(8); PG8_WAIT_L(0); PG8_BAR; PG8_MMA(0, 0, At, B0); PG8_MMA(0, 1, At, B1); PG8_BAR; PG8_SCHED;
	s_setprio 3
	s_waitcnt lgkmcnt(0)
	v_mfma_f32_16x16x32_bf16 v[62:65], v[130:133], v[162:165], v[62:65]
	v_mfma_f32_16x16x32_bf16 v[62:65], v[134:137], v[166:169], v[62:65]
	v_mfma_f32_16x16x32_bf16 v[58:61], v[138:141], v[162:165], v[58:61]
	v_mfma_f32_16x16x32_bf16 v[58:61], v[142:145], v[166:169], v[58:61]
	v_mfma_f32_16x16x32_bf16 v[42:45], v[138:141], v[182:185], v[42:45]
	v_mfma_f32_16x16x32_bf16 v[42:45], v[142:145], v[190:193], v[42:45]
	v_mfma_f32_16x16x32_bf16 v[46:49], v[130:133], v[182:185], v[46:49]
	v_mfma_f32_16x16x32_bf16 v[46:49], v[134:137], v[190:193], v[46:49]
	v_mfma_f32_16x16x32_bf16 v[30:33], v[130:133], v[194:197], v[30:33]
	v_mfma_f32_16x16x32_bf16 v[30:33], v[134:137], v[208:211], v[30:33]
	v_mfma_f32_16x16x32_bf16 v[26:29], v[138:141], v[194:197], v[26:29]
	v_mfma_f32_16x16x32_bf16 v[26:29], v[142:145], v[208:211], v[26:29]
	v_mfma_f32_16x16x32_bf16 v[10:13], v[138:141], v[212:215], v[10:13]
	v_mfma_f32_16x16x32_bf16 v[10:13], v[142:145], v[216:219], v[10:13]
	v_mfma_f32_16x16x32_bf16 v[14:17], v[130:133], v[212:215], v[14:17]
	v_mfma_f32_16x16x32_bf16 v[14:17], v[134:137], v[216:219], v[14:17]
	s_setprio 0
	s_setprio 3
	v_mfma_f32_16x16x32_bf16 v[54:57], v[146:149], v[162:165], v[54:57]
	v_mfma_f32_16x16x32_bf16 v[54:57], v[150:153], v[166:169], v[54:57]
	v_mfma_f32_16x16x32_bf16 v[50:53], v[154:157], v[162:165], v[50:53]
	v_mfma_f32_16x16x32_bf16 v[50:53], v[158:161], v[166:169], v[50:53]
	v_mfma_f32_16x16x32_bf16 v[34:37], v[154:157], v[182:185], v[34:37]
	v_mfma_f32_16x16x32_bf16 v[34:37], v[158:161], v[190:193], v[34:37]
	v_mfma_f32_16x16x32_bf16 v[38:41], v[146:149], v[182:185], v[38:41]
	v_mfma_f32_16x16x32_bf16 v[38:41], v[150:153], v[190:193], v[38:41]
	v_mfma_f32_16x16x32_bf16 v[22:25], v[146:149], v[194:197], v[22:25]
	v_mfma_f32_16x16x32_bf16 v[22:25], v[150:153], v[208:211], v[22:25]
	v_mfma_f32_16x16x32_bf16 v[18:21], v[154:157], v[194:197], v[18:21]
	v_mfma_f32_16x16x32_bf16 v[18:21], v[158:161], v[208:211], v[18:21]
	v_mfma_f32_16x16x32_bf16 v[2:5], v[154:157], v[212:215], v[2:5]
	v_mfma_f32_16x16x32_bf16 v[2:5], v[158:161], v[216:219], v[2:5]
	v_mfma_f32_16x16x32_bf16 v[6:9], v[146:149], v[212:215], v[6:9]
	v_mfma_f32_16x16x32_bf16 v[6:9], v[150:153], v[216:219], v[6:9]
	s_setprio 0
	s_barrier
	v_add_u32_e32 v142, s52, v189
	v_add_u32_e32 v158, s53, v189
	ds_read_b128 v[130:133], v142
	ds_read_b128 v[134:137], v142 offset:1024
	ds_read_b128 v[138:141], v142 offset:2048
	ds_read_b128 v[142:145], v142 offset:3072
	ds_read_b128 v[146:149], v158
	ds_read_b128 v[150:153], v158 offset:1024
	ds_read_b128 v[154:157], v158 offset:2048
	ds_read_b128 v[158:161], v158 offset:3072
	s_add_u32 s42, s42, 0x2b0000
	s_addc_u32 s43, s43, 0
	s_mov_b32 m0, s61
	v_lshl_add_u64 v[222:223], s[42:43], 0, v[172:173]
	ds_read_b128 v[162:165], v180 offset:32768
	ds_read_b128 v[166:169], v180 offset:33792
	ds_read_b128 v[182:185], v180 offset:34816
	ds_read_b128 v[190:193], v180 offset:35840
	ds_read_b128 v[194:197], v180 offset:36864
	ds_read_b128 v[208:211], v180 offset:37888
	ds_read_b128 v[212:215], v180 offset:38912
	ds_read_b128 v[216:219], v180 offset:39936
	global_load_lds_dwordx4 v[222:223], off
	v_lshl_add_u64 v[222:223], s[42:43], 0, v[176:177]
	s_mov_b32 m0, s62
	s_nop 0
	global_load_lds_dwordx4 v[222:223], off
	s_waitcnt vmcnt(8)
	s_waitcnt lgkmcnt(0)
	s_barrier
	s_setprio 3
	s_waitcnt lgkmcnt(0)
	v_mfma_f32_16x16x32_bf16 v[126:129], v[130:133], v[162:165], v[126:129]
	v_mfma_f32_16x16x32_bf16 v[126:129], v[134:137], v[166:169], v[126:129]
	v_mfma_f32_16x16x32_bf16 v[122:125], v[138:141], v[162:165], v[122:125]
	v_mfma_f32_16x16x32_bf16 v[122:125], v[142:145], v[166:169], v[122:125]
	v_mfma_f32_16x16x32_bf16 v[94:97], v[138:141], v[182:185], v[94:97]
	v_mfma_f32_16x16x32_bf16 v[94:97], v[142:145], v[190:193], v[94:97]
	v_mfma_f32_16x16x32_bf16 v[98:101], v[130:133], v[182:185], v[98:101]
	v_mfma_f32_16x16x32_bf16 v[98:101], v[134:137], v[190:193], v[98:101]
	v_mfma_f32_16x16x32_bf16 v[110:113], v[130:133], v[194:197], v[110:113]
	v_mfma_f32_16x16x32_bf16 v[110:113], v[134:137], v[208:211], v[110:113]
	v_mfma_f32_16x16x32_bf16 v[106:109], v[138:141], v[194:197], v[106:109]
	v_mfma_f32_16x16x32_bf16 v[106:109], v[142:145], v[208:211], v[106:109]
	v_mfma_f32_16x16x32_bf16 v[74:77], v[138:141], v[212:215], v[74:77]
	v_mfma_f32_16x16x32_bf16 v[74:77], v[142:145], v[216:219], v[74:77]
	v_mfma_f32_16x16x32_bf16 v[78:81], v[130:133], v[212:215], v[78:81]
	v_mfma_f32_16x16x32_bf16 v[78:81], v[134:137], v[216:219], v[78:81]
	s_setprio 0
	s_setprio 3
	v_mfma_f32_16x16x32_bf16 v[118:121], v[146:149], v[162:165], v[118:121]
	v_mfma_f32_16x16x32_bf16 v[118:121], v[150:153], v[166:169], v[118:121]
	v_mfma_f32_16x16x32_bf16 v[114:117], v[154:157], v[162:165], v[114:117]
	v_mfma_f32_16x16x32_bf16 v[114:117], v[158:161], v[166:169], v[114:117]
	v_mfma_f32_16x16x32_bf16 v[86:89], v[154:157], v[182:185], v[86:89]
	v_mfma_f32_16x16x32_bf16 v[86:89], v[158:161], v[190:193], v[86:89]
	v_mfma_f32_16x16x32_bf16 v[90:93], v[146:149], v[182:185], v[90:93]
	v_mfma_f32_16x16x32_bf16 v[90:93], v[150:153], v[190:193], v[90:93]
	v_mfma_f32_16x16x32_bf16 v[102:105], v[146:149], v[194:197], v[102:105]
	v_mfma_f32_16x16x32_bf16 v[102:105], v[150:153], v[208:211], v[102:105]
	v_mfma_f32_16x16x32_bf16 v[82:85], v[154:157], v[194:197], v[82:85]
	v_mfma_f32_16x16x32_bf16 v[82:85], v[158:161], v[208:211], v[82:85]
	v_mfma_f32_16x16x32_bf16 v[66:69], v[154:157], v[212:215], v[66:69]
	v_mfma_f32_16x16x32_bf16 v[66:69], v[158:161], v[216:219], v[66:69]
	v_mfma_f32_16x16x32_bf16 v[70:73], v[146:149], v[212:215], v[70:73]
	v_mfma_f32_16x16x32_bf16 v[70:73], v[150:153], v[216:219], v[70:73]
	s_setprio 0
	s_barrier
; #define PG8_STAGE(bufoff, gbase, voff) do { _Pragma("unroll") for (int _i = 0; _i < 2; ++_i) \
;         __builtin_amdgcn_global_load_lds((const unsigned*)((const char*)(gbase) + (voff)[_i]), (PG8_LAS unsigned*)(lds + (bufoff) + ldsw + _i * 8192), 16, 0, 0); } while (0)
; #define PG8_LDA(dst, b, h) do { _Pragma("unroll") for (int m = 0; m < 4; ++m) _Pragma("unroll") for (int k = 0; k < 2; ++k) dst[m][k] = *(const PG8_LAS bf16x8*)(lds + PG8_SA(b, h) + aoff + m * 2048 + k * 1024); } while (0)
; #define PG8_MMA(ai, bj, At, Bt) do { __builtin_amdgcn_s_setprio(3); _Pragma("unroll") for (int m = 0; m < 4; ++m) _Pragma("unroll") for (int n = 0; n < 2; ++n) _Pragma("unroll") for (int k = 0; k < 2; ++k) \
;         acc[ai][bj][m][n] = __builtin_amdgcn_mfma_f32_16x16x32_bf16(Bt[n][k], At[m][k], acc[ai][bj][m][n], 0, 0, 0); __builtin_amdgcn_s_setprio(0); } while (0)
; #define PG8_WAIT_V(n) asm volatile("s_waitcnt vmcnt(" #n ")" ::: "memory")
; #define PG8_WAIT_L(n) asm volatile("s_waitcnt lgkmcnt(" #n ")" ::: "memory")
; #define PG8_BAR __builtin_amdgcn_s_barrier()
; #define PG8_SCHED __builtin_amdgcn_sched_barrier(0)
; template <class Epi, class Sched, bool ALIGN_EPI = false, bool SP2 = false>
; __device__ __forceinline__ void gemm_phase(PG8_LAS unsigned char* lds, const Gemm g, const Sched& S, const Epi& E) {
;     ...
;         for (int t = 0; t < nt; t += 2) {
;             const bool last = (t == nt - 2);
;     ...
;             PG8_LDA(At, 1, 1); PG8_STAGE(PG8_SB(1, 0), b3, voffB); PG8_STAGE(PG8_SB(1, 1), b3 + hstepB, voffB); PG8_STAGE(PG8_SA(1, 0), a3, voffA);
;             PG8_WAIT_V(8); PG8_WAIT_L(0); PG8_BAR; PG8_MMA(1, 0, At, B0); PG8_MMA(1, 1, At, B1); PG8_BAR; PG8_SCHED;
	s_mov_b32 m0, s83
	v_lshl_add_u64 v[186:187], v[186:187], 0, s[18:19]
	s_add_u32 s40, s40, 0x2b0080
	ds_read_b128 v[162:165], v180 offset:49152
	ds_read_b128 v[166:169], v180 offset:50176
	ds_read_b128 v[182:185], v180 offset:51200
	ds_read_b128 v[190:193], v180 offset:52224
	ds_read_b128 v[194:197], v180 offset:53248
	ds_read_b128 v[208:211], v180 offset:54272
	ds_read_b128 v[212:215], v180 offset:55296
	ds_read_b128 v[216:219], v180 offset:56320
	global_load_lds_dwordx4 v[186:187], off
	v_lshl_add_u64 v[186:187], v[198:199], 0, s[18:19]
	s_mov_b32 m0, s84
	s_addc_u32 s41, s41, 0
	global_load_lds_dwordx4 v[186:187], off
	v_lshl_add_u64 v[186:187], s[40:41], 0, v[174:175]
	s_mov_b32 m0, s85
	s_nop 0
	global_load_lds_dwordx4 v[186:187], off
	v_lshl_add_u64 v[186:187], s[40:41], 0, v[178:179]
	s_mov_b32 m0, s86
	s_nop 0
	global_load_lds_dwordx4 v[186:187], off
	v_lshl_add_u64 v[186:187], v[204:205], 0, s[18:19]
	s_mov_b32 m0, s63
	s_nop 0
	global_load_lds_dwordx4 v[186:187], off
	v_lshl_add_u64 v[186:187], v[220:221], 0, s[18:19]
	s_mov_b32 m0, s64
	s_nop 0
	global_load_lds_dwordx4 v[186:187], off
	s_waitcnt vmcnt(8)
	s_waitcnt lgkmcnt(0)
	s_barrier
	s_setprio 3
	s_waitcnt lgkmcnt(0)
	v_mfma_f32_16x16x32_bf16 v[62:65], v[130:133], v[162:165], v[62:65]
	v_mfma_f32_16x16x32_bf16 v[62:65], v[134:137], v[166:169], v[62:65]
	v_mfma_f32_16x16x32_bf16 v[58:61], v[138:141], v[162:165], v[58:61]
	v_mfma_f32_16x16x32_bf16 v[58:61], v[142:145], v[166:169], v[58:61]
	v_mfma_f32_16x16x32_bf16 v[42:45], v[138:141], v[182:185], v[42:45]
	v_mfma_f32_16x16x32_bf16 v[42:45], v[142:145], v[190:193], v[42:45]
	v_mfma_f32_16x16x32_bf16 v[46:49], v[130:133], v[182:185], v[46:49]
	v_mfma_f32_16x16x32_bf16 v[46:49], v[134:137], v[190:193], v[46:49]
	v_mfma_f32_16x16x32_bf16 v[30:33], v[130:133], v[194:197], v[30:33]
	v_mfma_f32_16x16x32_bf16 v[30:33], v[134:137], v[208:211], v[30:33]
	v_mfma_f32_16x16x32_bf16 v[26:29], v[138:141], v[194:197], v[26:29]
	v_mfma_f32_16x16x32_bf16 v[26:29], v[142:145], v[208:211], v[26:29]
	v_mfma_f32_16x16x32_bf16 v[10:13], v[138:141], v[212:215], v[10:13]
	v_mfma_f32_16x16x32_bf16 v[10:13], v[142:145], v[216:219], v[10:13]
	v_mfma_f32_16x16x32_bf16 v[14:17], v[130:133], v[212:215], v[14:17]
	v_mfma_f32_16x16x32_bf16 v[14:17], v[134:137], v[216:219], v[14:17]
	s_setprio 0
	s_setprio 3
	v_mfma_f32_16x16x32_bf16 v[54:57], v[146:149], v[162:165], v[54:57]
	v_mfma_f32_16x16x32_bf16 v[54:57], v[150:153], v[166:169], v[54:57]
	v_mfma_f32_16x16x32_bf16 v[50:53], v[154:157], v[162:165], v[50:53]
	v_mfma_f32_16x16x32_bf16 v[50:53], v[158:161], v[166:169], v[50:53]
	v_mfma_f32_16x16x32_bf16 v[34:37], v[154:157], v[182:185], v[34:37]
	v_mfma_f32_16x16x32_bf16 v[34:37], v[158:161], v[190:193], v[34:37]
	v_mfma_f32_16x16x32_bf16 v[38:41], v[146:149], v[182:185], v[38:41]
	v_mfma_f32_16x16x32_bf16 v[38:41], v[150:153], v[190:193], v[38:41]
	v_mfma_f32_16x16x32_bf16 v[22:25], v[146:149], v[194:197], v[22:25]
	v_mfma_f32_16x16x32_bf16 v[22:25], v[150:153], v[208:211], v[22:25]
	v_mfma_f32_16x16x32_bf16 v[18:21], v[154:157], v[194:197], v[18:21]
	v_mfma_f32_16x16x32_bf16 v[18:21], v[158:161], v[208:211], v[18:21]
	v_mfma_f32_16x16x32_bf16 v[2:5], v[154:157], v[212:215], v[2:5]
	v_mfma_f32_16x16x32_bf16 v[2:5], v[158:161], v[216:219], v[2:5]
	v_mfma_f32_16x16x32_bf16 v[6:9], v[146:149], v[212:215], v[6:9]
	v_mfma_f32_16x16x32_bf16 v[6:9], v[150:153], v[216:219], v[6:9]
	s_setprio 0
	s_barrier
	s_add_i32 s67, s67, 2
	s_add_u32 s22, s22, 0x100
	s_addc_u32 s23, s23, 0
	s_cmpk_gt_u32 s67, 0xa9
	s_cbranch_scc1 .LBB0_1021
